# waves 0-3 issue their epilogue loads before the post-loop re-sync barrier
# baseline (speedup 1.0000x reference)
.LBB0_47:
	s_add_u32 s1, s28, 0xfffc0080
	s_addc_u32 s22, s29, -1
	s_add_i32 s23, 0, 0x10000
	v_add_u32_e32 v142, s23, v195
	ds_read_b128 v[130:133], v142
	ds_read_b128 v[134:137], v142 offset:1024
	ds_read_b128 v[138:141], v142 offset:2048
	ds_read_b128 v[142:145], v142 offset:3072
	s_cmp_eq_u32 s69, 12
	s_cselect_b32 s57, s21, s22
	s_cselect_b32 s56, s34, s1
	s_cselect_b32 s31, s47, s68
	s_cselect_b32 s30, s49, s67
	v_lshl_add_u64 v[176:177], s[28:29], 0, v[178:179]
	s_add_i32 m0, s59, 0xc000
	ds_read_b128 v[146:149], v197
	ds_read_b128 v[150:153], v197 offset:1024
	ds_read_b128 v[182:185], v197 offset:2048
	ds_read_b128 v[186:189], v197 offset:3072
	ds_read_b128 v[190:193], v197 offset:4096
	ds_read_b128 v[198:201], v197 offset:5120
	ds_read_b128 v[202:205], v197 offset:6144
	ds_read_b128 v[206:209], v197 offset:7168
	global_load_lds_dwordx4 v[176:177], off
	v_lshl_add_u64 v[176:177], s[28:29], 0, v[180:181]
	s_add_i32 m0, s59, 0xe000
	s_nop 0
	global_load_lds_dwordx4 v[176:177], off
	s_add_i32 s1, 0, 0x14000
	v_add_u32_e32 v168, s1, v195
	ds_read_b128 v[216:219], v168
	ds_read_b128 v[230:233], v168 offset:1024
	ds_read_b128 v[234:237], v168 offset:2048
	ds_read_b128 v[238:241], v168 offset:3072
	s_waitcnt vmcnt(8)
	s_waitcnt lgkmcnt(0)
	s_barrier
	s_setprio 1
	v_mfma_f32_16x16x32_bf16 v[126:129], v[130:133], v[146:149], v[126:129]
	v_mfma_f32_16x16x32_bf16 v[122:125], v[138:141], v[146:149], v[122:125]
	v_mfma_f32_16x16x32_bf16 v[110:113], v[130:133], v[182:185], v[110:113]
	v_mfma_f32_16x16x32_bf16 v[106:109], v[138:141], v[182:185], v[106:109]
	v_mfma_f32_16x16x32_bf16 v[94:97], v[130:133], v[190:193], v[94:97]
	v_mfma_f32_16x16x32_bf16 v[90:93], v[138:141], v[190:193], v[90:93]
	v_mfma_f32_16x16x32_bf16 v[78:81], v[130:133], v[202:205], v[78:81]
	v_mfma_f32_16x16x32_bf16 v[74:77], v[138:141], v[202:205], v[74:77]
	v_mfma_f32_16x16x32_bf16 v[126:129], v[134:137], v[150:153], v[126:129]
	v_mfma_f32_16x16x32_bf16 v[122:125], v[142:145], v[150:153], v[122:125]
	v_mfma_f32_16x16x32_bf16 v[110:113], v[134:137], v[186:189], v[110:113]
	v_mfma_f32_16x16x32_bf16 v[106:109], v[142:145], v[186:189], v[106:109]
	v_mfma_f32_16x16x32_bf16 v[94:97], v[134:137], v[198:201], v[94:97]
	v_mfma_f32_16x16x32_bf16 v[90:93], v[142:145], v[198:201], v[90:93]
	v_mfma_f32_16x16x32_bf16 v[78:81], v[134:137], v[206:209], v[78:81]
	v_mfma_f32_16x16x32_bf16 v[74:77], v[142:145], v[206:209], v[74:77]
	v_mfma_f32_16x16x32_bf16 v[118:121], v[216:219], v[146:149], v[118:121]
	v_mfma_f32_16x16x32_bf16 v[114:117], v[234:237], v[146:149], v[114:117]
	v_mfma_f32_16x16x32_bf16 v[102:105], v[216:219], v[182:185], v[102:105]
	v_mfma_f32_16x16x32_bf16 v[98:101], v[234:237], v[182:185], v[98:101]
	v_mfma_f32_16x16x32_bf16 v[86:89], v[216:219], v[190:193], v[86:89]
	v_mfma_f32_16x16x32_bf16 v[82:85], v[234:237], v[190:193], v[82:85]
	v_mfma_f32_16x16x32_bf16 v[70:73], v[216:219], v[202:205], v[70:73]
	v_mfma_f32_16x16x32_bf16 v[66:69], v[234:237], v[202:205], v[66:69]
	v_mfma_f32_16x16x32_bf16 v[118:121], v[230:233], v[150:153], v[118:121]
	v_mfma_f32_16x16x32_bf16 v[114:117], v[238:241], v[150:153], v[114:117]
	v_mfma_f32_16x16x32_bf16 v[102:105], v[230:233], v[186:189], v[102:105]
	v_mfma_f32_16x16x32_bf16 v[98:101], v[238:241], v[186:189], v[98:101]
	v_mfma_f32_16x16x32_bf16 v[86:89], v[230:233], v[198:201], v[86:89]
	v_mfma_f32_16x16x32_bf16 v[82:85], v[238:241], v[198:201], v[82:85]
	v_mfma_f32_16x16x32_bf16 v[70:73], v[230:233], v[206:209], v[70:73]
	v_mfma_f32_16x16x32_bf16 v[66:69], v[238:241], v[206:209], v[66:69]
	s_setprio 0
	s_barrier
	ds_read_b128 v[146:149], v197 offset:16384
	ds_read_b128 v[150:153], v197 offset:17408
	ds_read_b128 v[182:185], v197 offset:18432
	ds_read_b128 v[186:189], v197 offset:19456
	ds_read_b128 v[190:193], v197 offset:20480
	ds_read_b128 v[198:201], v197 offset:21504
	ds_read_b128 v[202:205], v197 offset:22528
	ds_read_b128 v[206:209], v197 offset:23552
	s_add_i32 s22, s23, s58
	v_lshl_add_u64 v[176:177], s[30:31], 0, v[0:1]
	s_mov_b32 m0, s22
	s_nop 0
	global_load_lds_dwordx4 v[176:177], off
	v_lshl_add_u64 v[220:221], s[30:31], 0, v[154:155]
	s_add_i32 m0, s22, 0x2000
	s_nop 0
	global_load_lds_dwordx4 v[220:221], off
	s_mov_b32 m0, s59
	v_lshl_add_u64 v[242:243], s[56:57], 0, v[158:159]
	global_load_lds_dwordx4 v[242:243], off
	v_lshl_add_u64 v[244:245], s[56:57], 0, v[156:157]
	s_mov_b32 m0, s60
	s_nop 0
	global_load_lds_dwordx4 v[244:245], off
	s_add_u32 s22, s30, 0x40000
	s_addc_u32 s23, s31, 0
	s_add_i32 s1, s1, s58
	s_mov_b32 m0, s1
	s_nop 0
	global_load_lds_dwordx4 v0, s[22:23]
	s_add_i32 m0, s1, 0x2000
	s_nop 0
	global_load_lds_dwordx4 v154, s[22:23]
	s_waitcnt vmcnt(8)
	s_waitcnt lgkmcnt(0)
	s_barrier
	s_setprio 1
	v_mfma_f32_16x16x32_bf16 v[62:65], v[130:133], v[146:149], v[62:65]
	v_mfma_f32_16x16x32_bf16 v[58:61], v[138:141], v[146:149], v[58:61]
	v_mfma_f32_16x16x32_bf16 v[46:49], v[130:133], v[182:185], v[46:49]
	v_mfma_f32_16x16x32_bf16 v[42:45], v[138:141], v[182:185], v[42:45]
	v_mfma_f32_16x16x32_bf16 v[30:33], v[130:133], v[190:193], v[30:33]
	v_mfma_f32_16x16x32_bf16 v[26:29], v[138:141], v[190:193], v[26:29]
	v_mfma_f32_16x16x32_bf16 v[14:17], v[130:133], v[202:205], v[14:17]
	v_mfma_f32_16x16x32_bf16 v[10:13], v[138:141], v[202:205], v[10:13]
	v_mfma_f32_16x16x32_bf16 v[62:65], v[134:137], v[150:153], v[62:65]
	v_mfma_f32_16x16x32_bf16 v[58:61], v[142:145], v[150:153], v[58:61]
	v_mfma_f32_16x16x32_bf16 v[46:49], v[134:137], v[186:189], v[46:49]
	v_mfma_f32_16x16x32_bf16 v[42:45], v[142:145], v[186:189], v[42:45]
	v_mfma_f32_16x16x32_bf16 v[30:33], v[134:137], v[198:201], v[30:33]
	v_mfma_f32_16x16x32_bf16 v[26:29], v[142:145], v[198:201], v[26:29]
	v_mfma_f32_16x16x32_bf16 v[14:17], v[134:137], v[206:209], v[14:17]
	v_mfma_f32_16x16x32_bf16 v[10:13], v[142:145], v[206:209], v[10:13]
	v_mfma_f32_16x16x32_bf16 v[54:57], v[216:219], v[146:149], v[54:57]
	v_mfma_f32_16x16x32_bf16 v[50:53], v[234:237], v[146:149], v[50:53]
	v_mfma_f32_16x16x32_bf16 v[38:41], v[216:219], v[182:185], v[38:41]
	v_mfma_f32_16x16x32_bf16 v[34:37], v[234:237], v[182:185], v[34:37]
	v_mfma_f32_16x16x32_bf16 v[22:25], v[216:219], v[190:193], v[22:25]
	v_mfma_f32_16x16x32_bf16 v[18:21], v[234:237], v[190:193], v[18:21]
	v_mfma_f32_16x16x32_bf16 v[6:9], v[216:219], v[202:205], v[6:9]
	v_mfma_f32_16x16x32_bf16 v[2:5], v[234:237], v[202:205], v[2:5]
	v_mfma_f32_16x16x32_bf16 v[54:57], v[230:233], v[150:153], v[54:57]
	v_mfma_f32_16x16x32_bf16 v[50:53], v[238:241], v[150:153], v[50:53]
	v_mfma_f32_16x16x32_bf16 v[38:41], v[230:233], v[186:189], v[38:41]
	v_mfma_f32_16x16x32_bf16 v[34:37], v[238:241], v[186:189], v[34:37]
	v_mfma_f32_16x16x32_bf16 v[22:25], v[230:233], v[198:201], v[22:25]
	v_mfma_f32_16x16x32_bf16 v[18:21], v[238:241], v[198:201], v[18:21]
	v_mfma_f32_16x16x32_bf16 v[6:9], v[230:233], v[206:209], v[6:9]
	v_mfma_f32_16x16x32_bf16 v[2:5], v[238:241], v[206:209], v[2:5]
	s_setprio 0
	s_barrier
	s_add_i32 s1, 0, 0x18000
	v_add_u32_e32 v142, s1, v195
	ds_read_b128 v[130:133], v142
	ds_read_b128 v[134:137], v142 offset:1024
	ds_read_b128 v[138:141], v142 offset:2048
	ds_read_b128 v[142:145], v142 offset:3072
	s_add_u32 s22, s56, 0x40000
	s_addc_u32 s23, s57, 0
	s_mov_b32 m0, s61
	v_lshl_add_u64 v[216:217], s[22:23], 0, v[158:159]
	ds_read_b128 v[146:149], v197 offset:32768
	ds_read_b128 v[150:153], v197 offset:33792
	ds_read_b128 v[182:185], v197 offset:34816
	ds_read_b128 v[186:189], v197 offset:35840
	ds_read_b128 v[190:193], v197 offset:36864
	ds_read_b128 v[198:201], v197 offset:37888
	ds_read_b128 v[202:205], v197 offset:38912
	ds_read_b128 v[206:209], v197 offset:39936
	global_load_lds_dwordx4 v[216:217], off
	v_lshl_add_u64 v[216:217], s[22:23], 0, v[156:157]
	s_mov_b32 m0, s62
	s_nop 0
	global_load_lds_dwordx4 v[216:217], off
	s_add_i32 s33, 0, 0x1c000
	v_add_u32_e32 v168, s33, v195
	ds_read_b128 v[216:219], v168
	ds_read_b128 v[230:233], v168 offset:1024
	ds_read_b128 v[234:237], v168 offset:2048
	ds_read_b128 v[238:241], v168 offset:3072
	s_waitcnt vmcnt(8)
	s_waitcnt lgkmcnt(0)
	s_barrier
	s_setprio 1
	v_mfma_f32_16x16x32_bf16 v[126:129], v[130:133], v[146:149], v[126:129]
	v_mfma_f32_16x16x32_bf16 v[122:125], v[138:141], v[146:149], v[122:125]
	v_mfma_f32_16x16x32_bf16 v[110:113], v[130:133], v[182:185], v[110:113]
	v_mfma_f32_16x16x32_bf16 v[106:109], v[138:141], v[182:185], v[106:109]
	v_mfma_f32_16x16x32_bf16 v[94:97], v[130:133], v[190:193], v[94:97]
	v_mfma_f32_16x16x32_bf16 v[90:93], v[138:141], v[190:193], v[90:93]
	v_mfma_f32_16x16x32_bf16 v[78:81], v[130:133], v[202:205], v[78:81]
	v_mfma_f32_16x16x32_bf16 v[74:77], v[138:141], v[202:205], v[74:77]
	v_mfma_f32_16x16x32_bf16 v[126:129], v[134:137], v[150:153], v[126:129]
	v_mfma_f32_16x16x32_bf16 v[122:125], v[142:145], v[150:153], v[122:125]
	v_mfma_f32_16x16x32_bf16 v[110:113], v[134:137], v[186:189], v[110:113]
	v_mfma_f32_16x16x32_bf16 v[106:109], v[142:145], v[186:189], v[106:109]
	v_mfma_f32_16x16x32_bf16 v[94:97], v[134:137], v[198:201], v[94:97]
	v_mfma_f32_16x16x32_bf16 v[90:93], v[142:145], v[198:201], v[90:93]
	v_mfma_f32_16x16x32_bf16 v[78:81], v[134:137], v[206:209], v[78:81]
	v_mfma_f32_16x16x32_bf16 v[74:77], v[142:145], v[206:209], v[74:77]
	v_mfma_f32_16x16x32_bf16 v[118:121], v[216:219], v[146:149], v[118:121]
	v_mfma_f32_16x16x32_bf16 v[114:117], v[234:237], v[146:149], v[114:117]
	v_mfma_f32_16x16x32_bf16 v[102:105], v[216:219], v[182:185], v[102:105]
	v_mfma_f32_16x16x32_bf16 v[98:101], v[234:237], v[182:185], v[98:101]
	v_mfma_f32_16x16x32_bf16 v[86:89], v[216:219], v[190:193], v[86:89]
	v_mfma_f32_16x16x32_bf16 v[82:85], v[234:237], v[190:193], v[82:85]
	v_mfma_f32_16x16x32_bf16 v[70:73], v[216:219], v[202:205], v[70:73]
	v_mfma_f32_16x16x32_bf16 v[66:69], v[234:237], v[202:205], v[66:69]
	v_mfma_f32_16x16x32_bf16 v[118:121], v[230:233], v[150:153], v[118:121]
	v_mfma_f32_16x16x32_bf16 v[114:117], v[238:241], v[150:153], v[114:117]
	v_mfma_f32_16x16x32_bf16 v[102:105], v[230:233], v[186:189], v[102:105]
	v_mfma_f32_16x16x32_bf16 v[98:101], v[238:241], v[186:189], v[98:101]
	v_mfma_f32_16x16x32_bf16 v[86:89], v[230:233], v[198:201], v[86:89]
	v_mfma_f32_16x16x32_bf16 v[82:85], v[238:241], v[198:201], v[82:85]
	v_mfma_f32_16x16x32_bf16 v[70:73], v[230:233], v[206:209], v[70:73]
	v_mfma_f32_16x16x32_bf16 v[66:69], v[238:241], v[206:209], v[66:69]
	s_setprio 0
	s_barrier
	ds_read_b128 v[146:149], v197 offset:49152
	ds_read_b128 v[150:153], v197 offset:50176
	ds_read_b128 v[182:185], v197 offset:51200
	ds_read_b128 v[186:189], v197 offset:52224
	ds_read_b128 v[190:193], v197 offset:53248
	ds_read_b128 v[198:201], v197 offset:54272
	ds_read_b128 v[202:205], v197 offset:55296
	ds_read_b128 v[206:209], v197 offset:56320
	s_add_i32 s1, s1, s58
	v_lshl_add_u64 v[176:177], v[176:177], 0, s[12:13]
	s_mov_b32 m0, s1
	s_nop 0
	global_load_lds_dwordx4 v[176:177], off
	v_lshl_add_u64 v[176:177], v[220:221], 0, s[12:13]
	s_add_i32 m0, s1, 0x2000
	s_nop 0
	global_load_lds_dwordx4 v[176:177], off
	s_mov_b32 m0, s64
	v_lshl_add_u64 v[176:177], v[242:243], 0, s[12:13]
	global_load_lds_dwordx4 v[176:177], off
	v_lshl_add_u64 v[176:177], v[244:245], 0, s[12:13]
	s_mov_b32 m0, s65
	s_nop 0
	global_load_lds_dwordx4 v[176:177], off
	s_add_u32 s22, s30, 0x40080
	s_addc_u32 s23, s31, 0
	s_add_i32 s1, s33, s58
	s_mov_b32 m0, s1
	s_nop 0
	global_load_lds_dwordx4 v0, s[22:23]
	s_add_i32 m0, s1, 0x2000
	s_nop 0
	global_load_lds_dwordx4 v154, s[22:23]
	s_waitcnt vmcnt(8)
	s_waitcnt lgkmcnt(0)
	s_barrier
	s_setprio 1
	v_mfma_f32_16x16x32_bf16 v[62:65], v[130:133], v[146:149], v[62:65]
	v_mfma_f32_16x16x32_bf16 v[58:61], v[138:141], v[146:149], v[58:61]
	v_mfma_f32_16x16x32_bf16 v[46:49], v[130:133], v[182:185], v[46:49]
	v_mfma_f32_16x16x32_bf16 v[42:45], v[138:141], v[182:185], v[42:45]
	v_mfma_f32_16x16x32_bf16 v[30:33], v[130:133], v[190:193], v[30:33]
	v_mfma_f32_16x16x32_bf16 v[26:29], v[138:141], v[190:193], v[26:29]
	v_mfma_f32_16x16x32_bf16 v[14:17], v[130:133], v[202:205], v[14:17]
	v_mfma_f32_16x16x32_bf16 v[10:13], v[138:141], v[202:205], v[10:13]
	v_mfma_f32_16x16x32_bf16 v[62:65], v[134:137], v[150:153], v[62:65]
	v_mfma_f32_16x16x32_bf16 v[58:61], v[142:145], v[150:153], v[58:61]
	v_mfma_f32_16x16x32_bf16 v[46:49], v[134:137], v[186:189], v[46:49]
	v_mfma_f32_16x16x32_bf16 v[42:45], v[142:145], v[186:189], v[42:45]
	v_mfma_f32_16x16x32_bf16 v[30:33], v[134:137], v[198:201], v[30:33]
	v_mfma_f32_16x16x32_bf16 v[26:29], v[142:145], v[198:201], v[26:29]
	v_mfma_f32_16x16x32_bf16 v[14:17], v[134:137], v[206:209], v[14:17]
	v_mfma_f32_16x16x32_bf16 v[10:13], v[142:145], v[206:209], v[10:13]
	v_mfma_f32_16x16x32_bf16 v[54:57], v[216:219], v[146:149], v[54:57]
	v_mfma_f32_16x16x32_bf16 v[50:53], v[234:237], v[146:149], v[50:53]
	v_mfma_f32_16x16x32_bf16 v[38:41], v[216:219], v[182:185], v[38:41]
	v_mfma_f32_16x16x32_bf16 v[34:37], v[234:237], v[182:185], v[34:37]
	v_mfma_f32_16x16x32_bf16 v[22:25], v[216:219], v[190:193], v[22:25]
	v_mfma_f32_16x16x32_bf16 v[18:21], v[234:237], v[190:193], v[18:21]
	v_mfma_f32_16x16x32_bf16 v[6:9], v[216:219], v[202:205], v[6:9]
	v_mfma_f32_16x16x32_bf16 v[2:5], v[234:237], v[202:205], v[2:5]
	v_mfma_f32_16x16x32_bf16 v[54:57], v[230:233], v[150:153], v[54:57]
	v_mfma_f32_16x16x32_bf16 v[50:53], v[238:241], v[150:153], v[50:53]
	v_mfma_f32_16x16x32_bf16 v[38:41], v[230:233], v[186:189], v[38:41]
	v_mfma_f32_16x16x32_bf16 v[34:37], v[238:241], v[186:189], v[34:37]
	v_mfma_f32_16x16x32_bf16 v[22:25], v[230:233], v[198:201], v[22:25]
	v_mfma_f32_16x16x32_bf16 v[18:21], v[238:241], v[198:201], v[18:21]
	v_mfma_f32_16x16x32_bf16 v[6:9], v[230:233], v[206:209], v[6:9]
	v_mfma_f32_16x16x32_bf16 v[2:5], v[238:241], v[206:209], v[2:5]
	s_setprio 0
	s_add_i32 s69, s69, 2
	s_add_u32 s28, s28, 0x100
	s_addc_u32 s29, s29, 0
	s_add_u32 s67, s67, 0x100
	s_addc_u32 s68, s68, 0
	s_cmp_gt_u32 s69, 13
	s_barrier
	s_cbranch_scc0 .LBB0_47
	v_lshl_add_u32 v184, s20, 8, v194
	v_ashrrev_i32_e32 v185, 31, v184
	v_or_b32_e32 v188, 16, v184
	v_lshlrev_b64 v[190:191], 6, v[184:185]
	v_ashrrev_i32_e32 v189, 31, v188
	v_lshl_add_u64 v[130:131], v[160:161], 0, v[190:191]
	v_lshlrev_b64 v[186:187], 6, v[188:189]
	global_load_dwordx4 v[200:203], v[130:131], off
	v_lshl_add_u64 v[130:131], v[160:161], 0, v[186:187]
	global_load_dwordx4 v[204:207], v[130:131], off
	v_lshl_or_b32 v182, s4, 8, v196
	v_ashrrev_i32_e32 v183, 31, v182
	v_lshlrev_b64 v[130:131], 10, v[184:185]
	v_lshl_add_u64 v[130:131], v[130:131], 0, v[182:183]
	v_lshlrev_b64 v[130:131], 1, v[130:131]
	v_lshl_add_u64 v[132:133], s[96:97], 0, v[130:131]
	global_load_dwordx4 v[216:219], v[132:133], off
	global_load_dwordx4 v[146:149], v[132:133], off offset:256
	v_lshl_add_u64 v[134:135], s[24:25], 0, v[130:131]
	global_load_dwordx4 v[230:233], v[134:135], off
	v_and_b32_e32 v135, 64, v212
	v_xor_b32_e32 v134, 16, v212
	v_add_u32_e32 v135, 64, v135
	v_xor_b32_e32 v136, 32, v212
	v_cmp_lt_i32_e32 vcc, v134, v135
	v_or_b32_e32 v130, 0x100, v130
	v_lshl_add_u64 v[130:131], s[24:25], 0, v[130:131]
	v_cndmask_b32_e32 v134, v212, v134, vcc
	v_cmp_lt_i32_e32 vcc, v136, v135
	v_lshlrev_b32_e32 v199, 2, v134
	s_mov_b32 s20, 0x3a800000
	v_cndmask_b32_e32 v135, v212, v136, vcc
	v_lshlrev_b32_e32 v198, 2, v135
	v_lshlrev_b64 v[134:135], 10, v[188:189]
	v_lshl_add_u64 v[134:135], v[134:135], 0, v[182:183]
	v_lshlrev_b64 v[134:135], 1, v[134:135]
	v_lshl_add_u64 v[132:133], s[96:97], 0, v[134:135]
	global_load_dwordx4 v[150:153], v[130:131], off
	global_load_dwordx4 v[138:141], v[132:133], off
	s_nop 0
	global_load_dwordx4 v[130:133], v[132:133], off offset:256
	v_lshl_add_u64 v[136:137], s[24:25], 0, v[134:135]
	v_or_b32_e32 v134, 0x100, v134
	v_lshl_add_u64 v[134:135], s[24:25], 0, v[134:135]
	global_load_dwordx4 v[142:145], v[136:137], off
	s_nop 0
	global_load_dwordx4 v[134:137], v[134:135], off
	s_lshl_b32 s28, s4, 2
	s_ashr_i32 s29, s28, 31
	s_cmpk_gt_u32 s0, 0xff
	s_cbranch_scc1 .Lrs_i1_post
	s_barrier
.Lrs_i1_post:
	s_waitcnt vmcnt(0)
	v_mov_b32_e32 v176, v201
	v_mov_b32_e32 v177, v202
	v_mov_b32_e32 v201, v203
	v_mov_b32_e32 v192, v205
	v_mov_b32_e32 v193, v206
	v_mov_b32_e32 v205, v207
	v_pk_add_f32 v[176:177], v[176:177], v[200:201]
	v_pk_add_f32 v[192:193], v[192:193], v[204:205]
	v_mov_b32_e32 v201, v176
	v_mov_b32_e32 v200, v192
	v_mov_b32_e32 v176, v193
	v_pk_add_f32 v[176:177], v[200:201], v[176:177]
	ds_bpermute_b32 v193, v199, v177
	ds_bpermute_b32 v192, v199, v176
	v_lshlrev_b32_e32 v208, 16, v218
	v_and_b32_e32 v209, 0xffff0000, v218
	v_lshlrev_b32_e32 v202, 16, v216
	v_and_b32_e32 v203, 0xffff0000, v216
	s_waitcnt lgkmcnt(0)
	v_pk_add_f32 v[176:177], v[176:177], v[192:193]
	ds_bpermute_b32 v193, v198, v177
	ds_bpermute_b32 v192, v198, v176
	v_lshlrev_b32_e32 v204, 16, v230
	v_and_b32_e32 v205, 0xffff0000, v230
	v_lshlrev_b32_e32 v200, 16, v217
	v_and_b32_e32 v201, 0xffff0000, v217
	s_waitcnt lgkmcnt(0)
	v_pk_add_f32 v[176:177], v[176:177], v[192:193]
	v_lshlrev_b32_e32 v206, 16, v231
	v_pk_fma_f32 v[192:193], v[176:177], s[20:21], v[166:167] op_sel_hi:[1,0,0]
	v_lshlrev_b32_e32 v176, 16, v219
	v_mul_f32_e32 v168, 0x4b800000, v193
	v_cmp_gt_f32_e32 vcc, s39, v193
	v_and_b32_e32 v177, 0xffff0000, v219
	v_and_b32_e32 v207, 0xffff0000, v231
	v_cndmask_b32_e32 v168, v193, v168, vcc
	v_rsq_f32_e32 v168, v168
	v_lshlrev_b32_e32 v216, 16, v232
	v_and_b32_e32 v217, 0xffff0000, v232
	v_mul_f32_e32 v169, 0x45800000, v168
	v_cndmask_b32_e32 v218, v168, v169, vcc
	v_pk_mul_f32 v[126:127], v[126:127], v[218:219] op_sel_hi:[1,0]
	v_pk_mul_f32 v[128:129], v[128:129], v[218:219] op_sel_hi:[1,0]
	v_pk_mul_f32 v[122:123], v[122:123], v[218:219] op_sel_hi:[1,0]
	v_mul_f32_e32 v126, 0xbfb8aa3b, v126
	v_mul_f32_e32 v127, 0xbfb8aa3b, v127
	v_pk_mul_f32 v[124:125], v[124:125], v[218:219] op_sel_hi:[1,0]
	v_mul_f32_e32 v128, 0xbfb8aa3b, v128
	v_mul_f32_e32 v129, 0xbfb8aa3b, v129
	v_mul_f32_e32 v122, 0xbfb8aa3b, v122
	v_mul_f32_e32 v123, 0xbfb8aa3b, v123
	v_exp_f32_e32 v126, v126
	v_exp_f32_e32 v127, v127
	v_mul_f32_e32 v124, 0xbfb8aa3b, v124
	v_mul_f32_e32 v125, 0xbfb8aa3b, v125
	v_exp_f32_e32 v128, v128
	v_exp_f32_e32 v129, v129
	v_exp_f32_e32 v122, v122
	v_exp_f32_e32 v123, v123
	v_exp_f32_e32 v124, v124
	v_exp_f32_e32 v125, v125
	v_add_f32_e32 v126, 1.0, v126
	v_add_f32_e32 v127, 1.0, v127
	v_add_f32_e32 v128, 1.0, v128
	v_add_f32_e32 v129, 1.0, v129
	v_add_f32_e32 v168, 1.0, v122
	v_add_f32_e32 v169, 1.0, v123
	v_rcp_f32_e32 v122, v126
	v_rcp_f32_e32 v123, v127
	v_add_f32_e32 v193, 1.0, v124
	v_add_f32_e32 v219, 1.0, v125
	v_rcp_f32_e32 v124, v128
	v_rcp_f32_e32 v125, v129
	v_rcp_f32_e32 v126, v168
	v_rcp_f32_e32 v127, v169
	v_rcp_f32_e32 v128, v193
	v_rcp_f32_e32 v129, v219
	v_pk_fma_f32 v[122:123], v[122:123], v[204:205], v[202:203]
	v_pk_fma_f32 v[124:125], v[124:125], v[206:207], v[200:201]
	v_pk_fma_f32 v[126:127], v[126:127], v[216:217], v[208:209]
	v_lshlrev_b32_e32 v200, 16, v233
	v_and_b32_e32 v201, 0xffff0000, v233
	v_cvt_pk_bf16_f32 v122, v122, v123
	v_pk_fma_f32 v[128:129], v[128:129], v[200:201], v[176:177]
	v_cvt_pk_bf16_f32 v123, v124, v125
	v_cvt_pk_bf16_f32 v124, v126, v127
	v_and_b32_e32 v127, 0xffff0000, v122
	v_pk_mul_f32 v[118:119], v[118:119], v[218:219] op_sel_hi:[1,0]
	v_cvt_pk_bf16_f32 v125, v128, v129
	v_lshlrev_b32_e32 v126, 16, v122
	v_mul_f32_e32 v127, v127, v127
	v_and_b32_e32 v128, 0xffff0000, v123
	v_mul_f32_e32 v118, 0xbfb8aa3b, v118
	v_mul_f32_e32 v119, 0xbfb8aa3b, v119
	v_fmac_f32_e32 v127, v126, v126
	v_lshlrev_b32_e32 v126, 16, v123
	v_mul_f32_e32 v128, v128, v128
	v_exp_f32_e32 v118, v118
	v_exp_f32_e32 v119, v119
	v_fmac_f32_e32 v128, v126, v126
	v_add_f32_e32 v126, v127, v128
	v_and_b32_e32 v128, 0xffff0000, v124
	v_pk_mul_f32 v[120:121], v[120:121], v[218:219] op_sel_hi:[1,0]
	v_lshlrev_b32_e32 v127, 16, v124
	v_mul_f32_e32 v128, v128, v128
	v_mul_f32_e32 v120, 0xbfb8aa3b, v120
	v_mul_f32_e32 v121, 0xbfb8aa3b, v121
	v_fmac_f32_e32 v128, v127, v127
	v_add_f32_e32 v118, 1.0, v118
	v_add_f32_e32 v119, 1.0, v119
	v_exp_f32_e32 v120, v120
	v_exp_f32_e32 v121, v121
	v_add_f32_e32 v126, v128, v126
	v_and_b32_e32 v128, 0xffff0000, v125
	v_rcp_f32_e32 v118, v118
	v_rcp_f32_e32 v119, v119
	v_lshlrev_b32_e32 v127, 16, v125
	v_mul_f32_e32 v128, v128, v128
	v_pk_mul_f32 v[114:115], v[114:115], v[218:219] op_sel_hi:[1,0]
	v_fmac_f32_e32 v128, v127, v127
	v_mul_f32_e32 v114, 0xbfb8aa3b, v114
	v_add_f32_e32 v168, v128, v126
	v_pk_mul_f32 v[116:117], v[116:117], v[218:219] op_sel_hi:[1,0]
	v_lshlrev_b32_e32 v126, 16, v146
	v_and_b32_e32 v127, 0xffff0000, v146
	v_lshlrev_b32_e32 v128, 16, v150
	v_and_b32_e32 v129, 0xffff0000, v150
	v_add_f32_e32 v120, 1.0, v120
	v_add_f32_e32 v121, 1.0, v121
	v_exp_f32_e32 v146, v114
	v_mul_f32_e32 v114, 0xbfb8aa3b, v115
	v_pk_fma_f32 v[118:119], v[118:119], v[128:129], v[126:127]
	v_rcp_f32_e32 v120, v120
	v_rcp_f32_e32 v121, v121
	v_lshlrev_b32_e32 v126, 16, v147
	v_and_b32_e32 v127, 0xffff0000, v147
	v_exp_f32_e32 v147, v114
	v_mul_f32_e32 v116, 0xbfb8aa3b, v116
	v_mul_f32_e32 v117, 0xbfb8aa3b, v117
	v_exp_f32_e32 v116, v116
	v_exp_f32_e32 v117, v117
	v_lshlrev_b32_e32 v128, 16, v151
	v_and_b32_e32 v129, 0xffff0000, v151
	v_pk_fma_f32 v[114:115], v[120:121], v[128:129], v[126:127]
	v_add_f32_e32 v120, 1.0, v146
	v_add_f32_e32 v121, 1.0, v147
	v_rcp_f32_e32 v120, v120
	v_rcp_f32_e32 v121, v121
	v_add_f32_e32 v116, 1.0, v116
	v_add_f32_e32 v117, 1.0, v117
	v_rcp_f32_e32 v116, v116
	v_rcp_f32_e32 v117, v117
	v_lshlrev_b32_e32 v126, 16, v148
	v_and_b32_e32 v127, 0xffff0000, v148
	v_lshlrev_b32_e32 v128, 16, v152
	v_and_b32_e32 v129, 0xffff0000, v152
	v_pk_fma_f32 v[120:121], v[120:121], v[128:129], v[126:127]
	v_lshlrev_b32_e32 v126, 16, v149
	v_and_b32_e32 v127, 0xffff0000, v149
	v_lshlrev_b32_e32 v128, 16, v153
	v_and_b32_e32 v129, 0xffff0000, v153
	v_pk_fma_f32 v[126:127], v[116:117], v[128:129], v[126:127]
	v_cvt_pk_bf16_f32 v116, v118, v119
	v_cvt_pk_bf16_f32 v117, v114, v115
	v_and_b32_e32 v115, 0xffff0000, v116
	v_lshlrev_b32_e32 v114, 16, v116
	v_mul_f32_e32 v115, v115, v115
	v_cvt_pk_bf16_f32 v118, v120, v121
	v_fmac_f32_e32 v115, v114, v114
	v_and_b32_e32 v120, 0xffff0000, v117
	v_add_f32_e32 v114, v115, v168
	v_lshlrev_b32_e32 v115, 16, v117
	v_mul_f32_e32 v120, v120, v120
	v_fmac_f32_e32 v120, v115, v115
	v_add_f32_e32 v114, v120, v114
	v_and_b32_e32 v120, 0xffff0000, v118
	v_lshlrev_b32_e32 v115, 16, v118
	v_mul_f32_e32 v120, v120, v120
	v_cvt_pk_bf16_f32 v119, v126, v127
	v_fmac_f32_e32 v120, v115, v115
	v_add_f32_e32 v114, v120, v114
	v_and_b32_e32 v120, 0xffff0000, v119
	v_lshlrev_b32_e32 v115, 16, v119
	v_mul_f32_e32 v120, v120, v120
	v_fmac_f32_e32 v120, v115, v115
	v_add_f32_e32 v114, v120, v114
	ds_bpermute_b32 v115, v199, v114
	v_lshlrev_b64 v[120:121], 11, v[184:185]
	v_lshl_add_u64 v[120:121], s[36:37], 0, v[120:121]
	v_cmp_gt_f32_e32 vcc, s39, v192
	v_lshl_add_u64 v[120:121], v[182:183], 1, v[120:121]
	s_waitcnt lgkmcnt(0)
	v_add_f32_e32 v114, v114, v115
	ds_bpermute_b32 v115, v198, v114
	global_store_dwordx4 v[120:121], v[122:125], off
	global_store_dwordx4 v[120:121], v[116:119], off offset:256
	s_and_saveexec_b64 s[30:31], s[40:41]
	s_cbranch_execz .LBB0_50
	v_lshl_add_u64 v[116:117], s[44:45], 0, v[190:191]
	v_lshl_add_u64 v[116:117], s[28:29], 2, v[116:117]
	s_lshl_b32 s4, s63, 2
	v_lshl_add_u64 v[116:117], v[116:117], 0, s[4:5]
	s_waitcnt lgkmcnt(0)
	v_add_f32_e32 v114, v114, v115
	global_store_dword v[116:117], v114, off

.LBB0_83:
	s_add_u32 s1, s28, 0xfffc0080
	s_addc_u32 s22, s29, -1
	s_add_i32 s23, 0, 0x10000
	v_add_u32_e32 v142, s23, v201
	ds_read_b128 v[130:133], v142
	ds_read_b128 v[134:137], v142 offset:1024
	ds_read_b128 v[138:141], v142 offset:2048
	ds_read_b128 v[142:145], v142 offset:3072
	s_cmp_eq_u32 s60, 12
	s_cselect_b32 s43, s27, s22
	s_cselect_b32 s42, s56, s1
	s_cselect_b32 s31, s7, s59
	s_cselect_b32 s30, s57, s58
	v_lshl_add_u64 v[176:177], s[28:29], 0, v[178:179]
	s_add_i32 m0, s46, 0xc000
	ds_read_b128 v[146:149], v205
	ds_read_b128 v[150:153], v205 offset:1024
	ds_read_b128 v[182:185], v205 offset:2048
	ds_read_b128 v[186:189], v205 offset:3072
	ds_read_b128 v[190:193], v205 offset:4096
	ds_read_b128 v[194:197], v205 offset:5120
	ds_read_b128 v[206:209], v205 offset:6144
	ds_read_b128 v[216:219], v205 offset:7168
	global_load_lds_dwordx4 v[176:177], off
	v_lshl_add_u64 v[176:177], s[28:29], 0, v[180:181]
	s_add_i32 m0, s46, 0xe000
	s_nop 0
	global_load_lds_dwordx4 v[176:177], off
	s_add_i32 s1, 0, 0x14000
	v_add_u32_e32 v168, s1, v201
	ds_read_b128 v[230:233], v168
	ds_read_b128 v[234:237], v168 offset:1024
	ds_read_b128 v[238:241], v168 offset:2048
	ds_read_b128 v[242:245], v168 offset:3072
	s_waitcnt vmcnt(8)
	s_waitcnt lgkmcnt(0)
	s_barrier
	s_setprio 1
	v_mfma_f32_16x16x32_bf16 v[126:129], v[130:133], v[146:149], v[126:129]
	v_mfma_f32_16x16x32_bf16 v[118:121], v[138:141], v[146:149], v[118:121]
	v_mfma_f32_16x16x32_bf16 v[110:113], v[130:133], v[182:185], v[110:113]
	v_mfma_f32_16x16x32_bf16 v[102:105], v[138:141], v[182:185], v[102:105]
	v_mfma_f32_16x16x32_bf16 v[94:97], v[130:133], v[190:193], v[94:97]
	v_mfma_f32_16x16x32_bf16 v[86:89], v[138:141], v[190:193], v[86:89]
	v_mfma_f32_16x16x32_bf16 v[78:81], v[130:133], v[206:209], v[78:81]
	v_mfma_f32_16x16x32_bf16 v[70:73], v[138:141], v[206:209], v[70:73]
	v_mfma_f32_16x16x32_bf16 v[126:129], v[134:137], v[150:153], v[126:129]
	v_mfma_f32_16x16x32_bf16 v[118:121], v[142:145], v[150:153], v[118:121]
	v_mfma_f32_16x16x32_bf16 v[110:113], v[134:137], v[186:189], v[110:113]
	v_mfma_f32_16x16x32_bf16 v[102:105], v[142:145], v[186:189], v[102:105]
	v_mfma_f32_16x16x32_bf16 v[94:97], v[134:137], v[194:197], v[94:97]
	v_mfma_f32_16x16x32_bf16 v[86:89], v[142:145], v[194:197], v[86:89]
	v_mfma_f32_16x16x32_bf16 v[78:81], v[134:137], v[216:219], v[78:81]
	v_mfma_f32_16x16x32_bf16 v[70:73], v[142:145], v[216:219], v[70:73]
	v_mfma_f32_16x16x32_bf16 v[122:125], v[230:233], v[146:149], v[122:125]
	v_mfma_f32_16x16x32_bf16 v[114:117], v[238:241], v[146:149], v[114:117]
	v_mfma_f32_16x16x32_bf16 v[106:109], v[230:233], v[182:185], v[106:109]
	v_mfma_f32_16x16x32_bf16 v[98:101], v[238:241], v[182:185], v[98:101]
	v_mfma_f32_16x16x32_bf16 v[90:93], v[230:233], v[190:193], v[90:93]
	v_mfma_f32_16x16x32_bf16 v[82:85], v[238:241], v[190:193], v[82:85]
	v_mfma_f32_16x16x32_bf16 v[74:77], v[230:233], v[206:209], v[74:77]
	v_mfma_f32_16x16x32_bf16 v[66:69], v[238:241], v[206:209], v[66:69]
	v_mfma_f32_16x16x32_bf16 v[122:125], v[234:237], v[150:153], v[122:125]
	v_mfma_f32_16x16x32_bf16 v[114:117], v[242:245], v[150:153], v[114:117]
	v_mfma_f32_16x16x32_bf16 v[106:109], v[234:237], v[186:189], v[106:109]
	v_mfma_f32_16x16x32_bf16 v[98:101], v[242:245], v[186:189], v[98:101]
	v_mfma_f32_16x16x32_bf16 v[90:93], v[234:237], v[194:197], v[90:93]
	v_mfma_f32_16x16x32_bf16 v[82:85], v[242:245], v[194:197], v[82:85]
	v_mfma_f32_16x16x32_bf16 v[74:77], v[234:237], v[216:219], v[74:77]
	v_mfma_f32_16x16x32_bf16 v[66:69], v[242:245], v[216:219], v[66:69]
	s_setprio 0
	s_barrier
	ds_read_b128 v[146:149], v205 offset:16384
	ds_read_b128 v[150:153], v205 offset:17408
	ds_read_b128 v[182:185], v205 offset:18432
	ds_read_b128 v[186:189], v205 offset:19456
	ds_read_b128 v[190:193], v205 offset:20480
	ds_read_b128 v[194:197], v205 offset:21504
	ds_read_b128 v[206:209], v205 offset:22528
	ds_read_b128 v[216:219], v205 offset:23552
	s_add_i32 s22, s23, s17
	v_lshl_add_u64 v[176:177], s[30:31], 0, v[0:1]
	s_mov_b32 m0, s22
	s_nop 0
	global_load_lds_dwordx4 v[176:177], off
	v_lshl_add_u64 v[202:203], s[30:31], 0, v[154:155]
	s_add_i32 m0, s22, 0x2000
	s_nop 0
	global_load_lds_dwordx4 v[202:203], off
	s_mov_b32 m0, s46
	v_lshl_add_u64 v[220:221], s[42:43], 0, v[158:159]
	global_load_lds_dwordx4 v[220:221], off
	v_lshl_add_u64 v[246:247], s[42:43], 0, v[156:157]
	s_mov_b32 m0, s47
	s_nop 0
	global_load_lds_dwordx4 v[246:247], off
	s_add_u32 s22, s30, 0x40000
	s_addc_u32 s23, s31, 0
	s_add_i32 s1, s1, s17
	s_mov_b32 m0, s1
	s_nop 0
	global_load_lds_dwordx4 v0, s[22:23]
	s_add_i32 m0, s1, 0x2000
	s_nop 0
	global_load_lds_dwordx4 v154, s[22:23]
	s_waitcnt vmcnt(8)
	s_waitcnt lgkmcnt(0)
	s_barrier
	s_setprio 1
	v_mfma_f32_16x16x32_bf16 v[62:65], v[130:133], v[146:149], v[62:65]
	v_mfma_f32_16x16x32_bf16 v[54:57], v[138:141], v[146:149], v[54:57]
	v_mfma_f32_16x16x32_bf16 v[46:49], v[130:133], v[182:185], v[46:49]
	v_mfma_f32_16x16x32_bf16 v[38:41], v[138:141], v[182:185], v[38:41]
	v_mfma_f32_16x16x32_bf16 v[30:33], v[130:133], v[190:193], v[30:33]
	v_mfma_f32_16x16x32_bf16 v[22:25], v[138:141], v[190:193], v[22:25]
	v_mfma_f32_16x16x32_bf16 v[14:17], v[130:133], v[206:209], v[14:17]
	v_mfma_f32_16x16x32_bf16 v[6:9], v[138:141], v[206:209], v[6:9]
	v_mfma_f32_16x16x32_bf16 v[62:65], v[134:137], v[150:153], v[62:65]
	v_mfma_f32_16x16x32_bf16 v[54:57], v[142:145], v[150:153], v[54:57]
	v_mfma_f32_16x16x32_bf16 v[46:49], v[134:137], v[186:189], v[46:49]
	v_mfma_f32_16x16x32_bf16 v[38:41], v[142:145], v[186:189], v[38:41]
	v_mfma_f32_16x16x32_bf16 v[30:33], v[134:137], v[194:197], v[30:33]
	v_mfma_f32_16x16x32_bf16 v[22:25], v[142:145], v[194:197], v[22:25]
	v_mfma_f32_16x16x32_bf16 v[14:17], v[134:137], v[216:219], v[14:17]
	v_mfma_f32_16x16x32_bf16 v[6:9], v[142:145], v[216:219], v[6:9]
	v_mfma_f32_16x16x32_bf16 v[58:61], v[230:233], v[146:149], v[58:61]
	v_mfma_f32_16x16x32_bf16 v[50:53], v[238:241], v[146:149], v[50:53]
	v_mfma_f32_16x16x32_bf16 v[42:45], v[230:233], v[182:185], v[42:45]
	v_mfma_f32_16x16x32_bf16 v[34:37], v[238:241], v[182:185], v[34:37]
	v_mfma_f32_16x16x32_bf16 v[26:29], v[230:233], v[190:193], v[26:29]
	v_mfma_f32_16x16x32_bf16 v[18:21], v[238:241], v[190:193], v[18:21]
	v_mfma_f32_16x16x32_bf16 v[10:13], v[230:233], v[206:209], v[10:13]
	v_mfma_f32_16x16x32_bf16 v[2:5], v[238:241], v[206:209], v[2:5]
	v_mfma_f32_16x16x32_bf16 v[58:61], v[234:237], v[150:153], v[58:61]
	v_mfma_f32_16x16x32_bf16 v[50:53], v[242:245], v[150:153], v[50:53]
	v_mfma_f32_16x16x32_bf16 v[42:45], v[234:237], v[186:189], v[42:45]
	v_mfma_f32_16x16x32_bf16 v[34:37], v[242:245], v[186:189], v[34:37]
	v_mfma_f32_16x16x32_bf16 v[26:29], v[234:237], v[194:197], v[26:29]
	v_mfma_f32_16x16x32_bf16 v[18:21], v[242:245], v[194:197], v[18:21]
	v_mfma_f32_16x16x32_bf16 v[10:13], v[234:237], v[216:219], v[10:13]
	v_mfma_f32_16x16x32_bf16 v[2:5], v[242:245], v[216:219], v[2:5]
	s_setprio 0
	s_barrier
	s_add_i32 s1, 0, 0x18000
	v_add_u32_e32 v142, s1, v201
	ds_read_b128 v[130:133], v142
	ds_read_b128 v[134:137], v142 offset:1024
	ds_read_b128 v[138:141], v142 offset:2048
	ds_read_b128 v[142:145], v142 offset:3072
	s_add_u32 s22, s42, 0x40000
	s_addc_u32 s23, s43, 0
	s_mov_b32 m0, s48
	v_lshl_add_u64 v[230:231], s[22:23], 0, v[158:159]
	ds_read_b128 v[146:149], v205 offset:32768
	ds_read_b128 v[150:153], v205 offset:33792
	ds_read_b128 v[182:185], v205 offset:34816
	ds_read_b128 v[186:189], v205 offset:35840
	ds_read_b128 v[190:193], v205 offset:36864
	ds_read_b128 v[194:197], v205 offset:37888
	ds_read_b128 v[206:209], v205 offset:38912
	ds_read_b128 v[216:219], v205 offset:39936
	global_load_lds_dwordx4 v[230:231], off
	v_lshl_add_u64 v[230:231], s[22:23], 0, v[156:157]
	s_mov_b32 m0, s49
	s_nop 0
	global_load_lds_dwordx4 v[230:231], off
	s_add_i32 s33, 0, 0x1c000
	v_add_u32_e32 v168, s33, v201
	ds_read_b128 v[230:233], v168
	ds_read_b128 v[234:237], v168 offset:1024
	ds_read_b128 v[238:241], v168 offset:2048
	ds_read_b128 v[242:245], v168 offset:3072
	s_waitcnt vmcnt(8)
	s_waitcnt lgkmcnt(0)
	s_barrier
	s_setprio 1
	v_mfma_f32_16x16x32_bf16 v[126:129], v[130:133], v[146:149], v[126:129]
	v_mfma_f32_16x16x32_bf16 v[118:121], v[138:141], v[146:149], v[118:121]
	v_mfma_f32_16x16x32_bf16 v[110:113], v[130:133], v[182:185], v[110:113]
	v_mfma_f32_16x16x32_bf16 v[102:105], v[138:141], v[182:185], v[102:105]
	v_mfma_f32_16x16x32_bf16 v[94:97], v[130:133], v[190:193], v[94:97]
	v_mfma_f32_16x16x32_bf16 v[86:89], v[138:141], v[190:193], v[86:89]
	v_mfma_f32_16x16x32_bf16 v[78:81], v[130:133], v[206:209], v[78:81]
	v_mfma_f32_16x16x32_bf16 v[70:73], v[138:141], v[206:209], v[70:73]
	v_mfma_f32_16x16x32_bf16 v[126:129], v[134:137], v[150:153], v[126:129]
	v_mfma_f32_16x16x32_bf16 v[118:121], v[142:145], v[150:153], v[118:121]
	v_mfma_f32_16x16x32_bf16 v[110:113], v[134:137], v[186:189], v[110:113]
	v_mfma_f32_16x16x32_bf16 v[102:105], v[142:145], v[186:189], v[102:105]
	v_mfma_f32_16x16x32_bf16 v[94:97], v[134:137], v[194:197], v[94:97]
	v_mfma_f32_16x16x32_bf16 v[86:89], v[142:145], v[194:197], v[86:89]
	v_mfma_f32_16x16x32_bf16 v[78:81], v[134:137], v[216:219], v[78:81]
	v_mfma_f32_16x16x32_bf16 v[70:73], v[142:145], v[216:219], v[70:73]
	v_mfma_f32_16x16x32_bf16 v[122:125], v[230:233], v[146:149], v[122:125]
	v_mfma_f32_16x16x32_bf16 v[114:117], v[238:241], v[146:149], v[114:117]
	v_mfma_f32_16x16x32_bf16 v[106:109], v[230:233], v[182:185], v[106:109]
	v_mfma_f32_16x16x32_bf16 v[98:101], v[238:241], v[182:185], v[98:101]
	v_mfma_f32_16x16x32_bf16 v[90:93], v[230:233], v[190:193], v[90:93]
	v_mfma_f32_16x16x32_bf16 v[82:85], v[238:241], v[190:193], v[82:85]
	v_mfma_f32_16x16x32_bf16 v[74:77], v[230:233], v[206:209], v[74:77]
	v_mfma_f32_16x16x32_bf16 v[66:69], v[238:241], v[206:209], v[66:69]
	v_mfma_f32_16x16x32_bf16 v[122:125], v[234:237], v[150:153], v[122:125]
	v_mfma_f32_16x16x32_bf16 v[114:117], v[242:245], v[150:153], v[114:117]
	v_mfma_f32_16x16x32_bf16 v[106:109], v[234:237], v[186:189], v[106:109]
	v_mfma_f32_16x16x32_bf16 v[98:101], v[242:245], v[186:189], v[98:101]
	v_mfma_f32_16x16x32_bf16 v[90:93], v[234:237], v[194:197], v[90:93]
	v_mfma_f32_16x16x32_bf16 v[82:85], v[242:245], v[194:197], v[82:85]
	v_mfma_f32_16x16x32_bf16 v[74:77], v[234:237], v[216:219], v[74:77]
	v_mfma_f32_16x16x32_bf16 v[66:69], v[242:245], v[216:219], v[66:69]
	s_setprio 0
	s_barrier
	ds_read_b128 v[146:149], v205 offset:49152
	ds_read_b128 v[150:153], v205 offset:50176
	ds_read_b128 v[182:185], v205 offset:51200
	ds_read_b128 v[186:189], v205 offset:52224
	ds_read_b128 v[190:193], v205 offset:53248
	ds_read_b128 v[194:197], v205 offset:54272
	ds_read_b128 v[206:209], v205 offset:55296
	ds_read_b128 v[216:219], v205 offset:56320
	s_add_i32 s1, s1, s17
	v_lshl_add_u64 v[176:177], v[176:177], 0, s[12:13]
	s_mov_b32 m0, s1
	s_nop 0
	global_load_lds_dwordx4 v[176:177], off
	v_lshl_add_u64 v[176:177], v[202:203], 0, s[12:13]
	s_add_i32 m0, s1, 0x2000
	s_nop 0
	global_load_lds_dwordx4 v[176:177], off
	s_mov_b32 m0, s20
	v_lshl_add_u64 v[176:177], v[220:221], 0, s[12:13]
	global_load_lds_dwordx4 v[176:177], off
	v_lshl_add_u64 v[176:177], v[246:247], 0, s[12:13]
	s_mov_b32 m0, s21
	s_nop 0
	global_load_lds_dwordx4 v[176:177], off
	s_add_u32 s22, s30, 0x40080
	s_addc_u32 s23, s31, 0
	s_add_i32 s1, s33, s17
	s_mov_b32 m0, s1
	s_nop 0
	global_load_lds_dwordx4 v0, s[22:23]
	s_add_i32 m0, s1, 0x2000
	s_nop 0
	global_load_lds_dwordx4 v154, s[22:23]
	s_waitcnt vmcnt(8)
	s_waitcnt lgkmcnt(0)
	s_barrier
	s_setprio 1
	v_mfma_f32_16x16x32_bf16 v[62:65], v[130:133], v[146:149], v[62:65]
	v_mfma_f32_16x16x32_bf16 v[54:57], v[138:141], v[146:149], v[54:57]
	v_mfma_f32_16x16x32_bf16 v[46:49], v[130:133], v[182:185], v[46:49]
	v_mfma_f32_16x16x32_bf16 v[38:41], v[138:141], v[182:185], v[38:41]
	v_mfma_f32_16x16x32_bf16 v[30:33], v[130:133], v[190:193], v[30:33]
	v_mfma_f32_16x16x32_bf16 v[22:25], v[138:141], v[190:193], v[22:25]
	v_mfma_f32_16x16x32_bf16 v[14:17], v[130:133], v[206:209], v[14:17]
	v_mfma_f32_16x16x32_bf16 v[6:9], v[138:141], v[206:209], v[6:9]
	v_mfma_f32_16x16x32_bf16 v[62:65], v[134:137], v[150:153], v[62:65]
	v_mfma_f32_16x16x32_bf16 v[54:57], v[142:145], v[150:153], v[54:57]
	v_mfma_f32_16x16x32_bf16 v[46:49], v[134:137], v[186:189], v[46:49]
	v_mfma_f32_16x16x32_bf16 v[38:41], v[142:145], v[186:189], v[38:41]
	v_mfma_f32_16x16x32_bf16 v[30:33], v[134:137], v[194:197], v[30:33]
	v_mfma_f32_16x16x32_bf16 v[22:25], v[142:145], v[194:197], v[22:25]
	v_mfma_f32_16x16x32_bf16 v[14:17], v[134:137], v[216:219], v[14:17]
	v_mfma_f32_16x16x32_bf16 v[6:9], v[142:145], v[216:219], v[6:9]
	v_mfma_f32_16x16x32_bf16 v[58:61], v[230:233], v[146:149], v[58:61]
	v_mfma_f32_16x16x32_bf16 v[50:53], v[238:241], v[146:149], v[50:53]
	v_mfma_f32_16x16x32_bf16 v[42:45], v[230:233], v[182:185], v[42:45]
	v_mfma_f32_16x16x32_bf16 v[34:37], v[238:241], v[182:185], v[34:37]
	v_mfma_f32_16x16x32_bf16 v[26:29], v[230:233], v[190:193], v[26:29]
	v_mfma_f32_16x16x32_bf16 v[18:21], v[238:241], v[190:193], v[18:21]
	v_mfma_f32_16x16x32_bf16 v[10:13], v[230:233], v[206:209], v[10:13]
	v_mfma_f32_16x16x32_bf16 v[2:5], v[238:241], v[206:209], v[2:5]
	v_mfma_f32_16x16x32_bf16 v[58:61], v[234:237], v[150:153], v[58:61]
	v_mfma_f32_16x16x32_bf16 v[50:53], v[242:245], v[150:153], v[50:53]
	v_mfma_f32_16x16x32_bf16 v[42:45], v[234:237], v[186:189], v[42:45]
	v_mfma_f32_16x16x32_bf16 v[34:37], v[242:245], v[186:189], v[34:37]
	v_mfma_f32_16x16x32_bf16 v[26:29], v[234:237], v[194:197], v[26:29]
	v_mfma_f32_16x16x32_bf16 v[18:21], v[242:245], v[194:197], v[18:21]
	v_mfma_f32_16x16x32_bf16 v[10:13], v[234:237], v[216:219], v[10:13]
	v_mfma_f32_16x16x32_bf16 v[2:5], v[242:245], v[216:219], v[2:5]
	s_setprio 0
	s_add_i32 s60, s60, 2
	s_add_u32 s28, s28, 0x100
	s_addc_u32 s29, s29, 0
	s_add_u32 s58, s58, 0x100
	s_addc_u32 s59, s59, 0
	s_cmp_gt_u32 s60, 13
	s_barrier
	s_cbranch_scc0 .LBB0_83
	v_lshl_add_u32 v196, s55, 8, v199
	v_ashrrev_i32_e32 v197, 31, v196
	v_lshlrev_b64 v[130:131], 6, v[196:197]
	v_or_b32_e32 v194, 16, v196
	v_lshl_add_u64 v[130:131], v[160:161], 0, v[130:131]
	v_ashrrev_i32_e32 v195, 31, v194
	global_load_dwordx4 v[206:209], v[130:131], off
	v_lshlrev_b64 v[130:131], 6, v[194:195]
	v_lshl_add_u64 v[130:131], v[160:161], 0, v[130:131]
	global_load_dwordx4 v[216:219], v[130:131], off
	v_or_b32_e32 v192, 32, v196
	v_ashrrev_i32_e32 v193, 31, v192
	v_lshlrev_b64 v[130:131], 6, v[192:193]
	v_or_b32_e32 v190, 48, v196
	v_lshl_add_u64 v[130:131], v[160:161], 0, v[130:131]
	v_ashrrev_i32_e32 v191, 31, v190
	global_load_dwordx4 v[150:153], v[130:131], off
	v_lshlrev_b64 v[130:131], 6, v[190:191]
	v_lshl_add_u64 v[130:131], v[160:161], 0, v[130:131]
	global_load_dwordx4 v[146:149], v[130:131], off
	v_add_u32_e32 v188, 0x80, v196
	v_ashrrev_i32_e32 v189, 31, v188
	v_lshlrev_b64 v[130:131], 6, v[188:189]
	v_add_u32_e32 v186, 0x90, v196
	v_lshl_add_u64 v[130:131], v[160:161], 0, v[130:131]
	v_ashrrev_i32_e32 v187, 31, v186
	global_load_dwordx4 v[142:145], v[130:131], off
	v_lshlrev_b64 v[130:131], 6, v[186:187]
	v_lshl_add_u64 v[130:131], v[160:161], 0, v[130:131]
	global_load_dwordx4 v[138:141], v[130:131], off
	v_add_u32_e32 v184, 0xa0, v196
	v_ashrrev_i32_e32 v185, 31, v184
	v_lshlrev_b64 v[130:131], 6, v[184:185]
	v_add_u32_e32 v182, 0xb0, v196
	v_lshl_add_u64 v[130:131], v[160:161], 0, v[130:131]
	v_ashrrev_i32_e32 v183, 31, v182
	global_load_dwordx4 v[134:137], v[130:131], off
	v_lshlrev_b64 v[130:131], 6, v[182:183]
	v_lshl_add_u64 v[130:131], v[160:161], 0, v[130:131]
	global_load_dwordx4 v[130:133], v[130:131], off
	v_and_b32_e32 v169, 64, v212
	v_xor_b32_e32 v168, 16, v212
	v_add_u32_e32 v169, 64, v169
	v_cmp_lt_i32_e32 vcc, v168, v169
	s_mov_b32 s22, 0x358637bd
	s_mov_b32 s55, s26
	v_cndmask_b32_e32 v168, v212, v168, vcc
	v_lshlrev_b32_e32 v185, 2, v168
	v_xor_b32_e32 v168, 32, v212
	v_cmp_lt_i32_e32 vcc, v168, v169
	s_mov_b64 s[30:31], s[44:45]
	s_mov_b64 s[28:29], s[36:37]
	v_cndmask_b32_e32 v168, v212, v168, vcc
	v_lshlrev_b32_e32 v183, 2, v168
	s_cmpk_gt_u32 s0, 0xff
	s_cbranch_scc1 .Lrs_i2_post
	s_barrier
.Lrs_i2_post:
	s_waitcnt vmcnt(0)
	v_mov_b32_e32 v176, v207
	v_mov_b32_e32 v177, v208
	v_mov_b32_e32 v207, v209
	v_mov_b32_e32 v202, v217
	v_mov_b32_e32 v203, v218
	v_mov_b32_e32 v217, v219
	v_pk_add_f32 v[176:177], v[176:177], v[206:207]
	v_pk_add_f32 v[202:203], v[202:203], v[216:217]
	v_mov_b32_e32 v207, v176
	v_mov_b32_e32 v206, v202
	v_mov_b32_e32 v176, v203
	v_pk_add_f32 v[176:177], v[206:207], v[176:177]
	ds_bpermute_b32 v203, v185, v177
	ds_bpermute_b32 v202, v185, v176
	s_waitcnt lgkmcnt(0)
	v_pk_add_f32 v[176:177], v[176:177], v[202:203]
	ds_bpermute_b32 v203, v183, v177
	ds_bpermute_b32 v202, v183, v176
	s_waitcnt lgkmcnt(0)
	v_pk_add_f32 v[176:177], v[176:177], v[202:203]
	v_mov_b64_e32 v[202:203], s[22:23]
	s_mov_b32 s22, 0x3a800000
	v_pk_fma_f32 v[176:177], v[176:177], s[22:23], v[202:203] op_sel_hi:[1,0,0]
	s_nop 0
	v_mul_f32_e32 v168, 0x4b800000, v177
	v_cmp_gt_f32_e64 s[42:43], s39, v177
	v_cmp_gt_f32_e32 vcc, s39, v176
	s_nop 0
	v_cndmask_b32_e64 v168, v177, v168, s[42:43]
	v_rsq_f32_e32 v168, v168
	v_mov_b32_e32 v177, v152
	v_mov_b32_e32 v152, v147
	v_mov_b32_e32 v147, v149
	v_mul_f32_e32 v169, 0x45800000, v168
	v_cndmask_b32_e64 v200, v168, v169, s[42:43]
	v_mul_f32_e32 v168, 0x4b800000, v176
	v_cndmask_b32_e32 v168, v176, v168, vcc
	v_mov_b32_e32 v176, v151
	v_mov_b32_e32 v151, v153
	v_mov_b32_e32 v153, v148
	v_pk_add_f32 v[150:151], v[176:177], v[150:151]
	v_pk_add_f32 v[146:147], v[152:153], v[146:147]
	v_mov_b32_e32 v149, v150
	v_mov_b32_e32 v148, v146
	v_mov_b32_e32 v150, v147
	v_pk_add_f32 v[146:147], v[148:149], v[150:151]
	ds_bpermute_b32 v149, v185, v147
	ds_bpermute_b32 v148, v185, v146
	v_mov_b32_e32 v150, v143
	v_mov_b32_e32 v151, v144
	v_mov_b32_e32 v143, v145
	v_mov_b32_e32 v144, v139
	v_mov_b32_e32 v145, v140
	v_mov_b32_e32 v139, v141
	v_pk_add_f32 v[142:143], v[150:151], v[142:143]
	v_pk_add_f32 v[138:139], v[144:145], v[138:139]
	s_waitcnt lgkmcnt(0)
	v_pk_add_f32 v[146:147], v[146:147], v[148:149]
	v_mov_b32_e32 v140, v138
	v_mov_b32_e32 v141, v142
	v_mov_b32_e32 v142, v139
	ds_bpermute_b32 v149, v183, v147
	ds_bpermute_b32 v148, v183, v146
	v_pk_add_f32 v[138:139], v[140:141], v[142:143]
	ds_bpermute_b32 v141, v185, v139
	ds_bpermute_b32 v140, v185, v138
	v_mov_b32_e32 v142, v135
	v_mov_b32_e32 v143, v136
	v_mov_b32_e32 v135, v137
	v_mov_b32_e32 v136, v131
	v_mov_b32_e32 v137, v132
	v_mov_b32_e32 v131, v133
	s_waitcnt lgkmcnt(2)
	v_pk_add_f32 v[146:147], v[146:147], v[148:149]
	v_pk_add_f32 v[134:135], v[142:143], v[134:135]
	v_pk_add_f32 v[130:131], v[136:137], v[130:131]
	v_pk_fma_f32 v[146:147], v[146:147], s[22:23], v[202:203] op_sel_hi:[1,0,0]
	s_waitcnt lgkmcnt(0)
	v_pk_add_f32 v[138:139], v[138:139], v[140:141]
	v_mov_b32_e32 v132, v130
	v_mov_b32_e32 v133, v134
	v_mov_b32_e32 v134, v131
	v_mul_f32_e32 v148, 0x4b800000, v147
	v_cmp_gt_f32_e64 s[42:43], s39, v147
	ds_bpermute_b32 v141, v183, v139
	ds_bpermute_b32 v140, v183, v138
	v_pk_add_f32 v[130:131], v[132:133], v[134:135]
	v_cndmask_b32_e64 v147, v147, v148, s[42:43]
	ds_bpermute_b32 v133, v185, v131
	ds_bpermute_b32 v132, v185, v130
	v_rsq_f32_e32 v168, v168
	v_rsq_f32_e32 v147, v147
	s_waitcnt lgkmcnt(2)
	v_pk_add_f32 v[138:139], v[138:139], v[140:141]
	v_pk_mul_f32 v[126:127], v[126:127], v[200:201] op_sel_hi:[1,0]
	v_mul_f32_e32 v169, 0x45800000, v168
	v_mul_f32_e32 v148, 0x45800000, v147
	v_pk_fma_f32 v[138:139], v[138:139], s[22:23], v[202:203] op_sel_hi:[1,0,0]
	s_waitcnt lgkmcnt(0)
	v_pk_add_f32 v[130:131], v[130:131], v[132:133]
	v_cndmask_b32_e32 v198, v168, v169, vcc
	v_cmp_gt_f32_e32 vcc, s39, v146
	v_cndmask_b32_e64 v148, v147, v148, s[42:43]
	v_mul_f32_e32 v147, 0x4b800000, v146
	v_mul_f32_e32 v140, 0x4b800000, v139
	v_cmp_gt_f32_e64 s[42:43], s39, v139
	ds_bpermute_b32 v133, v183, v131
	ds_bpermute_b32 v132, v183, v130
	v_cndmask_b32_e32 v146, v146, v147, vcc
	v_cndmask_b32_e64 v139, v139, v140, s[42:43]
	v_rsq_f32_e32 v146, v146
	v_rsq_f32_e32 v139, v139
	s_waitcnt lgkmcnt(0)
	v_pk_add_f32 v[130:131], v[130:131], v[132:133]
	v_pk_mul_f32 v[122:123], v[122:123], v[200:201] op_sel_hi:[1,0]
	v_mul_f32_e32 v147, 0x45800000, v146
	v_mul_f32_e32 v140, 0x45800000, v139
	v_pk_fma_f32 v[130:131], v[130:131], s[22:23], v[202:203] op_sel_hi:[1,0,0]
	v_cndmask_b32_e32 v146, v146, v147, vcc
	v_cmp_gt_f32_e32 vcc, s39, v138
	v_cndmask_b32_e64 v140, v139, v140, s[42:43]
	v_mul_f32_e32 v139, 0x4b800000, v138
	v_mul_f32_e32 v132, 0x4b800000, v131
	v_cmp_gt_f32_e64 s[42:43], s39, v131
	v_cndmask_b32_e32 v138, v138, v139, vcc
	v_rsq_f32_e32 v138, v138
	v_cndmask_b32_e64 v131, v131, v132, s[42:43]
	v_rsq_f32_e32 v131, v131
	v_pk_mul_f32 v[124:125], v[124:125], v[200:201] op_sel_hi:[1,0]
	v_mul_f32_e32 v139, 0x45800000, v138
	v_cndmask_b32_e32 v138, v138, v139, vcc
	v_mul_f32_e32 v132, 0x45800000, v131
	v_cmp_gt_f32_e32 vcc, s39, v130
	v_cndmask_b32_e64 v132, v131, v132, s[42:43]
	v_mul_f32_e32 v131, 0x4b800000, v130
	v_cndmask_b32_e32 v130, v130, v131, vcc
	v_rsq_f32_e32 v130, v130
	v_pk_mul_f32 v[118:119], v[118:119], v[200:201] op_sel_hi:[1,0]
	v_pk_mul_f32 v[114:115], v[114:115], v[200:201] op_sel_hi:[1,0]
	v_lshl_or_b32 v134, s34, 7, v204
	v_mul_f32_e32 v131, 0x45800000, v130
	v_cndmask_b32_e32 v130, v130, v131, vcc
	v_mul_f32_e32 v131, 0xbfb8aa3b, v126
	v_exp_f32_e32 v131, v131
	v_pk_mul_f32 v[116:117], v[116:117], v[200:201] op_sel_hi:[1,0]
	v_ashrrev_i32_e32 v135, 31, v134
	v_pk_mul_f32 v[110:111], v[110:111], v[198:199] op_sel_hi:[1,0]
	v_add_f32_e32 v131, 1.0, v131
	v_rcp_f32_e32 v136, v131
	v_mul_f32_e32 v131, 0xbfb8aa3b, v127
	v_exp_f32_e32 v131, v131
	v_pk_mul_f32 v[106:107], v[106:107], v[198:199] op_sel_hi:[1,0]
	v_pk_mul_f32 v[108:109], v[108:109], v[198:199] op_sel_hi:[1,0]
	v_pk_mul_f32 v[102:103], v[102:103], v[198:199] op_sel_hi:[1,0]
	v_add_f32_e32 v131, 1.0, v131
	v_rcp_f32_e32 v137, v131
	v_pk_mul_f32 v[98:99], v[98:99], v[198:199] op_sel_hi:[1,0]
	v_pk_mul_f32 v[100:101], v[100:101], v[198:199] op_sel_hi:[1,0]
	v_pk_mul_f32 v[94:95], v[94:95], v[148:149] op_sel_hi:[1,0]
	v_pk_mul_f32 v[126:127], v[126:127], v[136:137]
	v_pk_mul_f32 v[90:91], v[90:91], v[148:149] op_sel_hi:[1,0]
	v_pk_mul_f32 v[122:123], v[122:123], v[126:127]
	v_pk_mul_f32 v[126:127], v[128:129], v[200:201] op_sel_hi:[1,0]
	v_cvt_pk_bf16_f32 v122, v122, v123
	v_mul_f32_e32 v128, 0xbfb8aa3b, v126
	v_mul_f32_e32 v129, 0xbfb8aa3b, v127
	v_exp_f32_e32 v128, v128
	v_exp_f32_e32 v129, v129
	v_pk_mul_f32 v[92:93], v[92:93], v[148:149] op_sel_hi:[1,0]
	v_pk_mul_f32 v[86:87], v[86:87], v[148:149] op_sel_hi:[1,0]
	v_add_f32_e32 v128, 1.0, v128
	v_add_f32_e32 v129, 1.0, v129
	v_rcp_f32_e32 v128, v128
	v_rcp_f32_e32 v129, v129
	v_pk_mul_f32 v[82:83], v[82:83], v[148:149] op_sel_hi:[1,0]
	v_pk_mul_f32 v[84:85], v[84:85], v[148:149] op_sel_hi:[1,0]
	v_pk_mul_f32 v[78:79], v[78:79], v[146:147] op_sel_hi:[1,0]
	v_pk_mul_f32 v[126:127], v[126:127], v[128:129]
	v_pk_mul_f32 v[74:75], v[74:75], v[146:147] op_sel_hi:[1,0]
	v_pk_mul_f32 v[124:125], v[124:125], v[126:127]
	v_pk_mul_f32 v[76:77], v[76:77], v[146:147] op_sel_hi:[1,0]
	v_cvt_pk_bf16_f32 v123, v124, v125
	v_mul_f32_e32 v124, 0xbfb8aa3b, v118
	v_mul_f32_e32 v125, 0xbfb8aa3b, v119
	v_exp_f32_e32 v124, v124
	v_exp_f32_e32 v125, v125
	v_pk_mul_f32 v[70:71], v[70:71], v[146:147] op_sel_hi:[1,0]
	v_pk_mul_f32 v[66:67], v[66:67], v[146:147] op_sel_hi:[1,0]
	v_add_f32_e32 v124, 1.0, v124
	v_add_f32_e32 v125, 1.0, v125
	v_rcp_f32_e32 v124, v124
	v_rcp_f32_e32 v125, v125
	v_pk_mul_f32 v[68:69], v[68:69], v[146:147] op_sel_hi:[1,0]
	v_pk_mul_f32 v[62:63], v[62:63], v[140:141] op_sel_hi:[1,0]
	v_pk_mul_f32 v[58:59], v[58:59], v[140:141] op_sel_hi:[1,0]
	v_pk_mul_f32 v[118:119], v[118:119], v[124:125]
	v_pk_mul_f32 v[60:61], v[60:61], v[140:141] op_sel_hi:[1,0]
	v_pk_mul_f32 v[114:115], v[114:115], v[118:119]
	v_pk_mul_f32 v[118:119], v[120:121], v[200:201] op_sel_hi:[1,0]
	v_cvt_pk_bf16_f32 v124, v114, v115
	v_mul_f32_e32 v120, 0xbfb8aa3b, v118
	v_mul_f32_e32 v121, 0xbfb8aa3b, v119
	v_exp_f32_e32 v120, v120
	v_exp_f32_e32 v121, v121
	v_mov_b64_e32 v[114:115], s[68:69]
	v_pk_mul_f32 v[54:55], v[54:55], v[140:141] op_sel_hi:[1,0]
	v_add_f32_e32 v120, 1.0, v120
	v_add_f32_e32 v121, 1.0, v121
	v_rcp_f32_e32 v120, v120
	v_rcp_f32_e32 v121, v121
	v_pk_mul_f32 v[50:51], v[50:51], v[140:141] op_sel_hi:[1,0]
	v_pk_mul_f32 v[52:53], v[52:53], v[140:141] op_sel_hi:[1,0]
	v_pk_mul_f32 v[46:47], v[46:47], v[138:139] op_sel_hi:[1,0]
	v_pk_mul_f32 v[118:119], v[118:119], v[120:121]
	v_pk_mul_f32 v[42:43], v[42:43], v[138:139] op_sel_hi:[1,0]
	v_pk_mul_f32 v[116:117], v[116:117], v[118:119]
	v_mad_i64_i32 v[118:119], s[22:23], v196, s38, v[114:115]
	v_cvt_pk_bf16_f32 v125, v116, v117
	v_lshlrev_b64 v[116:117], 1, v[134:135]
	v_lshl_add_u64 v[118:119], v[118:119], 0, v[116:117]
	global_store_dwordx4 v[118:119], v[122:125], off
	v_mul_f32_e32 v118, 0xbfb8aa3b, v110
	v_mul_f32_e32 v119, 0xbfb8aa3b, v111
	v_exp_f32_e32 v118, v118
	v_exp_f32_e32 v119, v119
	v_pk_mul_f32 v[44:45], v[44:45], v[138:139] op_sel_hi:[1,0]
	v_pk_mul_f32 v[38:39], v[38:39], v[138:139] op_sel_hi:[1,0]
	v_add_f32_e32 v118, 1.0, v118
	v_add_f32_e32 v119, 1.0, v119
	v_rcp_f32_e32 v118, v118
	v_rcp_f32_e32 v119, v119
	v_pk_mul_f32 v[34:35], v[34:35], v[138:139] op_sel_hi:[1,0]
	v_pk_mul_f32 v[36:37], v[36:37], v[138:139] op_sel_hi:[1,0]
	v_pk_mul_f32 v[30:31], v[30:31], v[132:133] op_sel_hi:[1,0]
	v_pk_mul_f32 v[110:111], v[110:111], v[118:119]
	v_pk_mul_f32 v[26:27], v[26:27], v[132:133] op_sel_hi:[1,0]
	v_pk_mul_f32 v[106:107], v[106:107], v[110:111]
	v_pk_mul_f32 v[110:111], v[112:113], v[198:199] op_sel_hi:[1,0]
	v_cvt_pk_bf16_f32 v106, v106, v107
	v_mul_f32_e32 v112, 0xbfb8aa3b, v110
	v_mul_f32_e32 v113, 0xbfb8aa3b, v111
	v_exp_f32_e32 v112, v112
	v_exp_f32_e32 v113, v113
	v_pk_mul_f32 v[28:29], v[28:29], v[132:133] op_sel_hi:[1,0]
	v_pk_mul_f32 v[22:23], v[22:23], v[132:133] op_sel_hi:[1,0]
	v_add_f32_e32 v112, 1.0, v112
	v_add_f32_e32 v113, 1.0, v113
	v_rcp_f32_e32 v112, v112
	v_rcp_f32_e32 v113, v113
	v_pk_mul_f32 v[18:19], v[18:19], v[132:133] op_sel_hi:[1,0]
	v_pk_mul_f32 v[20:21], v[20:21], v[132:133] op_sel_hi:[1,0]
	v_pk_mul_f32 v[14:15], v[14:15], v[130:131] op_sel_hi:[1,0]
	v_pk_mul_f32 v[110:111], v[110:111], v[112:113]
	v_pk_mul_f32 v[10:11], v[10:11], v[130:131] op_sel_hi:[1,0]
	v_pk_mul_f32 v[108:109], v[108:109], v[110:111]
	v_pk_mul_f32 v[12:13], v[12:13], v[130:131] op_sel_hi:[1,0]
	v_cvt_pk_bf16_f32 v107, v108, v109
	v_mul_f32_e32 v108, 0xbfb8aa3b, v102
	v_mul_f32_e32 v109, 0xbfb8aa3b, v103
	v_exp_f32_e32 v108, v108
	v_exp_f32_e32 v109, v109
	v_pk_mul_f32 v[6:7], v[6:7], v[130:131] op_sel_hi:[1,0]
	v_pk_mul_f32 v[2:3], v[2:3], v[130:131] op_sel_hi:[1,0]
	v_add_f32_e32 v108, 1.0, v108
	v_add_f32_e32 v109, 1.0, v109
	v_rcp_f32_e32 v108, v108
	v_rcp_f32_e32 v109, v109
	v_pk_mul_f32 v[4:5], v[4:5], v[130:131] op_sel_hi:[1,0]
	s_and_b64 vcc, exec, s[40:41]
	s_mov_b32 s34, s6
	v_pk_mul_f32 v[102:103], v[102:103], v[108:109]
	s_nop 0
	v_pk_mul_f32 v[98:99], v[98:99], v[102:103]
	v_pk_mul_f32 v[102:103], v[104:105], v[198:199] op_sel_hi:[1,0]
	v_cvt_pk_bf16_f32 v108, v98, v99
	v_mul_f32_e32 v104, 0xbfb8aa3b, v102
	v_mul_f32_e32 v105, 0xbfb8aa3b, v103
	v_exp_f32_e32 v104, v104
	v_exp_f32_e32 v105, v105
	v_mad_i64_i32 v[98:99], s[22:23], v194, s38, v[114:115]
	v_add_f32_e32 v104, 1.0, v104
	v_add_f32_e32 v105, 1.0, v105
	v_rcp_f32_e32 v104, v104
	v_rcp_f32_e32 v105, v105
	v_lshl_add_u64 v[98:99], v[98:99], 0, v[116:117]
	v_pk_mul_f32 v[102:103], v[102:103], v[104:105]
	s_nop 0
	v_pk_mul_f32 v[100:101], v[100:101], v[102:103]
	s_nop 0
	v_cvt_pk_bf16_f32 v109, v100, v101
	global_store_dwordx4 v[98:99], v[106:109], off
	v_mul_f32_e32 v98, 0xbfb8aa3b, v94
	v_mul_f32_e32 v99, 0xbfb8aa3b, v95
	v_exp_f32_e32 v98, v98
	v_exp_f32_e32 v99, v99
	v_add_f32_e32 v98, 1.0, v98
	v_add_f32_e32 v99, 1.0, v99
	v_rcp_f32_e32 v98, v98
	v_rcp_f32_e32 v99, v99
	s_nop 0
	v_pk_mul_f32 v[94:95], v[94:95], v[98:99]
	s_nop 0
	v_pk_mul_f32 v[90:91], v[90:91], v[94:95]
	v_pk_mul_f32 v[94:95], v[96:97], v[148:149] op_sel_hi:[1,0]
	v_cvt_pk_bf16_f32 v90, v90, v91
	v_mul_f32_e32 v96, 0xbfb8aa3b, v94
	v_mul_f32_e32 v97, 0xbfb8aa3b, v95
	v_exp_f32_e32 v96, v96
	v_exp_f32_e32 v97, v97
	v_add_f32_e32 v96, 1.0, v96
	v_add_f32_e32 v97, 1.0, v97
	v_rcp_f32_e32 v96, v96
	v_rcp_f32_e32 v97, v97
	s_nop 0
	v_pk_mul_f32 v[94:95], v[94:95], v[96:97]
	s_nop 0
	v_pk_mul_f32 v[92:93], v[92:93], v[94:95]
	s_nop 0
	v_cvt_pk_bf16_f32 v91, v92, v93
	v_mul_f32_e32 v92, 0xbfb8aa3b, v86
	v_mul_f32_e32 v93, 0xbfb8aa3b, v87
	v_exp_f32_e32 v92, v92
	v_exp_f32_e32 v93, v93
	v_add_f32_e32 v92, 1.0, v92
	v_add_f32_e32 v93, 1.0, v93
	v_rcp_f32_e32 v92, v92
	v_rcp_f32_e32 v93, v93
	s_nop 0
	v_pk_mul_f32 v[86:87], v[86:87], v[92:93]
	s_nop 0
	v_pk_mul_f32 v[82:83], v[82:83], v[86:87]
	v_pk_mul_f32 v[86:87], v[88:89], v[148:149] op_sel_hi:[1,0]
	v_cvt_pk_bf16_f32 v92, v82, v83
	v_mul_f32_e32 v88, 0xbfb8aa3b, v86
	v_mul_f32_e32 v89, 0xbfb8aa3b, v87
	v_exp_f32_e32 v88, v88
	v_exp_f32_e32 v89, v89
	v_mad_i64_i32 v[82:83], s[22:23], v192, s38, v[114:115]
	v_add_f32_e32 v88, 1.0, v88
	v_add_f32_e32 v89, 1.0, v89
	v_rcp_f32_e32 v88, v88
	v_rcp_f32_e32 v89, v89
	v_lshl_add_u64 v[82:83], v[82:83], 0, v[116:117]
	v_pk_mul_f32 v[86:87], v[86:87], v[88:89]
	s_nop 0
	v_pk_mul_f32 v[84:85], v[84:85], v[86:87]
	s_nop 0
	v_cvt_pk_bf16_f32 v93, v84, v85
	global_store_dwordx4 v[82:83], v[90:93], off
	v_mul_f32_e32 v82, 0xbfb8aa3b, v78
	v_mul_f32_e32 v83, 0xbfb8aa3b, v79
	v_exp_f32_e32 v82, v82
	v_exp_f32_e32 v83, v83
	v_add_f32_e32 v82, 1.0, v82
	v_add_f32_e32 v83, 1.0, v83
	v_rcp_f32_e32 v82, v82
	v_rcp_f32_e32 v83, v83
	s_nop 0
	v_pk_mul_f32 v[78:79], v[78:79], v[82:83]
	s_nop 0
	v_pk_mul_f32 v[74:75], v[74:75], v[78:79]
	v_pk_mul_f32 v[78:79], v[80:81], v[146:147] op_sel_hi:[1,0]
	v_cvt_pk_bf16_f32 v74, v74, v75
	v_mul_f32_e32 v80, 0xbfb8aa3b, v78
	v_mul_f32_e32 v81, 0xbfb8aa3b, v79
	v_exp_f32_e32 v80, v80
	v_exp_f32_e32 v81, v81
	v_add_f32_e32 v80, 1.0, v80
	v_add_f32_e32 v81, 1.0, v81
	v_rcp_f32_e32 v80, v80
	v_rcp_f32_e32 v81, v81
	s_nop 0
	v_pk_mul_f32 v[78:79], v[78:79], v[80:81]
	s_nop 0
	v_pk_mul_f32 v[76:77], v[76:77], v[78:79]
	s_nop 0
	v_cvt_pk_bf16_f32 v75, v76, v77
	v_mul_f32_e32 v76, 0xbfb8aa3b, v70
	v_mul_f32_e32 v77, 0xbfb8aa3b, v71
	v_exp_f32_e32 v76, v76
	v_exp_f32_e32 v77, v77
	v_add_f32_e32 v76, 1.0, v76
	v_add_f32_e32 v77, 1.0, v77
	v_rcp_f32_e32 v76, v76
	v_rcp_f32_e32 v77, v77
	s_nop 0
	v_pk_mul_f32 v[70:71], v[70:71], v[76:77]
	s_nop 0
	v_pk_mul_f32 v[66:67], v[66:67], v[70:71]
	v_pk_mul_f32 v[70:71], v[72:73], v[146:147] op_sel_hi:[1,0]
	v_cvt_pk_bf16_f32 v76, v66, v67
	v_mul_f32_e32 v72, 0xbfb8aa3b, v70
	v_mul_f32_e32 v73, 0xbfb8aa3b, v71
	v_exp_f32_e32 v72, v72
	v_exp_f32_e32 v73, v73
	v_mad_i64_i32 v[66:67], s[22:23], v190, s38, v[114:115]
	v_add_f32_e32 v72, 1.0, v72
	v_add_f32_e32 v73, 1.0, v73
	v_rcp_f32_e32 v72, v72
	v_rcp_f32_e32 v73, v73
	v_lshl_add_u64 v[66:67], v[66:67], 0, v[116:117]
	v_pk_mul_f32 v[70:71], v[70:71], v[72:73]
	s_nop 0
	v_pk_mul_f32 v[68:69], v[68:69], v[70:71]
	s_nop 0
	v_cvt_pk_bf16_f32 v77, v68, v69
	global_store_dwordx4 v[66:67], v[74:77], off
	v_mul_f32_e32 v66, 0xbfb8aa3b, v62
	v_mul_f32_e32 v67, 0xbfb8aa3b, v63
	v_exp_f32_e32 v66, v66
	v_exp_f32_e32 v67, v67
	v_add_f32_e32 v66, 1.0, v66
	v_add_f32_e32 v67, 1.0, v67
	v_rcp_f32_e32 v66, v66
	v_rcp_f32_e32 v67, v67
	s_nop 0
	v_pk_mul_f32 v[62:63], v[62:63], v[66:67]
	s_nop 0
	v_pk_mul_f32 v[58:59], v[58:59], v[62:63]
	v_pk_mul_f32 v[62:63], v[64:65], v[140:141] op_sel_hi:[1,0]
	v_cvt_pk_bf16_f32 v58, v58, v59
	v_mul_f32_e32 v64, 0xbfb8aa3b, v62
	v_mul_f32_e32 v65, 0xbfb8aa3b, v63
	v_exp_f32_e32 v64, v64
	v_exp_f32_e32 v65, v65
	v_add_f32_e32 v64, 1.0, v64
	v_add_f32_e32 v65, 1.0, v65
	v_rcp_f32_e32 v64, v64
	v_rcp_f32_e32 v65, v65
	s_nop 0
	v_pk_mul_f32 v[62:63], v[62:63], v[64:65]
	s_nop 0
	v_pk_mul_f32 v[60:61], v[60:61], v[62:63]
	s_nop 0
	v_cvt_pk_bf16_f32 v59, v60, v61
	v_mul_f32_e32 v60, 0xbfb8aa3b, v54
	v_mul_f32_e32 v61, 0xbfb8aa3b, v55
	v_exp_f32_e32 v60, v60
	v_exp_f32_e32 v61, v61
	v_add_f32_e32 v60, 1.0, v60
	v_add_f32_e32 v61, 1.0, v61
	v_rcp_f32_e32 v60, v60
	v_rcp_f32_e32 v61, v61
	s_nop 0
	v_pk_mul_f32 v[54:55], v[54:55], v[60:61]
	s_nop 0
	v_pk_mul_f32 v[50:51], v[50:51], v[54:55]
	v_pk_mul_f32 v[54:55], v[56:57], v[140:141] op_sel_hi:[1,0]
	v_cvt_pk_bf16_f32 v60, v50, v51
	v_mul_f32_e32 v56, 0xbfb8aa3b, v54
	v_mul_f32_e32 v57, 0xbfb8aa3b, v55
	v_exp_f32_e32 v56, v56
	v_exp_f32_e32 v57, v57
	v_mad_i64_i32 v[50:51], s[22:23], v188, s38, v[114:115]
	v_add_f32_e32 v56, 1.0, v56
	v_add_f32_e32 v57, 1.0, v57
	v_rcp_f32_e32 v56, v56
	v_rcp_f32_e32 v57, v57
	v_lshl_add_u64 v[50:51], v[50:51], 0, v[116:117]
	v_pk_mul_f32 v[54:55], v[54:55], v[56:57]
	s_nop 0
	v_pk_mul_f32 v[52:53], v[52:53], v[54:55]
	s_nop 0
	v_cvt_pk_bf16_f32 v61, v52, v53
	global_store_dwordx4 v[50:51], v[58:61], off
	v_mul_f32_e32 v50, 0xbfb8aa3b, v46
	v_mul_f32_e32 v51, 0xbfb8aa3b, v47
	v_exp_f32_e32 v50, v50
	v_exp_f32_e32 v51, v51
	v_add_f32_e32 v50, 1.0, v50
	v_add_f32_e32 v51, 1.0, v51
	v_rcp_f32_e32 v50, v50
	v_rcp_f32_e32 v51, v51
	s_nop 0
	v_pk_mul_f32 v[46:47], v[46:47], v[50:51]
	s_nop 0
	v_pk_mul_f32 v[42:43], v[42:43], v[46:47]
	v_pk_mul_f32 v[46:47], v[48:49], v[138:139] op_sel_hi:[1,0]
	v_cvt_pk_bf16_f32 v42, v42, v43
	v_mul_f32_e32 v48, 0xbfb8aa3b, v46
	v_mul_f32_e32 v49, 0xbfb8aa3b, v47
	v_exp_f32_e32 v48, v48
	v_exp_f32_e32 v49, v49
	v_add_f32_e32 v48, 1.0, v48
	v_add_f32_e32 v49, 1.0, v49
	v_rcp_f32_e32 v48, v48
	v_rcp_f32_e32 v49, v49
	s_nop 0
	v_pk_mul_f32 v[46:47], v[46:47], v[48:49]
	s_nop 0
	v_pk_mul_f32 v[44:45], v[44:45], v[46:47]
	s_nop 0
	v_cvt_pk_bf16_f32 v43, v44, v45
	v_mul_f32_e32 v44, 0xbfb8aa3b, v38
	v_mul_f32_e32 v45, 0xbfb8aa3b, v39
	v_exp_f32_e32 v44, v44
	v_exp_f32_e32 v45, v45
	v_add_f32_e32 v44, 1.0, v44
	v_add_f32_e32 v45, 1.0, v45
	v_rcp_f32_e32 v44, v44
	v_rcp_f32_e32 v45, v45
	s_nop 0
	v_pk_mul_f32 v[38:39], v[38:39], v[44:45]
	s_nop 0
	v_pk_mul_f32 v[34:35], v[34:35], v[38:39]
	v_pk_mul_f32 v[38:39], v[40:41], v[138:139] op_sel_hi:[1,0]
	v_cvt_pk_bf16_f32 v44, v34, v35
	v_mul_f32_e32 v40, 0xbfb8aa3b, v38
	v_mul_f32_e32 v41, 0xbfb8aa3b, v39
	v_exp_f32_e32 v40, v40
	v_exp_f32_e32 v41, v41
	v_mad_i64_i32 v[34:35], s[22:23], v186, s38, v[114:115]
	v_add_f32_e32 v40, 1.0, v40
	v_add_f32_e32 v41, 1.0, v41
	v_rcp_f32_e32 v40, v40
	v_rcp_f32_e32 v41, v41
	v_lshl_add_u64 v[34:35], v[34:35], 0, v[116:117]
	v_pk_mul_f32 v[38:39], v[38:39], v[40:41]
	s_nop 0
	v_pk_mul_f32 v[36:37], v[36:37], v[38:39]
	s_nop 0
	v_cvt_pk_bf16_f32 v45, v36, v37
	global_store_dwordx4 v[34:35], v[42:45], off
	v_mul_f32_e32 v34, 0xbfb8aa3b, v30
	v_mul_f32_e32 v35, 0xbfb8aa3b, v31
	v_exp_f32_e32 v34, v34
	v_exp_f32_e32 v35, v35
	v_add_f32_e32 v34, 1.0, v34
	v_add_f32_e32 v35, 1.0, v35
	v_rcp_f32_e32 v34, v34
	v_rcp_f32_e32 v35, v35
	s_nop 0
	v_pk_mul_f32 v[30:31], v[30:31], v[34:35]
	s_nop 0
	v_pk_mul_f32 v[26:27], v[26:27], v[30:31]
	v_pk_mul_f32 v[30:31], v[32:33], v[132:133] op_sel_hi:[1,0]
	v_cvt_pk_bf16_f32 v26, v26, v27
	v_mul_f32_e32 v32, 0xbfb8aa3b, v30
	v_mul_f32_e32 v33, 0xbfb8aa3b, v31
	v_exp_f32_e32 v32, v32
	v_exp_f32_e32 v33, v33
	v_add_f32_e32 v32, 1.0, v32
	v_add_f32_e32 v33, 1.0, v33
	v_rcp_f32_e32 v32, v32
	v_rcp_f32_e32 v33, v33
	s_nop 0
	v_pk_mul_f32 v[30:31], v[30:31], v[32:33]
	s_nop 0
	v_pk_mul_f32 v[28:29], v[28:29], v[30:31]
	s_nop 0
	v_cvt_pk_bf16_f32 v27, v28, v29
	v_mul_f32_e32 v28, 0xbfb8aa3b, v22
	v_mul_f32_e32 v29, 0xbfb8aa3b, v23
	v_exp_f32_e32 v28, v28
	v_exp_f32_e32 v29, v29
	v_add_f32_e32 v28, 1.0, v28
	v_add_f32_e32 v29, 1.0, v29
	v_rcp_f32_e32 v28, v28
	v_rcp_f32_e32 v29, v29
	s_nop 0
	v_pk_mul_f32 v[22:23], v[22:23], v[28:29]
	s_nop 0
	v_pk_mul_f32 v[18:19], v[18:19], v[22:23]
	v_pk_mul_f32 v[22:23], v[24:25], v[132:133] op_sel_hi:[1,0]
	v_cvt_pk_bf16_f32 v28, v18, v19
	v_mul_f32_e32 v24, 0xbfb8aa3b, v22
	v_mul_f32_e32 v25, 0xbfb8aa3b, v23
	v_exp_f32_e32 v24, v24
	v_exp_f32_e32 v25, v25
	v_mad_i64_i32 v[18:19], s[22:23], v184, s38, v[114:115]
	v_add_f32_e32 v24, 1.0, v24
	v_add_f32_e32 v25, 1.0, v25
	v_rcp_f32_e32 v24, v24
	v_rcp_f32_e32 v25, v25
	v_lshl_add_u64 v[18:19], v[18:19], 0, v[116:117]
	v_pk_mul_f32 v[22:23], v[22:23], v[24:25]
	s_nop 0
	v_pk_mul_f32 v[20:21], v[20:21], v[22:23]
	s_nop 0
	v_cvt_pk_bf16_f32 v29, v20, v21
	global_store_dwordx4 v[18:19], v[26:29], off
	v_mul_f32_e32 v18, 0xbfb8aa3b, v14
	v_mul_f32_e32 v19, 0xbfb8aa3b, v15
	v_exp_f32_e32 v18, v18
	v_exp_f32_e32 v19, v19
	v_add_f32_e32 v18, 1.0, v18
	v_add_f32_e32 v19, 1.0, v19
	v_rcp_f32_e32 v18, v18
	v_rcp_f32_e32 v19, v19
	s_nop 0
	v_pk_mul_f32 v[14:15], v[14:15], v[18:19]
	s_nop 0
	v_pk_mul_f32 v[10:11], v[10:11], v[14:15]
	v_pk_mul_f32 v[14:15], v[16:17], v[130:131] op_sel_hi:[1,0]
	v_cvt_pk_bf16_f32 v10, v10, v11
	v_mul_f32_e32 v16, 0xbfb8aa3b, v14
	v_mul_f32_e32 v17, 0xbfb8aa3b, v15
	v_exp_f32_e32 v16, v16
	v_exp_f32_e32 v17, v17
	v_add_f32_e32 v16, 1.0, v16
	v_add_f32_e32 v17, 1.0, v17
	v_rcp_f32_e32 v16, v16
	v_rcp_f32_e32 v17, v17
	s_nop 0
	v_pk_mul_f32 v[14:15], v[14:15], v[16:17]
	s_nop 0
	v_pk_mul_f32 v[12:13], v[12:13], v[14:15]
	s_nop 0
	v_cvt_pk_bf16_f32 v11, v12, v13
	v_mul_f32_e32 v12, 0xbfb8aa3b, v6
	v_mul_f32_e32 v13, 0xbfb8aa3b, v7
	v_exp_f32_e32 v12, v12
	v_exp_f32_e32 v13, v13
	v_add_f32_e32 v12, 1.0, v12
	v_add_f32_e32 v13, 1.0, v13
	v_rcp_f32_e32 v12, v12
	v_rcp_f32_e32 v13, v13
	s_nop 0
	v_pk_mul_f32 v[6:7], v[6:7], v[12:13]
	s_nop 0
	v_pk_mul_f32 v[2:3], v[2:3], v[6:7]
	v_pk_mul_f32 v[6:7], v[8:9], v[130:131] op_sel_hi:[1,0]
	v_cvt_pk_bf16_f32 v12, v2, v3
	v_mul_f32_e32 v8, 0xbfb8aa3b, v6
	v_mul_f32_e32 v9, 0xbfb8aa3b, v7
	v_exp_f32_e32 v8, v8
	v_exp_f32_e32 v9, v9
	v_mad_i64_i32 v[2:3], s[22:23], v182, s38, v[114:115]
	v_add_f32_e32 v8, 1.0, v8
	v_add_f32_e32 v9, 1.0, v9
	v_rcp_f32_e32 v8, v8
	v_rcp_f32_e32 v9, v9
	v_lshl_add_u64 v[2:3], v[2:3], 0, v[116:117]
	v_pk_mul_f32 v[6:7], v[6:7], v[8:9]
	s_nop 0
	v_pk_mul_f32 v[4:5], v[4:5], v[6:7]
	s_nop 0
	v_cvt_pk_bf16_f32 v13, v4, v5
	global_store_dwordx4 v[2:3], v[10:13], off
	s_cbranch_vccz .LBB0_80
	s_waitcnt vmcnt(0)
	s_cmpk_gt_u32 s0, 0xff
	s_cbranch_scc1 .LBB0_87
	s_nop 0

.LBB0_120:
	s_add_i32 s23, s22, 2
	s_add_u32 s1, s36, 0x80
	s_addc_u32 s30, s37, 0
	s_add_i32 s33, 0, 0x10000
	v_add_u32_e32 v142, s33, v203
	ds_read_b128 v[130:133], v142
	ds_read_b128 v[134:137], v142 offset:1024
	ds_read_b128 v[138:141], v142 offset:2048
	ds_read_b128 v[142:145], v142 offset:3072
	s_cmp_eq_u32 s69, s22
	s_cselect_b32 s31, s27, s30
	s_cselect_b32 s30, s26, s1
	s_cselect_b32 s47, s29, s49
	s_cselect_b32 s46, s28, s48
	v_lshl_add_u64 v[176:177], s[36:37], 0, v[180:181]
	s_add_i32 m0, s21, 0xc000
	ds_read_b128 v[146:149], v205
	ds_read_b128 v[150:153], v205 offset:1024
	ds_read_b128 v[154:157], v205 offset:2048
	ds_read_b128 v[184:187], v205 offset:3072
	ds_read_b128 v[188:191], v205 offset:4096
	ds_read_b128 v[192:195], v205 offset:5120
	ds_read_b128 v[196:199], v205 offset:6144
	ds_read_b128 v[206:209], v205 offset:7168
	global_load_lds_dwordx4 v[176:177], off
	v_lshl_add_u64 v[176:177], s[36:37], 0, v[182:183]
	s_add_i32 m0, s21, 0xe000
	s_nop 0
	global_load_lds_dwordx4 v[176:177], off
	s_add_i32 s1, 0, 0x14000
	v_add_u32_e32 v168, s1, v203
	ds_read_b128 v[216:219], v168
	ds_read_b128 v[230:233], v168 offset:1024
	ds_read_b128 v[234:237], v168 offset:2048
	ds_read_b128 v[238:241], v168 offset:3072
	s_waitcnt vmcnt(8)
	s_waitcnt lgkmcnt(0)
	s_barrier
	s_setprio 1
	v_mfma_f32_16x16x32_bf16 v[126:129], v[130:133], v[146:149], v[126:129]
	v_mfma_f32_16x16x32_bf16 v[122:125], v[138:141], v[146:149], v[122:125]
	v_mfma_f32_16x16x32_bf16 v[110:113], v[130:133], v[154:157], v[110:113]
	v_mfma_f32_16x16x32_bf16 v[106:109], v[138:141], v[154:157], v[106:109]
	v_mfma_f32_16x16x32_bf16 v[94:97], v[130:133], v[188:191], v[94:97]
	v_mfma_f32_16x16x32_bf16 v[90:93], v[138:141], v[188:191], v[90:93]
	v_mfma_f32_16x16x32_bf16 v[78:81], v[130:133], v[196:199], v[78:81]
	v_mfma_f32_16x16x32_bf16 v[74:77], v[138:141], v[196:199], v[74:77]
	v_mfma_f32_16x16x32_bf16 v[126:129], v[134:137], v[150:153], v[126:129]
	v_mfma_f32_16x16x32_bf16 v[122:125], v[142:145], v[150:153], v[122:125]
	v_mfma_f32_16x16x32_bf16 v[110:113], v[134:137], v[184:187], v[110:113]
	v_mfma_f32_16x16x32_bf16 v[106:109], v[142:145], v[184:187], v[106:109]
	v_mfma_f32_16x16x32_bf16 v[94:97], v[134:137], v[192:195], v[94:97]
	v_mfma_f32_16x16x32_bf16 v[90:93], v[142:145], v[192:195], v[90:93]
	v_mfma_f32_16x16x32_bf16 v[78:81], v[134:137], v[206:209], v[78:81]
	v_mfma_f32_16x16x32_bf16 v[74:77], v[142:145], v[206:209], v[74:77]
	v_mfma_f32_16x16x32_bf16 v[118:121], v[216:219], v[146:149], v[118:121]
	v_mfma_f32_16x16x32_bf16 v[114:117], v[234:237], v[146:149], v[114:117]
	v_mfma_f32_16x16x32_bf16 v[102:105], v[216:219], v[154:157], v[102:105]
	v_mfma_f32_16x16x32_bf16 v[98:101], v[234:237], v[154:157], v[98:101]
	v_mfma_f32_16x16x32_bf16 v[86:89], v[216:219], v[188:191], v[86:89]
	v_mfma_f32_16x16x32_bf16 v[82:85], v[234:237], v[188:191], v[82:85]
	v_mfma_f32_16x16x32_bf16 v[70:73], v[216:219], v[196:199], v[70:73]
	v_mfma_f32_16x16x32_bf16 v[66:69], v[234:237], v[196:199], v[66:69]
	v_mfma_f32_16x16x32_bf16 v[118:121], v[230:233], v[150:153], v[118:121]
	v_mfma_f32_16x16x32_bf16 v[114:117], v[238:241], v[150:153], v[114:117]
	v_mfma_f32_16x16x32_bf16 v[102:105], v[230:233], v[184:187], v[102:105]
	v_mfma_f32_16x16x32_bf16 v[98:101], v[238:241], v[184:187], v[98:101]
	v_mfma_f32_16x16x32_bf16 v[86:89], v[230:233], v[192:195], v[86:89]
	v_mfma_f32_16x16x32_bf16 v[82:85], v[238:241], v[192:195], v[82:85]
	v_mfma_f32_16x16x32_bf16 v[70:73], v[230:233], v[206:209], v[70:73]
	v_mfma_f32_16x16x32_bf16 v[66:69], v[238:241], v[206:209], v[66:69]
	s_setprio 0
	s_barrier
	ds_read_b128 v[146:149], v205 offset:16384
	ds_read_b128 v[150:153], v205 offset:17408
	ds_read_b128 v[154:157], v205 offset:18432
	ds_read_b128 v[184:187], v205 offset:19456
	ds_read_b128 v[188:191], v205 offset:20480
	ds_read_b128 v[192:195], v205 offset:21504
	ds_read_b128 v[196:199], v205 offset:22528
	ds_read_b128 v[206:209], v205 offset:23552
	s_add_i32 s22, s33, s20
	v_lshl_add_u64 v[176:177], s[46:47], 0, v[0:1]
	s_mov_b32 m0, s22
	s_nop 0
	global_load_lds_dwordx4 v[176:177], off
	v_lshl_add_u64 v[200:201], s[46:47], 0, v[158:159]
	s_add_i32 m0, s22, 0x2000
	s_nop 0
	global_load_lds_dwordx4 v[200:201], off
	s_mov_b32 m0, s21
	v_lshl_add_u64 v[220:221], s[30:31], 0, v[178:179]
	global_load_lds_dwordx4 v[220:221], off
	v_lshl_add_u64 v[242:243], s[30:31], 0, v[160:161]
	s_mov_b32 m0, s34
	s_nop 0
	global_load_lds_dwordx4 v[242:243], off
	s_add_u32 s46, s46, s6
	s_addc_u32 s47, s47, 0
	s_add_i32 s1, s1, s20
	v_lshl_add_u64 v[244:245], s[46:47], 0, v[0:1]
	s_mov_b32 m0, s1
	v_lshl_add_u64 v[246:247], s[46:47], 0, v[158:159]
	global_load_lds_dwordx4 v[244:245], off
	s_add_i32 m0, s1, 0x2000
	s_nop 0
	global_load_lds_dwordx4 v[246:247], off
	s_waitcnt vmcnt(8)
	s_waitcnt lgkmcnt(0)
	s_barrier
	s_setprio 1
	v_mfma_f32_16x16x32_bf16 v[62:65], v[130:133], v[146:149], v[62:65]
	v_mfma_f32_16x16x32_bf16 v[58:61], v[138:141], v[146:149], v[58:61]
	v_mfma_f32_16x16x32_bf16 v[46:49], v[130:133], v[154:157], v[46:49]
	v_mfma_f32_16x16x32_bf16 v[42:45], v[138:141], v[154:157], v[42:45]
	v_mfma_f32_16x16x32_bf16 v[30:33], v[130:133], v[188:191], v[30:33]
	v_mfma_f32_16x16x32_bf16 v[26:29], v[138:141], v[188:191], v[26:29]
	v_mfma_f32_16x16x32_bf16 v[14:17], v[130:133], v[196:199], v[14:17]
	v_mfma_f32_16x16x32_bf16 v[10:13], v[138:141], v[196:199], v[10:13]
	v_mfma_f32_16x16x32_bf16 v[62:65], v[134:137], v[150:153], v[62:65]
	v_mfma_f32_16x16x32_bf16 v[58:61], v[142:145], v[150:153], v[58:61]
	v_mfma_f32_16x16x32_bf16 v[46:49], v[134:137], v[184:187], v[46:49]
	v_mfma_f32_16x16x32_bf16 v[42:45], v[142:145], v[184:187], v[42:45]
	v_mfma_f32_16x16x32_bf16 v[30:33], v[134:137], v[192:195], v[30:33]
	v_mfma_f32_16x16x32_bf16 v[26:29], v[142:145], v[192:195], v[26:29]
	v_mfma_f32_16x16x32_bf16 v[14:17], v[134:137], v[206:209], v[14:17]
	v_mfma_f32_16x16x32_bf16 v[10:13], v[142:145], v[206:209], v[10:13]
	v_mfma_f32_16x16x32_bf16 v[54:57], v[216:219], v[146:149], v[54:57]
	v_mfma_f32_16x16x32_bf16 v[50:53], v[234:237], v[146:149], v[50:53]
	v_mfma_f32_16x16x32_bf16 v[38:41], v[216:219], v[154:157], v[38:41]
	v_mfma_f32_16x16x32_bf16 v[34:37], v[234:237], v[154:157], v[34:37]
	v_mfma_f32_16x16x32_bf16 v[22:25], v[216:219], v[188:191], v[22:25]
	v_mfma_f32_16x16x32_bf16 v[18:21], v[234:237], v[188:191], v[18:21]
	v_mfma_f32_16x16x32_bf16 v[6:9], v[216:219], v[196:199], v[6:9]
	v_mfma_f32_16x16x32_bf16 v[2:5], v[234:237], v[196:199], v[2:5]
	v_mfma_f32_16x16x32_bf16 v[54:57], v[230:233], v[150:153], v[54:57]
	v_mfma_f32_16x16x32_bf16 v[50:53], v[238:241], v[150:153], v[50:53]
	v_mfma_f32_16x16x32_bf16 v[38:41], v[230:233], v[184:187], v[38:41]
	v_mfma_f32_16x16x32_bf16 v[34:37], v[238:241], v[184:187], v[34:37]
	v_mfma_f32_16x16x32_bf16 v[22:25], v[230:233], v[192:195], v[22:25]
	v_mfma_f32_16x16x32_bf16 v[18:21], v[238:241], v[192:195], v[18:21]
	v_mfma_f32_16x16x32_bf16 v[6:9], v[230:233], v[206:209], v[6:9]
	v_mfma_f32_16x16x32_bf16 v[2:5], v[238:241], v[206:209], v[2:5]
	s_setprio 0
	s_barrier
	s_add_i32 s1, 0, 0x18000
	v_add_u32_e32 v142, s1, v203
	ds_read_b128 v[130:133], v142
	ds_read_b128 v[134:137], v142 offset:1024
	ds_read_b128 v[138:141], v142 offset:2048
	ds_read_b128 v[142:145], v142 offset:3072
	s_add_u32 s30, s30, s6
	s_addc_u32 s31, s31, 0
	s_mov_b32 m0, s63
	v_lshl_add_u64 v[216:217], s[30:31], 0, v[178:179]
	ds_read_b128 v[146:149], v205 offset:32768
	ds_read_b128 v[150:153], v205 offset:33792
	ds_read_b128 v[154:157], v205 offset:34816
	ds_read_b128 v[184:187], v205 offset:35840
	ds_read_b128 v[188:191], v205 offset:36864
	ds_read_b128 v[192:195], v205 offset:37888
	ds_read_b128 v[196:199], v205 offset:38912
	ds_read_b128 v[206:209], v205 offset:39936
	global_load_lds_dwordx4 v[216:217], off
	v_lshl_add_u64 v[216:217], s[30:31], 0, v[160:161]
	s_mov_b32 m0, s64
	s_nop 0
	global_load_lds_dwordx4 v[216:217], off
	s_add_i32 s22, 0, 0x1c000
	v_add_u32_e32 v168, s22, v203
	ds_read_b128 v[216:219], v168
	ds_read_b128 v[230:233], v168 offset:1024
	ds_read_b128 v[234:237], v168 offset:2048
	ds_read_b128 v[238:241], v168 offset:3072
	s_waitcnt vmcnt(8)
	s_waitcnt lgkmcnt(0)
	s_barrier
	s_setprio 1
	v_mfma_f32_16x16x32_bf16 v[126:129], v[130:133], v[146:149], v[126:129]
	v_mfma_f32_16x16x32_bf16 v[122:125], v[138:141], v[146:149], v[122:125]
	v_mfma_f32_16x16x32_bf16 v[110:113], v[130:133], v[154:157], v[110:113]
	v_mfma_f32_16x16x32_bf16 v[106:109], v[138:141], v[154:157], v[106:109]
	v_mfma_f32_16x16x32_bf16 v[94:97], v[130:133], v[188:191], v[94:97]
	v_mfma_f32_16x16x32_bf16 v[90:93], v[138:141], v[188:191], v[90:93]
	v_mfma_f32_16x16x32_bf16 v[78:81], v[130:133], v[196:199], v[78:81]
	v_mfma_f32_16x16x32_bf16 v[74:77], v[138:141], v[196:199], v[74:77]
	v_mfma_f32_16x16x32_bf16 v[126:129], v[134:137], v[150:153], v[126:129]
	v_mfma_f32_16x16x32_bf16 v[122:125], v[142:145], v[150:153], v[122:125]
	v_mfma_f32_16x16x32_bf16 v[110:113], v[134:137], v[184:187], v[110:113]
	v_mfma_f32_16x16x32_bf16 v[106:109], v[142:145], v[184:187], v[106:109]
	v_mfma_f32_16x16x32_bf16 v[94:97], v[134:137], v[192:195], v[94:97]
	v_mfma_f32_16x16x32_bf16 v[90:93], v[142:145], v[192:195], v[90:93]
	v_mfma_f32_16x16x32_bf16 v[78:81], v[134:137], v[206:209], v[78:81]
	v_mfma_f32_16x16x32_bf16 v[74:77], v[142:145], v[206:209], v[74:77]
	v_mfma_f32_16x16x32_bf16 v[118:121], v[216:219], v[146:149], v[118:121]
	v_mfma_f32_16x16x32_bf16 v[114:117], v[234:237], v[146:149], v[114:117]
	v_mfma_f32_16x16x32_bf16 v[102:105], v[216:219], v[154:157], v[102:105]
	v_mfma_f32_16x16x32_bf16 v[98:101], v[234:237], v[154:157], v[98:101]
	v_mfma_f32_16x16x32_bf16 v[86:89], v[216:219], v[188:191], v[86:89]
	v_mfma_f32_16x16x32_bf16 v[82:85], v[234:237], v[188:191], v[82:85]
	v_mfma_f32_16x16x32_bf16 v[70:73], v[216:219], v[196:199], v[70:73]
	v_mfma_f32_16x16x32_bf16 v[66:69], v[234:237], v[196:199], v[66:69]
	v_mfma_f32_16x16x32_bf16 v[118:121], v[230:233], v[150:153], v[118:121]
	v_mfma_f32_16x16x32_bf16 v[114:117], v[238:241], v[150:153], v[114:117]
	v_mfma_f32_16x16x32_bf16 v[102:105], v[230:233], v[184:187], v[102:105]
	v_mfma_f32_16x16x32_bf16 v[98:101], v[238:241], v[184:187], v[98:101]
	v_mfma_f32_16x16x32_bf16 v[86:89], v[230:233], v[192:195], v[86:89]
	v_mfma_f32_16x16x32_bf16 v[82:85], v[238:241], v[192:195], v[82:85]
	v_mfma_f32_16x16x32_bf16 v[70:73], v[230:233], v[206:209], v[70:73]
	v_mfma_f32_16x16x32_bf16 v[66:69], v[238:241], v[206:209], v[66:69]
	s_setprio 0
	s_barrier
	ds_read_b128 v[146:149], v205 offset:49152
	ds_read_b128 v[150:153], v205 offset:50176
	ds_read_b128 v[154:157], v205 offset:51200
	ds_read_b128 v[184:187], v205 offset:52224
	ds_read_b128 v[188:191], v205 offset:53248
	ds_read_b128 v[192:195], v205 offset:54272
	ds_read_b128 v[196:199], v205 offset:55296
	ds_read_b128 v[206:209], v205 offset:56320
	s_add_i32 s1, s1, s20
	v_lshl_add_u64 v[176:177], v[176:177], 0, s[12:13]
	s_mov_b32 m0, s1
	s_nop 0
	global_load_lds_dwordx4 v[176:177], off
	v_lshl_add_u64 v[176:177], v[200:201], 0, s[12:13]
	s_add_i32 m0, s1, 0x2000
	s_nop 0
	global_load_lds_dwordx4 v[176:177], off
	s_mov_b32 m0, s65
	v_lshl_add_u64 v[176:177], v[220:221], 0, s[12:13]
	global_load_lds_dwordx4 v[176:177], off
	v_lshl_add_u64 v[176:177], v[242:243], 0, s[12:13]
	s_mov_b32 m0, s66
	s_nop 0
	global_load_lds_dwordx4 v[176:177], off
	s_add_i32 s1, s22, s20
	v_lshl_add_u64 v[176:177], v[244:245], 0, s[12:13]
	s_mov_b32 m0, s1
	s_nop 0
	global_load_lds_dwordx4 v[176:177], off
	v_lshl_add_u64 v[176:177], v[246:247], 0, s[12:13]
	s_add_i32 m0, s1, 0x2000
	s_nop 0
	global_load_lds_dwordx4 v[176:177], off
	s_waitcnt vmcnt(8)
	s_waitcnt lgkmcnt(0)
	s_barrier
	s_setprio 1
	v_mfma_f32_16x16x32_bf16 v[62:65], v[130:133], v[146:149], v[62:65]
	v_mfma_f32_16x16x32_bf16 v[58:61], v[138:141], v[146:149], v[58:61]
	v_mfma_f32_16x16x32_bf16 v[46:49], v[130:133], v[154:157], v[46:49]
	v_mfma_f32_16x16x32_bf16 v[42:45], v[138:141], v[154:157], v[42:45]
	v_mfma_f32_16x16x32_bf16 v[30:33], v[130:133], v[188:191], v[30:33]
	v_mfma_f32_16x16x32_bf16 v[26:29], v[138:141], v[188:191], v[26:29]
	v_mfma_f32_16x16x32_bf16 v[14:17], v[130:133], v[196:199], v[14:17]
	v_mfma_f32_16x16x32_bf16 v[10:13], v[138:141], v[196:199], v[10:13]
	v_mfma_f32_16x16x32_bf16 v[62:65], v[134:137], v[150:153], v[62:65]
	v_mfma_f32_16x16x32_bf16 v[58:61], v[142:145], v[150:153], v[58:61]
	v_mfma_f32_16x16x32_bf16 v[46:49], v[134:137], v[184:187], v[46:49]
	v_mfma_f32_16x16x32_bf16 v[42:45], v[142:145], v[184:187], v[42:45]
	v_mfma_f32_16x16x32_bf16 v[30:33], v[134:137], v[192:195], v[30:33]
	v_mfma_f32_16x16x32_bf16 v[26:29], v[142:145], v[192:195], v[26:29]
	v_mfma_f32_16x16x32_bf16 v[14:17], v[134:137], v[206:209], v[14:17]
	v_mfma_f32_16x16x32_bf16 v[10:13], v[142:145], v[206:209], v[10:13]
	v_mfma_f32_16x16x32_bf16 v[54:57], v[216:219], v[146:149], v[54:57]
	v_mfma_f32_16x16x32_bf16 v[50:53], v[234:237], v[146:149], v[50:53]
	v_mfma_f32_16x16x32_bf16 v[38:41], v[216:219], v[154:157], v[38:41]
	v_mfma_f32_16x16x32_bf16 v[34:37], v[234:237], v[154:157], v[34:37]
	v_mfma_f32_16x16x32_bf16 v[22:25], v[216:219], v[188:191], v[22:25]
	v_mfma_f32_16x16x32_bf16 v[18:21], v[234:237], v[188:191], v[18:21]
	v_mfma_f32_16x16x32_bf16 v[6:9], v[216:219], v[196:199], v[6:9]
	v_mfma_f32_16x16x32_bf16 v[2:5], v[234:237], v[196:199], v[2:5]
	v_mfma_f32_16x16x32_bf16 v[54:57], v[230:233], v[150:153], v[54:57]
	v_mfma_f32_16x16x32_bf16 v[50:53], v[238:241], v[150:153], v[50:53]
	v_mfma_f32_16x16x32_bf16 v[38:41], v[230:233], v[184:187], v[38:41]
	v_mfma_f32_16x16x32_bf16 v[34:37], v[238:241], v[184:187], v[34:37]
	v_mfma_f32_16x16x32_bf16 v[22:25], v[230:233], v[192:195], v[22:25]
	v_mfma_f32_16x16x32_bf16 v[18:21], v[238:241], v[192:195], v[18:21]
	v_mfma_f32_16x16x32_bf16 v[6:9], v[230:233], v[206:209], v[6:9]
	v_mfma_f32_16x16x32_bf16 v[2:5], v[238:241], v[206:209], v[2:5]
	s_setprio 0
	s_add_u32 s36, s36, 0x100
	s_addc_u32 s37, s37, 0
	s_add_u32 s48, s48, 0x100
	s_addc_u32 s49, s49, 0
	s_cmp_ge_u32 s23, s68
	s_mov_b32 s22, s23
	s_barrier
	s_cbranch_scc0 .LBB0_120
	v_and_b32_e32 v131, 64, v212
	v_xor_b32_e32 v130, 16, v212
	v_add_u32_e32 v131, 64, v131
	v_cmp_lt_i32_e32 vcc, v130, v131
	v_lshl_or_b32 v184, s4, 8, v204
	v_lshl_add_u32 v186, s72, 8, v202
	v_cndmask_b32_e32 v130, v212, v130, vcc
	v_ashrrev_i32_e32 v185, 31, v184
	v_lshlrev_b32_e32 v206, 2, v130
	v_xor_b32_e32 v130, 32, v212
	v_cmp_lt_i32_e32 vcc, v130, v131
	v_lshlrev_b64 v[176:177], 1, v[184:185]
	v_ashrrev_i32_e32 v187, 31, v186
	v_cndmask_b32_e32 v130, v212, v130, vcc
	v_lshl_add_u64 v[188:189], s[96:97], 0, v[176:177]
	v_lshlrev_b64 v[208:209], 11, v[186:187]
	v_lshlrev_b32_e32 v207, 2, v130
	v_lshl_add_u64 v[130:131], v[188:189], 0, v[208:209]
	global_load_dwordx4 v[216:219], v[130:131], off
	global_load_dwordx4 v[154:157], v[130:131], off offset:256
	v_or_b32_e32 v198, 16, v186
	v_ashrrev_i32_e32 v199, 31, v198
	v_or_b32_e32 v194, 32, v186
	v_lshlrev_b64 v[200:201], 11, v[198:199]
	v_ashrrev_i32_e32 v195, 31, v194
	v_or_b32_e32 v190, 48, v186
	v_lshl_add_u64 v[130:131], v[188:189], 0, v[200:201]
	v_lshlrev_b64 v[196:197], 11, v[194:195]
	v_ashrrev_i32_e32 v191, 31, v190
	global_load_dwordx4 v[150:153], v[130:131], off
	global_load_dwordx4 v[146:149], v[130:131], off offset:256
	v_lshl_add_u64 v[130:131], v[188:189], 0, v[196:197]
	v_lshlrev_b64 v[192:193], 11, v[190:191]
	global_load_dwordx4 v[142:145], v[130:131], off
	global_load_dwordx4 v[134:137], v[130:131], off offset:256
	v_lshl_add_u64 v[130:131], v[188:189], 0, v[192:193]
	global_load_dwordx4 v[138:141], v[130:131], off
	s_nop 0
	global_load_dwordx4 v[130:133], v[130:131], off offset:256
	s_lshl_b32 s36, s4, 2
	s_ashr_i32 s37, s36, 31
	s_cmpk_gt_u32 s16, 0xff
	s_cbranch_scc1 .Lrs_i3_post
	s_barrier
.Lrs_i3_post:
	s_waitcnt vmcnt(0)
	v_lshlrev_b32_e32 v220, 16, v216
	v_and_b32_e32 v221, 0xffff0000, v216
	v_lshlrev_b32_e32 v216, 16, v217
	v_and_b32_e32 v217, 0xffff0000, v217
	v_pk_add_f32 v[128:129], v[128:129], v[216:217]
	v_pk_add_f32 v[126:127], v[126:127], v[220:221]
	v_lshlrev_b32_e32 v216, 16, v218
	v_and_b32_e32 v217, 0xffff0000, v218
	v_lshlrev_b32_e32 v218, 16, v219
	v_and_b32_e32 v219, 0xffff0000, v219
	v_pk_add_f32 v[218:219], v[124:125], v[218:219]
	v_pk_add_f32 v[124:125], v[122:123], v[216:217]
	v_cvt_pk_bf16_f32 v122, v126, v127
	v_lshl_add_u64 v[126:127], s[96:97], 0, v[208:209]
	v_cvt_pk_bf16_f32 v123, v128, v129
	v_cvt_pk_bf16_f32 v124, v124, v125
	v_cvt_pk_bf16_f32 v125, v218, v219
	v_lshl_add_u64 v[126:127], v[126:127], 0, v[176:177]
	global_store_dwordx4 v[126:127], v[122:125], off
	v_lshlrev_b32_e32 v128, 16, v122
	s_nop 0
	v_and_b32_e32 v122, 0xffff0000, v122
	v_mul_f32_e32 v122, v122, v122
	v_fmac_f32_e32 v122, v128, v128
	v_lshlrev_b32_e32 v128, 16, v123
	v_and_b32_e32 v123, 0xffff0000, v123
	v_mul_f32_e32 v123, v123, v123
	v_fmac_f32_e32 v123, v128, v128
	v_add_f32_e32 v122, v122, v123
	v_lshlrev_b32_e32 v123, 16, v124
	v_and_b32_e32 v124, 0xffff0000, v124
	v_mul_f32_e32 v124, v124, v124
	v_fmac_f32_e32 v124, v123, v123
	v_add_f32_e32 v122, v124, v122
	v_and_b32_e32 v124, 0xffff0000, v125
	v_lshlrev_b32_e32 v123, 16, v125
	v_mul_f32_e32 v124, v124, v124
	v_fmac_f32_e32 v124, v123, v123
	v_add_f32_e32 v128, v124, v122
	v_lshlrev_b32_e32 v122, 16, v154
	v_and_b32_e32 v123, 0xffff0000, v154
	v_lshlrev_b32_e32 v124, 16, v155
	v_and_b32_e32 v125, 0xffff0000, v155
	v_pk_add_f32 v[120:121], v[120:121], v[124:125]
	v_pk_add_f32 v[118:119], v[118:119], v[122:123]
	v_lshlrev_b32_e32 v122, 16, v156
	v_and_b32_e32 v123, 0xffff0000, v156
	v_lshlrev_b32_e32 v124, 16, v157
	v_and_b32_e32 v125, 0xffff0000, v157
	v_pk_add_f32 v[124:125], v[116:117], v[124:125]
	v_pk_add_f32 v[116:117], v[114:115], v[122:123]
	v_cvt_pk_bf16_f32 v114, v118, v119
	v_cvt_pk_bf16_f32 v115, v120, v121
	v_cvt_pk_bf16_f32 v116, v116, v117
	v_cvt_pk_bf16_f32 v117, v124, v125
	global_store_dwordx4 v[126:127], v[114:117], off offset:256
	v_lshlrev_b32_e32 v118, 16, v114
	s_nop 0
	v_and_b32_e32 v114, 0xffff0000, v114
	v_mul_f32_e32 v114, v114, v114
	v_fmac_f32_e32 v114, v118, v118
	v_lshlrev_b32_e32 v118, 16, v115
	v_and_b32_e32 v115, 0xffff0000, v115
	v_mul_f32_e32 v115, v115, v115
	v_add_f32_e32 v114, v114, v128
	v_fmac_f32_e32 v115, v118, v118
	v_add_f32_e32 v114, v115, v114
	v_lshlrev_b32_e32 v115, 16, v116
	v_and_b32_e32 v116, 0xffff0000, v116
	v_mul_f32_e32 v116, v116, v116
	v_fmac_f32_e32 v116, v115, v115
	v_add_f32_e32 v114, v116, v114
	v_and_b32_e32 v116, 0xffff0000, v117
	v_lshlrev_b32_e32 v115, 16, v117
	v_mul_f32_e32 v116, v116, v116
	v_fmac_f32_e32 v116, v115, v115
	v_add_f32_e32 v114, v116, v114
	ds_bpermute_b32 v115, v206, v114
	s_waitcnt lgkmcnt(0)
	v_add_f32_e32 v114, v114, v115
	ds_bpermute_b32 v115, v207, v114
	s_and_saveexec_b64 s[30:31], s[42:43]
	s_cbranch_execz .LBB0_123
	v_lshlrev_b64 v[116:117], 6, v[186:187]
	v_lshl_add_u64 v[116:117], s[58:59], 0, v[116:117]
	v_lshl_add_u64 v[116:117], s[36:37], 2, v[116:117]
	s_lshl_b32 s4, s67, 2
	v_lshl_add_u64 v[116:117], v[116:117], 0, s[4:5]
	s_waitcnt lgkmcnt(0)
	v_add_f32_e32 v114, v114, v115
	global_store_dword v[116:117], v114, off

.LBB0_159:
	s_add_i32 s23, s22, 2
	s_add_u32 s1, s36, 0x80
	s_addc_u32 s30, s37, 0
	s_add_i32 s33, 0, 0x10000
	v_add_u32_e32 v142, s33, v181
	ds_read_b128 v[130:133], v142
	ds_read_b128 v[134:137], v142 offset:1024
	ds_read_b128 v[138:141], v142 offset:2048
	ds_read_b128 v[142:145], v142 offset:3072
	s_cmp_eq_u32 s68, s22
	s_cselect_b32 s31, s27, s30
	s_cselect_b32 s30, s26, s1
	s_cselect_b32 s47, s29, s49
	s_cselect_b32 s46, s28, s48
	v_lshl_add_u64 v[160:161], s[36:37], 0, v[152:153]
	s_add_i32 m0, s21, 0xc000
	ds_read_b128 v[156:159], v183
	ds_read_b128 v[184:187], v183 offset:1024
	ds_read_b128 v[188:191], v183 offset:2048
	ds_read_b128 v[192:195], v183 offset:3072
	ds_read_b128 v[196:199], v183 offset:4096
	ds_read_b128 v[200:203], v183 offset:5120
	ds_read_b128 v[204:207], v183 offset:6144
	ds_read_b128 v[216:219], v183 offset:7168
	global_load_lds_dwordx4 v[160:161], off
	v_lshl_add_u64 v[160:161], s[36:37], 0, v[154:155]
	s_add_i32 m0, s21, 0xe000
	s_nop 0
	global_load_lds_dwordx4 v[160:161], off
	s_add_i32 s1, 0, 0x14000
	v_add_u32_e32 v160, s1, v181
	ds_read_b128 v[230:233], v160
	ds_read_b128 v[234:237], v160 offset:1024
	ds_read_b128 v[238:241], v160 offset:2048
	ds_read_b128 v[242:245], v160 offset:3072
	s_waitcnt vmcnt(8)
	s_waitcnt lgkmcnt(0)
	s_barrier
	s_setprio 1
	v_mfma_f32_16x16x32_bf16 v[126:129], v[130:133], v[156:159], v[126:129]
	v_mfma_f32_16x16x32_bf16 v[122:125], v[138:141], v[156:159], v[122:125]
	v_mfma_f32_16x16x32_bf16 v[110:113], v[130:133], v[188:191], v[110:113]
	v_mfma_f32_16x16x32_bf16 v[106:109], v[138:141], v[188:191], v[106:109]
	v_mfma_f32_16x16x32_bf16 v[94:97], v[130:133], v[196:199], v[94:97]
	v_mfma_f32_16x16x32_bf16 v[90:93], v[138:141], v[196:199], v[90:93]
	v_mfma_f32_16x16x32_bf16 v[78:81], v[130:133], v[204:207], v[78:81]
	v_mfma_f32_16x16x32_bf16 v[74:77], v[138:141], v[204:207], v[74:77]
	v_mfma_f32_16x16x32_bf16 v[126:129], v[134:137], v[184:187], v[126:129]
	v_mfma_f32_16x16x32_bf16 v[122:125], v[142:145], v[184:187], v[122:125]
	v_mfma_f32_16x16x32_bf16 v[110:113], v[134:137], v[192:195], v[110:113]
	v_mfma_f32_16x16x32_bf16 v[106:109], v[142:145], v[192:195], v[106:109]
	v_mfma_f32_16x16x32_bf16 v[94:97], v[134:137], v[200:203], v[94:97]
	v_mfma_f32_16x16x32_bf16 v[90:93], v[142:145], v[200:203], v[90:93]
	v_mfma_f32_16x16x32_bf16 v[78:81], v[134:137], v[216:219], v[78:81]
	v_mfma_f32_16x16x32_bf16 v[74:77], v[142:145], v[216:219], v[74:77]
	v_mfma_f32_16x16x32_bf16 v[118:121], v[230:233], v[156:159], v[118:121]
	v_mfma_f32_16x16x32_bf16 v[114:117], v[238:241], v[156:159], v[114:117]
	v_mfma_f32_16x16x32_bf16 v[102:105], v[230:233], v[188:191], v[102:105]
	v_mfma_f32_16x16x32_bf16 v[98:101], v[238:241], v[188:191], v[98:101]
	v_mfma_f32_16x16x32_bf16 v[86:89], v[230:233], v[196:199], v[86:89]
	v_mfma_f32_16x16x32_bf16 v[82:85], v[238:241], v[196:199], v[82:85]
	v_mfma_f32_16x16x32_bf16 v[70:73], v[230:233], v[204:207], v[70:73]
	v_mfma_f32_16x16x32_bf16 v[66:69], v[238:241], v[204:207], v[66:69]
	v_mfma_f32_16x16x32_bf16 v[118:121], v[234:237], v[184:187], v[118:121]
	v_mfma_f32_16x16x32_bf16 v[114:117], v[242:245], v[184:187], v[114:117]
	v_mfma_f32_16x16x32_bf16 v[102:105], v[234:237], v[192:195], v[102:105]
	v_mfma_f32_16x16x32_bf16 v[98:101], v[242:245], v[192:195], v[98:101]
	v_mfma_f32_16x16x32_bf16 v[86:89], v[234:237], v[200:203], v[86:89]
	v_mfma_f32_16x16x32_bf16 v[82:85], v[242:245], v[200:203], v[82:85]
	v_mfma_f32_16x16x32_bf16 v[70:73], v[234:237], v[216:219], v[70:73]
	v_mfma_f32_16x16x32_bf16 v[66:69], v[242:245], v[216:219], v[66:69]
	s_setprio 0
	s_barrier
	ds_read_b128 v[156:159], v183 offset:16384
	ds_read_b128 v[184:187], v183 offset:17408
	ds_read_b128 v[188:191], v183 offset:18432
	ds_read_b128 v[192:195], v183 offset:19456
	ds_read_b128 v[196:199], v183 offset:20480
	ds_read_b128 v[200:203], v183 offset:21504
	ds_read_b128 v[204:207], v183 offset:22528
	ds_read_b128 v[216:219], v183 offset:23552
	s_add_i32 s22, s33, s20
	v_lshl_add_u64 v[160:161], s[46:47], 0, v[0:1]
	s_mov_b32 m0, s22
	v_lshl_add_u64 v[176:177], s[46:47], 0, v[146:147]
	global_load_lds_dwordx4 v[160:161], off
	s_add_i32 m0, s22, 0x2000
	s_nop 0
	global_load_lds_dwordx4 v[176:177], off
	s_mov_b32 m0, s21
	v_lshl_add_u64 v[178:179], s[30:31], 0, v[150:151]
	global_load_lds_dwordx4 v[178:179], off
	v_lshl_add_u64 v[208:209], s[30:31], 0, v[148:149]
	s_mov_b32 m0, s34
	s_nop 0
	global_load_lds_dwordx4 v[208:209], off
	s_add_u32 s46, s46, s6
	s_addc_u32 s47, s47, 0
	s_add_i32 s1, s1, s20
	v_lshl_add_u64 v[220:221], s[46:47], 0, v[0:1]
	s_mov_b32 m0, s1
	v_lshl_add_u64 v[246:247], s[46:47], 0, v[146:147]
	global_load_lds_dwordx4 v[220:221], off
	s_add_i32 m0, s1, 0x2000
	s_nop 0
	global_load_lds_dwordx4 v[246:247], off
	s_waitcnt vmcnt(8)
	s_waitcnt lgkmcnt(0)
	s_barrier
	s_setprio 1
	v_mfma_f32_16x16x32_bf16 v[62:65], v[130:133], v[156:159], v[62:65]
	v_mfma_f32_16x16x32_bf16 v[58:61], v[138:141], v[156:159], v[58:61]
	v_mfma_f32_16x16x32_bf16 v[46:49], v[130:133], v[188:191], v[46:49]
	v_mfma_f32_16x16x32_bf16 v[42:45], v[138:141], v[188:191], v[42:45]
	v_mfma_f32_16x16x32_bf16 v[30:33], v[130:133], v[196:199], v[30:33]
	v_mfma_f32_16x16x32_bf16 v[26:29], v[138:141], v[196:199], v[26:29]
	v_mfma_f32_16x16x32_bf16 v[14:17], v[130:133], v[204:207], v[14:17]
	v_mfma_f32_16x16x32_bf16 v[10:13], v[138:141], v[204:207], v[10:13]
	v_mfma_f32_16x16x32_bf16 v[62:65], v[134:137], v[184:187], v[62:65]
	v_mfma_f32_16x16x32_bf16 v[58:61], v[142:145], v[184:187], v[58:61]
	v_mfma_f32_16x16x32_bf16 v[46:49], v[134:137], v[192:195], v[46:49]
	v_mfma_f32_16x16x32_bf16 v[42:45], v[142:145], v[192:195], v[42:45]
	v_mfma_f32_16x16x32_bf16 v[30:33], v[134:137], v[200:203], v[30:33]
	v_mfma_f32_16x16x32_bf16 v[26:29], v[142:145], v[200:203], v[26:29]
	v_mfma_f32_16x16x32_bf16 v[14:17], v[134:137], v[216:219], v[14:17]
	v_mfma_f32_16x16x32_bf16 v[10:13], v[142:145], v[216:219], v[10:13]
	v_mfma_f32_16x16x32_bf16 v[54:57], v[230:233], v[156:159], v[54:57]
	v_mfma_f32_16x16x32_bf16 v[50:53], v[238:241], v[156:159], v[50:53]
	v_mfma_f32_16x16x32_bf16 v[38:41], v[230:233], v[188:191], v[38:41]
	v_mfma_f32_16x16x32_bf16 v[34:37], v[238:241], v[188:191], v[34:37]
	v_mfma_f32_16x16x32_bf16 v[22:25], v[230:233], v[196:199], v[22:25]
	v_mfma_f32_16x16x32_bf16 v[18:21], v[238:241], v[196:199], v[18:21]
	v_mfma_f32_16x16x32_bf16 v[6:9], v[230:233], v[204:207], v[6:9]
	v_mfma_f32_16x16x32_bf16 v[2:5], v[238:241], v[204:207], v[2:5]
	v_mfma_f32_16x16x32_bf16 v[54:57], v[234:237], v[184:187], v[54:57]
	v_mfma_f32_16x16x32_bf16 v[50:53], v[242:245], v[184:187], v[50:53]
	v_mfma_f32_16x16x32_bf16 v[38:41], v[234:237], v[192:195], v[38:41]
	v_mfma_f32_16x16x32_bf16 v[34:37], v[242:245], v[192:195], v[34:37]
	v_mfma_f32_16x16x32_bf16 v[22:25], v[234:237], v[200:203], v[22:25]
	v_mfma_f32_16x16x32_bf16 v[18:21], v[242:245], v[200:203], v[18:21]
	v_mfma_f32_16x16x32_bf16 v[6:9], v[234:237], v[216:219], v[6:9]
	v_mfma_f32_16x16x32_bf16 v[2:5], v[242:245], v[216:219], v[2:5]
	s_setprio 0
	s_barrier
	s_add_i32 s1, 0, 0x18000
	v_add_u32_e32 v142, s1, v181
	ds_read_b128 v[130:133], v142
	ds_read_b128 v[134:137], v142 offset:1024
	ds_read_b128 v[138:141], v142 offset:2048
	ds_read_b128 v[142:145], v142 offset:3072
	s_add_u32 s30, s30, s6
	s_addc_u32 s31, s31, 0
	s_mov_b32 m0, s63
	v_lshl_add_u64 v[230:231], s[30:31], 0, v[150:151]
	ds_read_b128 v[156:159], v183 offset:32768
	ds_read_b128 v[184:187], v183 offset:33792
	ds_read_b128 v[188:191], v183 offset:34816
	ds_read_b128 v[192:195], v183 offset:35840
	ds_read_b128 v[196:199], v183 offset:36864
	ds_read_b128 v[200:203], v183 offset:37888
	ds_read_b128 v[204:207], v183 offset:38912
	ds_read_b128 v[216:219], v183 offset:39936
	global_load_lds_dwordx4 v[230:231], off
	v_lshl_add_u64 v[230:231], s[30:31], 0, v[148:149]
	s_mov_b32 m0, s64
	s_nop 0
	global_load_lds_dwordx4 v[230:231], off
	s_add_i32 s22, 0, 0x1c000
	v_add_u32_e32 v168, s22, v181
	ds_read_b128 v[230:233], v168
	ds_read_b128 v[234:237], v168 offset:1024
	ds_read_b128 v[238:241], v168 offset:2048
	ds_read_b128 v[242:245], v168 offset:3072
	s_waitcnt vmcnt(8)
	s_waitcnt lgkmcnt(0)
	s_barrier
	s_setprio 1
	v_mfma_f32_16x16x32_bf16 v[126:129], v[130:133], v[156:159], v[126:129]
	v_mfma_f32_16x16x32_bf16 v[122:125], v[138:141], v[156:159], v[122:125]
	v_mfma_f32_16x16x32_bf16 v[110:113], v[130:133], v[188:191], v[110:113]
	v_mfma_f32_16x16x32_bf16 v[106:109], v[138:141], v[188:191], v[106:109]
	v_mfma_f32_16x16x32_bf16 v[94:97], v[130:133], v[196:199], v[94:97]
	v_mfma_f32_16x16x32_bf16 v[90:93], v[138:141], v[196:199], v[90:93]
	v_mfma_f32_16x16x32_bf16 v[78:81], v[130:133], v[204:207], v[78:81]
	v_mfma_f32_16x16x32_bf16 v[74:77], v[138:141], v[204:207], v[74:77]
	v_mfma_f32_16x16x32_bf16 v[126:129], v[134:137], v[184:187], v[126:129]
	v_mfma_f32_16x16x32_bf16 v[122:125], v[142:145], v[184:187], v[122:125]
	v_mfma_f32_16x16x32_bf16 v[110:113], v[134:137], v[192:195], v[110:113]
	v_mfma_f32_16x16x32_bf16 v[106:109], v[142:145], v[192:195], v[106:109]
	v_mfma_f32_16x16x32_bf16 v[94:97], v[134:137], v[200:203], v[94:97]
	v_mfma_f32_16x16x32_bf16 v[90:93], v[142:145], v[200:203], v[90:93]
	v_mfma_f32_16x16x32_bf16 v[78:81], v[134:137], v[216:219], v[78:81]
	v_mfma_f32_16x16x32_bf16 v[74:77], v[142:145], v[216:219], v[74:77]
	v_mfma_f32_16x16x32_bf16 v[118:121], v[230:233], v[156:159], v[118:121]
	v_mfma_f32_16x16x32_bf16 v[114:117], v[238:241], v[156:159], v[114:117]
	v_mfma_f32_16x16x32_bf16 v[102:105], v[230:233], v[188:191], v[102:105]
	v_mfma_f32_16x16x32_bf16 v[98:101], v[238:241], v[188:191], v[98:101]
	v_mfma_f32_16x16x32_bf16 v[86:89], v[230:233], v[196:199], v[86:89]
	v_mfma_f32_16x16x32_bf16 v[82:85], v[238:241], v[196:199], v[82:85]
	v_mfma_f32_16x16x32_bf16 v[70:73], v[230:233], v[204:207], v[70:73]
	v_mfma_f32_16x16x32_bf16 v[66:69], v[238:241], v[204:207], v[66:69]
	v_mfma_f32_16x16x32_bf16 v[118:121], v[234:237], v[184:187], v[118:121]
	v_mfma_f32_16x16x32_bf16 v[114:117], v[242:245], v[184:187], v[114:117]
	v_mfma_f32_16x16x32_bf16 v[102:105], v[234:237], v[192:195], v[102:105]
	v_mfma_f32_16x16x32_bf16 v[98:101], v[242:245], v[192:195], v[98:101]
	v_mfma_f32_16x16x32_bf16 v[86:89], v[234:237], v[200:203], v[86:89]
	v_mfma_f32_16x16x32_bf16 v[82:85], v[242:245], v[200:203], v[82:85]
	v_mfma_f32_16x16x32_bf16 v[70:73], v[234:237], v[216:219], v[70:73]
	v_mfma_f32_16x16x32_bf16 v[66:69], v[242:245], v[216:219], v[66:69]
	s_setprio 0
	s_barrier
	ds_read_b128 v[156:159], v183 offset:49152
	ds_read_b128 v[184:187], v183 offset:50176
	ds_read_b128 v[188:191], v183 offset:51200
	ds_read_b128 v[192:195], v183 offset:52224
	ds_read_b128 v[196:199], v183 offset:53248
	ds_read_b128 v[200:203], v183 offset:54272
	ds_read_b128 v[204:207], v183 offset:55296
	ds_read_b128 v[216:219], v183 offset:56320
	s_add_i32 s1, s1, s20
	v_lshl_add_u64 v[160:161], v[160:161], 0, s[12:13]
	s_mov_b32 m0, s1
	s_nop 0
	global_load_lds_dwordx4 v[160:161], off
	v_lshl_add_u64 v[160:161], v[176:177], 0, s[12:13]
	s_add_i32 m0, s1, 0x2000
	s_nop 0
	global_load_lds_dwordx4 v[160:161], off
	s_mov_b32 m0, s65
	v_lshl_add_u64 v[160:161], v[178:179], 0, s[12:13]
	global_load_lds_dwordx4 v[160:161], off
	v_lshl_add_u64 v[160:161], v[208:209], 0, s[12:13]
	s_mov_b32 m0, s66
	s_nop 0
	global_load_lds_dwordx4 v[160:161], off
	s_add_i32 s1, s22, s20
	v_lshl_add_u64 v[160:161], v[220:221], 0, s[12:13]
	s_mov_b32 m0, s1
	s_nop 0
	global_load_lds_dwordx4 v[160:161], off
	v_lshl_add_u64 v[160:161], v[246:247], 0, s[12:13]
	s_add_i32 m0, s1, 0x2000
	s_nop 0
	global_load_lds_dwordx4 v[160:161], off
	s_waitcnt vmcnt(8)
	s_waitcnt lgkmcnt(0)
	s_barrier
	s_setprio 1
	v_mfma_f32_16x16x32_bf16 v[62:65], v[130:133], v[156:159], v[62:65]
	v_mfma_f32_16x16x32_bf16 v[58:61], v[138:141], v[156:159], v[58:61]
	v_mfma_f32_16x16x32_bf16 v[46:49], v[130:133], v[188:191], v[46:49]
	v_mfma_f32_16x16x32_bf16 v[42:45], v[138:141], v[188:191], v[42:45]
	v_mfma_f32_16x16x32_bf16 v[30:33], v[130:133], v[196:199], v[30:33]
	v_mfma_f32_16x16x32_bf16 v[26:29], v[138:141], v[196:199], v[26:29]
	v_mfma_f32_16x16x32_bf16 v[14:17], v[130:133], v[204:207], v[14:17]
	v_mfma_f32_16x16x32_bf16 v[10:13], v[138:141], v[204:207], v[10:13]
	v_mfma_f32_16x16x32_bf16 v[62:65], v[134:137], v[184:187], v[62:65]
	v_mfma_f32_16x16x32_bf16 v[58:61], v[142:145], v[184:187], v[58:61]
	v_mfma_f32_16x16x32_bf16 v[46:49], v[134:137], v[192:195], v[46:49]
	v_mfma_f32_16x16x32_bf16 v[42:45], v[142:145], v[192:195], v[42:45]
	v_mfma_f32_16x16x32_bf16 v[30:33], v[134:137], v[200:203], v[30:33]
	v_mfma_f32_16x16x32_bf16 v[26:29], v[142:145], v[200:203], v[26:29]
	v_mfma_f32_16x16x32_bf16 v[14:17], v[134:137], v[216:219], v[14:17]
	v_mfma_f32_16x16x32_bf16 v[10:13], v[142:145], v[216:219], v[10:13]
	v_mfma_f32_16x16x32_bf16 v[54:57], v[230:233], v[156:159], v[54:57]
	v_mfma_f32_16x16x32_bf16 v[50:53], v[238:241], v[156:159], v[50:53]
	v_mfma_f32_16x16x32_bf16 v[38:41], v[230:233], v[188:191], v[38:41]
	v_mfma_f32_16x16x32_bf16 v[34:37], v[238:241], v[188:191], v[34:37]
	v_mfma_f32_16x16x32_bf16 v[22:25], v[230:233], v[196:199], v[22:25]
	v_mfma_f32_16x16x32_bf16 v[18:21], v[238:241], v[196:199], v[18:21]
	v_mfma_f32_16x16x32_bf16 v[6:9], v[230:233], v[204:207], v[6:9]
	v_mfma_f32_16x16x32_bf16 v[2:5], v[238:241], v[204:207], v[2:5]
	v_mfma_f32_16x16x32_bf16 v[54:57], v[234:237], v[184:187], v[54:57]
	v_mfma_f32_16x16x32_bf16 v[50:53], v[242:245], v[184:187], v[50:53]
	v_mfma_f32_16x16x32_bf16 v[38:41], v[234:237], v[192:195], v[38:41]
	v_mfma_f32_16x16x32_bf16 v[34:37], v[242:245], v[192:195], v[34:37]
	v_mfma_f32_16x16x32_bf16 v[22:25], v[234:237], v[200:203], v[22:25]
	v_mfma_f32_16x16x32_bf16 v[18:21], v[242:245], v[200:203], v[18:21]
	v_mfma_f32_16x16x32_bf16 v[6:9], v[234:237], v[216:219], v[6:9]
	v_mfma_f32_16x16x32_bf16 v[2:5], v[242:245], v[216:219], v[2:5]
	s_setprio 0
	s_add_u32 s36, s36, 0x100
	s_addc_u32 s37, s37, 0
	s_add_u32 s48, s48, 0x100
	s_addc_u32 s49, s49, 0
	s_cmp_ge_u32 s23, s0
	s_mov_b32 s22, s23
	s_barrier
	s_cbranch_scc0 .LBB0_159
	v_readlane_b32 s22, v254, 31
	v_readlane_b32 s23, v254, 32
	s_load_dwordx2 s[22:23], s[22:23], 0x0
	v_lshl_add_u32 v158, s71, 8, v180
	v_lshl_or_b32 v156, s4, 8, v182
	v_ashrrev_i32_e32 v157, 31, v156
	v_ashrrev_i32_e32 v159, 31, v158
	s_waitcnt lgkmcnt(0)
	v_lshl_add_u64 v[160:161], v[156:157], 2, s[22:23]
	v_lshlrev_b64 v[130:131], 12, v[158:159]
	v_lshl_add_u64 v[130:131], v[160:161], 0, v[130:131]
	global_load_dwordx4 v[186:189], v[130:131], off
	global_load_dwordx4 v[190:193], v[130:131], off offset:16
	global_load_dwordx4 v[194:197], v[130:131], off offset:512
	global_load_dwordx4 v[198:201], v[130:131], off offset:528
	v_or_b32_e32 v178, 16, v158
	v_ashrrev_i32_e32 v179, 31, v178
	v_lshlrev_b64 v[130:131], 12, v[178:179]
	v_lshl_add_u64 v[134:135], v[160:161], 0, v[130:131]
	global_load_dwordx4 v[138:141], v[134:135], off offset:16
	global_load_dwordx4 v[142:145], v[134:135], off
	global_load_dwordx4 v[130:133], v[134:135], off offset:528
	s_nop 0
	global_load_dwordx4 v[134:137], v[134:135], off offset:512
	v_and_b32_e32 v169, 64, v212
	v_xor_b32_e32 v168, 16, v212
	v_add_u32_e32 v169, 64, v169
	v_xor_b32_e32 v176, 32, v212
	v_cmp_lt_i32_e32 vcc, v168, v169
	s_lshl_b32 s36, s4, 2
	s_ashr_i32 s37, s36, 31
	v_cndmask_b32_e32 v168, v212, v168, vcc
	v_cmp_lt_i32_e32 vcc, v176, v169
	v_lshlrev_b32_e32 v184, 2, v168
	s_cmpk_gt_u32 s16, 0xff
	s_cbranch_scc1 .Lrs_i4_post
	s_barrier
.Lrs_i4_post:
	s_waitcnt vmcnt(0)
	v_pk_add_f32 v[128:129], v[128:129], v[188:189]
	v_pk_add_f32 v[126:127], v[126:127], v[186:187]
	v_cndmask_b32_e32 v169, v212, v176, vcc
	v_pk_add_f32 v[122:123], v[122:123], v[190:191]
	v_pk_add_f32 v[176:177], v[120:121], v[196:197]
	v_pk_add_f32 v[116:117], v[116:117], v[200:201]
	v_pk_add_f32 v[114:115], v[114:115], v[198:199]
	v_cvt_pk_bf16_f32 v120, v126, v127
	v_cvt_pk_bf16_f32 v121, v128, v129
	v_pk_add_f32 v[124:125], v[124:125], v[192:193]
	v_pk_add_f32 v[118:119], v[118:119], v[194:195]
	v_cvt_pk_bf16_f32 v122, v122, v123
	v_cvt_pk_bf16_f32 v126, v114, v115
	v_cvt_pk_bf16_f32 v127, v116, v117
	v_and_b32_e32 v115, 0xffff0000, v120
	v_and_b32_e32 v117, 0xffff0000, v121
	v_cvt_pk_bf16_f32 v123, v124, v125
	v_cvt_pk_bf16_f32 v124, v118, v119
	v_lshlrev_b32_e32 v114, 16, v120
	v_lshlrev_b32_e32 v116, 16, v121
	v_and_b32_e32 v119, 0xffff0000, v122
	v_mul_f32_e32 v115, v115, v115
	v_mul_f32_e32 v117, v117, v117
	v_lshlrev_b32_e32 v118, 16, v122
	v_and_b32_e32 v129, 0xffff0000, v123
	v_mul_f32_e32 v119, v119, v119
	v_fmac_f32_e32 v115, v114, v114
	v_fmac_f32_e32 v117, v116, v116
	v_cvt_pk_bf16_f32 v125, v176, v177
	v_lshlrev_b32_e32 v128, 16, v123
	v_and_b32_e32 v176, 0xffff0000, v124
	v_mul_f32_e32 v129, v129, v129
	v_fmac_f32_e32 v119, v118, v118
	v_add_f32_e32 v114, v115, v117
	v_lshlrev_b32_e32 v168, 16, v124
	v_and_b32_e32 v185, 0xffff0000, v125
	v_mul_f32_e32 v176, v176, v176
	v_fmac_f32_e32 v129, v128, v128
	v_add_f32_e32 v114, v114, v119
	v_lshlrev_b32_e32 v177, 16, v125
	v_and_b32_e32 v187, 0xffff0000, v126
	v_mul_f32_e32 v185, v185, v185
	v_fmac_f32_e32 v176, v168, v168
	v_add_f32_e32 v114, v129, v114
	v_lshlrev_b32_e32 v186, 16, v126
	v_and_b32_e32 v189, 0xffff0000, v127
	v_mul_f32_e32 v187, v187, v187
	v_fmac_f32_e32 v185, v177, v177
	v_add_f32_e32 v114, v176, v114
	v_lshlrev_b32_e32 v188, 16, v127
	v_mul_f32_e32 v189, v189, v189
	v_fmac_f32_e32 v187, v186, v186
	v_add_f32_e32 v114, v185, v114
	v_add_f32_e32 v114, v187, v114
	v_fmac_f32_e32 v189, v188, v188
	v_add_f32_e32 v114, v189, v114
	ds_bpermute_b32 v115, v184, v114
	v_lshlrev_b32_e32 v118, 2, v169
	v_lshlrev_b64 v[116:117], 11, v[158:159]
	v_lshl_add_u64 v[116:117], s[96:97], 0, v[116:117]
	v_lshl_add_u64 v[116:117], v[156:157], 1, v[116:117]
	s_waitcnt lgkmcnt(0)
	v_add_f32_e32 v114, v114, v115
	ds_bpermute_b32 v115, v118, v114
	global_store_dwordx4 v[116:117], v[120:123], off
	global_store_dwordx4 v[116:117], v[124:127], off offset:256
	s_and_saveexec_b64 s[30:31], s[42:43]
	s_cbranch_execz .LBB0_162
	v_lshlrev_b64 v[116:117], 6, v[158:159]
	v_lshl_add_u64 v[116:117], s[58:59], 0, v[116:117]
	v_lshl_add_u64 v[116:117], s[36:37], 2, v[116:117]
	s_lshl_b32 s4, s67, 2
	v_lshl_add_u64 v[116:117], v[116:117], 0, s[4:5]
	s_waitcnt lgkmcnt(0)
	v_add_f32_e32 v114, v114, v115
	global_store_dword v[116:117], v114, off

.LBB0_289:
	s_add_u32 s1, s42, 0xfffc0080
	s_addc_u32 s22, s43, -1
	s_add_i32 s23, 0, 0x10000
	v_add_u32_e32 v142, s23, v217
	ds_read_b128 v[130:133], v142
	ds_read_b128 v[134:137], v142 offset:1024
	ds_read_b128 v[138:141], v142 offset:2048
	ds_read_b128 v[142:145], v142 offset:3072
	s_cmp_eq_u32 s54, 12
	s_cselect_b32 s45, s27, s22
	s_cselect_b32 s44, s50, s1
	s_cselect_b32 s31, s7, s53
	s_cselect_b32 s30, s51, s52
	v_lshl_add_u64 v[176:177], s[42:43], 0, v[190:191]
	s_add_i32 m0, s16, 0xc000
	ds_read_b128 v[146:149], v219
	ds_read_b128 v[150:153], v219 offset:1024
	ds_read_b128 v[154:157], v219 offset:2048
	ds_read_b128 v[158:161], v219 offset:3072
	ds_read_b128 v[194:197], v219 offset:4096
	ds_read_b128 v[198:201], v219 offset:5120
	ds_read_b128 v[202:205], v219 offset:6144
	ds_read_b128 v[206:209], v219 offset:7168
	global_load_lds_dwordx4 v[176:177], off
	v_lshl_add_u64 v[176:177], s[42:43], 0, v[192:193]
	s_add_i32 m0, s16, 0xe000
	s_nop 0
	global_load_lds_dwordx4 v[176:177], off
	s_add_i32 s1, 0, 0x14000
	v_add_u32_e32 v168, s1, v217
	ds_read_b128 v[230:233], v168
	ds_read_b128 v[234:237], v168 offset:1024
	ds_read_b128 v[238:241], v168 offset:2048
	ds_read_b128 v[242:245], v168 offset:3072
	s_waitcnt vmcnt(8)
	s_waitcnt lgkmcnt(0)
	s_barrier
	s_setprio 1
	v_mfma_f32_16x16x32_bf16 v[126:129], v[130:133], v[146:149], v[126:129]
	v_mfma_f32_16x16x32_bf16 v[122:125], v[138:141], v[146:149], v[122:125]
	v_mfma_f32_16x16x32_bf16 v[118:121], v[130:133], v[154:157], v[118:121]
	v_mfma_f32_16x16x32_bf16 v[110:113], v[138:141], v[154:157], v[110:113]
	v_mfma_f32_16x16x32_bf16 v[102:105], v[130:133], v[194:197], v[102:105]
	v_mfma_f32_16x16x32_bf16 v[94:97], v[138:141], v[194:197], v[94:97]
	v_mfma_f32_16x16x32_bf16 v[86:89], v[130:133], v[202:205], v[86:89]
	v_mfma_f32_16x16x32_bf16 v[78:81], v[138:141], v[202:205], v[78:81]
	v_mfma_f32_16x16x32_bf16 v[126:129], v[134:137], v[150:153], v[126:129]
	v_mfma_f32_16x16x32_bf16 v[122:125], v[142:145], v[150:153], v[122:125]
	v_mfma_f32_16x16x32_bf16 v[118:121], v[134:137], v[158:161], v[118:121]
	v_mfma_f32_16x16x32_bf16 v[110:113], v[142:145], v[158:161], v[110:113]
	v_mfma_f32_16x16x32_bf16 v[102:105], v[134:137], v[198:201], v[102:105]
	v_mfma_f32_16x16x32_bf16 v[94:97], v[142:145], v[198:201], v[94:97]
	v_mfma_f32_16x16x32_bf16 v[86:89], v[134:137], v[206:209], v[86:89]
	v_mfma_f32_16x16x32_bf16 v[78:81], v[142:145], v[206:209], v[78:81]
	v_mfma_f32_16x16x32_bf16 v[114:117], v[230:233], v[146:149], v[114:117]
	v_mfma_f32_16x16x32_bf16 v[106:109], v[238:241], v[146:149], v[106:109]
	v_mfma_f32_16x16x32_bf16 v[98:101], v[230:233], v[154:157], v[98:101]
	v_mfma_f32_16x16x32_bf16 v[90:93], v[238:241], v[154:157], v[90:93]
	v_mfma_f32_16x16x32_bf16 v[82:85], v[230:233], v[194:197], v[82:85]
	v_mfma_f32_16x16x32_bf16 v[74:77], v[238:241], v[194:197], v[74:77]
	v_mfma_f32_16x16x32_bf16 v[70:73], v[230:233], v[202:205], v[70:73]
	v_mfma_f32_16x16x32_bf16 v[66:69], v[238:241], v[202:205], v[66:69]
	v_mfma_f32_16x16x32_bf16 v[114:117], v[234:237], v[150:153], v[114:117]
	v_mfma_f32_16x16x32_bf16 v[106:109], v[242:245], v[150:153], v[106:109]
	v_mfma_f32_16x16x32_bf16 v[98:101], v[234:237], v[158:161], v[98:101]
	v_mfma_f32_16x16x32_bf16 v[90:93], v[242:245], v[158:161], v[90:93]
	v_mfma_f32_16x16x32_bf16 v[82:85], v[234:237], v[198:201], v[82:85]
	v_mfma_f32_16x16x32_bf16 v[74:77], v[242:245], v[198:201], v[74:77]
	v_mfma_f32_16x16x32_bf16 v[70:73], v[234:237], v[206:209], v[70:73]
	v_mfma_f32_16x16x32_bf16 v[66:69], v[242:245], v[206:209], v[66:69]
	s_setprio 0
	s_barrier
	ds_read_b128 v[146:149], v219 offset:16384
	ds_read_b128 v[150:153], v219 offset:17408
	ds_read_b128 v[154:157], v219 offset:18432
	ds_read_b128 v[158:161], v219 offset:19456
	ds_read_b128 v[194:197], v219 offset:20480
	ds_read_b128 v[198:201], v219 offset:21504
	ds_read_b128 v[202:205], v219 offset:22528
	ds_read_b128 v[206:209], v219 offset:23552
	s_add_i32 s22, s23, s4
	v_lshl_add_u64 v[176:177], s[30:31], 0, v[0:1]
	s_mov_b32 m0, s22
	s_nop 0
	global_load_lds_dwordx4 v[176:177], off
	v_lshl_add_u64 v[220:221], s[30:31], 0, v[178:179]
	s_add_i32 m0, s22, 0x2000
	s_nop 0
	global_load_lds_dwordx4 v[220:221], off
	s_mov_b32 m0, s16
	v_lshl_add_u64 v[246:247], s[44:45], 0, v[182:183]
	global_load_lds_dwordx4 v[246:247], off
	v_lshl_add_u64 v[248:249], s[44:45], 0, v[180:181]
	s_mov_b32 m0, s17
	s_nop 0
	global_load_lds_dwordx4 v[248:249], off
	s_add_u32 s22, s30, 0x40000
	s_addc_u32 s23, s31, 0
	s_add_i32 s1, s1, s4
	s_mov_b32 m0, s1
	s_nop 0
	global_load_lds_dwordx4 v0, s[22:23]
	s_add_i32 m0, s1, 0x2000
	s_nop 0
	global_load_lds_dwordx4 v178, s[22:23]
	s_waitcnt vmcnt(8)
	s_waitcnt lgkmcnt(0)
	s_barrier
	s_setprio 1
	v_mfma_f32_16x16x32_bf16 v[62:65], v[130:133], v[146:149], v[62:65]
	v_mfma_f32_16x16x32_bf16 v[58:61], v[138:141], v[146:149], v[58:61]
	v_mfma_f32_16x16x32_bf16 v[54:57], v[130:133], v[154:157], v[54:57]
	v_mfma_f32_16x16x32_bf16 v[46:49], v[138:141], v[154:157], v[46:49]
	v_mfma_f32_16x16x32_bf16 v[38:41], v[130:133], v[194:197], v[38:41]
	v_mfma_f32_16x16x32_bf16 v[30:33], v[138:141], v[194:197], v[30:33]
	v_mfma_f32_16x16x32_bf16 v[22:25], v[130:133], v[202:205], v[22:25]
	v_mfma_f32_16x16x32_bf16 v[14:17], v[138:141], v[202:205], v[14:17]
	v_mfma_f32_16x16x32_bf16 v[62:65], v[134:137], v[150:153], v[62:65]
	v_mfma_f32_16x16x32_bf16 v[58:61], v[142:145], v[150:153], v[58:61]
	v_mfma_f32_16x16x32_bf16 v[54:57], v[134:137], v[158:161], v[54:57]
	v_mfma_f32_16x16x32_bf16 v[46:49], v[142:145], v[158:161], v[46:49]
	v_mfma_f32_16x16x32_bf16 v[38:41], v[134:137], v[198:201], v[38:41]
	v_mfma_f32_16x16x32_bf16 v[30:33], v[142:145], v[198:201], v[30:33]
	v_mfma_f32_16x16x32_bf16 v[22:25], v[134:137], v[206:209], v[22:25]
	v_mfma_f32_16x16x32_bf16 v[14:17], v[142:145], v[206:209], v[14:17]
	v_mfma_f32_16x16x32_bf16 v[50:53], v[230:233], v[146:149], v[50:53]
	v_mfma_f32_16x16x32_bf16 v[42:45], v[238:241], v[146:149], v[42:45]
	v_mfma_f32_16x16x32_bf16 v[34:37], v[230:233], v[154:157], v[34:37]
	v_mfma_f32_16x16x32_bf16 v[26:29], v[238:241], v[154:157], v[26:29]
	v_mfma_f32_16x16x32_bf16 v[18:21], v[230:233], v[194:197], v[18:21]
	v_mfma_f32_16x16x32_bf16 v[10:13], v[238:241], v[194:197], v[10:13]
	v_mfma_f32_16x16x32_bf16 v[6:9], v[230:233], v[202:205], v[6:9]
	v_mfma_f32_16x16x32_bf16 v[2:5], v[238:241], v[202:205], v[2:5]
	v_mfma_f32_16x16x32_bf16 v[50:53], v[234:237], v[150:153], v[50:53]
	v_mfma_f32_16x16x32_bf16 v[42:45], v[242:245], v[150:153], v[42:45]
	v_mfma_f32_16x16x32_bf16 v[34:37], v[234:237], v[158:161], v[34:37]
	v_mfma_f32_16x16x32_bf16 v[26:29], v[242:245], v[158:161], v[26:29]
	v_mfma_f32_16x16x32_bf16 v[18:21], v[234:237], v[198:201], v[18:21]
	v_mfma_f32_16x16x32_bf16 v[10:13], v[242:245], v[198:201], v[10:13]
	v_mfma_f32_16x16x32_bf16 v[6:9], v[234:237], v[206:209], v[6:9]
	v_mfma_f32_16x16x32_bf16 v[2:5], v[242:245], v[206:209], v[2:5]
	s_setprio 0
	s_barrier
	s_add_i32 s1, 0, 0x18000
	v_add_u32_e32 v142, s1, v217
	ds_read_b128 v[130:133], v142
	ds_read_b128 v[134:137], v142 offset:1024
	ds_read_b128 v[138:141], v142 offset:2048
	ds_read_b128 v[142:145], v142 offset:3072
	s_add_u32 s22, s44, 0x40000
	s_addc_u32 s23, s45, 0
	s_mov_b32 m0, s20
	v_lshl_add_u64 v[230:231], s[22:23], 0, v[182:183]
	ds_read_b128 v[146:149], v219 offset:32768
	ds_read_b128 v[150:153], v219 offset:33792
	ds_read_b128 v[154:157], v219 offset:34816
	ds_read_b128 v[158:161], v219 offset:35840
	ds_read_b128 v[194:197], v219 offset:36864
	ds_read_b128 v[198:201], v219 offset:37888
	ds_read_b128 v[202:205], v219 offset:38912
	ds_read_b128 v[206:209], v219 offset:39936
	global_load_lds_dwordx4 v[230:231], off
	v_lshl_add_u64 v[230:231], s[22:23], 0, v[180:181]
	s_mov_b32 m0, s21
	s_nop 0
	global_load_lds_dwordx4 v[230:231], off
	s_add_i32 s33, 0, 0x1c000
	v_add_u32_e32 v168, s33, v217
	ds_read_b128 v[230:233], v168
	ds_read_b128 v[234:237], v168 offset:1024
	ds_read_b128 v[238:241], v168 offset:2048
	ds_read_b128 v[242:245], v168 offset:3072
	s_waitcnt vmcnt(8)
	s_waitcnt lgkmcnt(0)
	s_barrier
	s_setprio 1
	v_mfma_f32_16x16x32_bf16 v[126:129], v[130:133], v[146:149], v[126:129]
	v_mfma_f32_16x16x32_bf16 v[122:125], v[138:141], v[146:149], v[122:125]
	v_mfma_f32_16x16x32_bf16 v[118:121], v[130:133], v[154:157], v[118:121]
	v_mfma_f32_16x16x32_bf16 v[110:113], v[138:141], v[154:157], v[110:113]
	v_mfma_f32_16x16x32_bf16 v[102:105], v[130:133], v[194:197], v[102:105]
	v_mfma_f32_16x16x32_bf16 v[94:97], v[138:141], v[194:197], v[94:97]
	v_mfma_f32_16x16x32_bf16 v[86:89], v[130:133], v[202:205], v[86:89]
	v_mfma_f32_16x16x32_bf16 v[78:81], v[138:141], v[202:205], v[78:81]
	v_mfma_f32_16x16x32_bf16 v[126:129], v[134:137], v[150:153], v[126:129]
	v_mfma_f32_16x16x32_bf16 v[122:125], v[142:145], v[150:153], v[122:125]
	v_mfma_f32_16x16x32_bf16 v[118:121], v[134:137], v[158:161], v[118:121]
	v_mfma_f32_16x16x32_bf16 v[110:113], v[142:145], v[158:161], v[110:113]
	v_mfma_f32_16x16x32_bf16 v[102:105], v[134:137], v[198:201], v[102:105]
	v_mfma_f32_16x16x32_bf16 v[94:97], v[142:145], v[198:201], v[94:97]
	v_mfma_f32_16x16x32_bf16 v[86:89], v[134:137], v[206:209], v[86:89]
	v_mfma_f32_16x16x32_bf16 v[78:81], v[142:145], v[206:209], v[78:81]
	v_mfma_f32_16x16x32_bf16 v[114:117], v[230:233], v[146:149], v[114:117]
	v_mfma_f32_16x16x32_bf16 v[106:109], v[238:241], v[146:149], v[106:109]
	v_mfma_f32_16x16x32_bf16 v[98:101], v[230:233], v[154:157], v[98:101]
	v_mfma_f32_16x16x32_bf16 v[90:93], v[238:241], v[154:157], v[90:93]
	v_mfma_f32_16x16x32_bf16 v[82:85], v[230:233], v[194:197], v[82:85]
	v_mfma_f32_16x16x32_bf16 v[74:77], v[238:241], v[194:197], v[74:77]
	v_mfma_f32_16x16x32_bf16 v[70:73], v[230:233], v[202:205], v[70:73]
	v_mfma_f32_16x16x32_bf16 v[66:69], v[238:241], v[202:205], v[66:69]
	v_mfma_f32_16x16x32_bf16 v[114:117], v[234:237], v[150:153], v[114:117]
	v_mfma_f32_16x16x32_bf16 v[106:109], v[242:245], v[150:153], v[106:109]
	v_mfma_f32_16x16x32_bf16 v[98:101], v[234:237], v[158:161], v[98:101]
	v_mfma_f32_16x16x32_bf16 v[90:93], v[242:245], v[158:161], v[90:93]
	v_mfma_f32_16x16x32_bf16 v[82:85], v[234:237], v[198:201], v[82:85]
	v_mfma_f32_16x16x32_bf16 v[74:77], v[242:245], v[198:201], v[74:77]
	v_mfma_f32_16x16x32_bf16 v[70:73], v[234:237], v[206:209], v[70:73]
	v_mfma_f32_16x16x32_bf16 v[66:69], v[242:245], v[206:209], v[66:69]
	s_setprio 0
	s_barrier
	ds_read_b128 v[146:149], v219 offset:49152
	ds_read_b128 v[150:153], v219 offset:50176
	ds_read_b128 v[154:157], v219 offset:51200
	ds_read_b128 v[158:161], v219 offset:52224
	ds_read_b128 v[194:197], v219 offset:53248
	ds_read_b128 v[198:201], v219 offset:54272
	ds_read_b128 v[202:205], v219 offset:55296
	ds_read_b128 v[206:209], v219 offset:56320
	s_add_i32 s1, s1, s4
	v_lshl_add_u64 v[176:177], v[176:177], 0, s[12:13]
	s_mov_b32 m0, s1
	s_nop 0
	global_load_lds_dwordx4 v[176:177], off
	v_lshl_add_u64 v[176:177], v[220:221], 0, s[12:13]
	s_add_i32 m0, s1, 0x2000
	s_nop 0
	global_load_lds_dwordx4 v[176:177], off
	s_mov_b32 m0, s34
	v_lshl_add_u64 v[176:177], v[246:247], 0, s[12:13]
	global_load_lds_dwordx4 v[176:177], off
	v_lshl_add_u64 v[176:177], v[248:249], 0, s[12:13]
	s_mov_b32 m0, s46
	s_nop 0
	global_load_lds_dwordx4 v[176:177], off
	s_add_u32 s22, s30, 0x40080
	s_addc_u32 s23, s31, 0
	s_add_i32 s1, s33, s4
	s_mov_b32 m0, s1
	s_nop 0
	global_load_lds_dwordx4 v0, s[22:23]
	s_add_i32 m0, s1, 0x2000
	s_nop 0
	global_load_lds_dwordx4 v178, s[22:23]
	s_waitcnt vmcnt(8)
	s_waitcnt lgkmcnt(0)
	s_barrier
	s_setprio 1
	v_mfma_f32_16x16x32_bf16 v[62:65], v[130:133], v[146:149], v[62:65]
	v_mfma_f32_16x16x32_bf16 v[58:61], v[138:141], v[146:149], v[58:61]
	v_mfma_f32_16x16x32_bf16 v[54:57], v[130:133], v[154:157], v[54:57]
	v_mfma_f32_16x16x32_bf16 v[46:49], v[138:141], v[154:157], v[46:49]
	v_mfma_f32_16x16x32_bf16 v[38:41], v[130:133], v[194:197], v[38:41]
	v_mfma_f32_16x16x32_bf16 v[30:33], v[138:141], v[194:197], v[30:33]
	v_mfma_f32_16x16x32_bf16 v[22:25], v[130:133], v[202:205], v[22:25]
	v_mfma_f32_16x16x32_bf16 v[14:17], v[138:141], v[202:205], v[14:17]
	v_mfma_f32_16x16x32_bf16 v[62:65], v[134:137], v[150:153], v[62:65]
	v_mfma_f32_16x16x32_bf16 v[58:61], v[142:145], v[150:153], v[58:61]
	v_mfma_f32_16x16x32_bf16 v[54:57], v[134:137], v[158:161], v[54:57]
	v_mfma_f32_16x16x32_bf16 v[46:49], v[142:145], v[158:161], v[46:49]
	v_mfma_f32_16x16x32_bf16 v[38:41], v[134:137], v[198:201], v[38:41]
	v_mfma_f32_16x16x32_bf16 v[30:33], v[142:145], v[198:201], v[30:33]
	v_mfma_f32_16x16x32_bf16 v[22:25], v[134:137], v[206:209], v[22:25]
	v_mfma_f32_16x16x32_bf16 v[14:17], v[142:145], v[206:209], v[14:17]
	v_mfma_f32_16x16x32_bf16 v[50:53], v[230:233], v[146:149], v[50:53]
	v_mfma_f32_16x16x32_bf16 v[42:45], v[238:241], v[146:149], v[42:45]
	v_mfma_f32_16x16x32_bf16 v[34:37], v[230:233], v[154:157], v[34:37]
	v_mfma_f32_16x16x32_bf16 v[26:29], v[238:241], v[154:157], v[26:29]
	v_mfma_f32_16x16x32_bf16 v[18:21], v[230:233], v[194:197], v[18:21]
	v_mfma_f32_16x16x32_bf16 v[10:13], v[238:241], v[194:197], v[10:13]
	v_mfma_f32_16x16x32_bf16 v[6:9], v[230:233], v[202:205], v[6:9]
	v_mfma_f32_16x16x32_bf16 v[2:5], v[238:241], v[202:205], v[2:5]
	v_mfma_f32_16x16x32_bf16 v[50:53], v[234:237], v[150:153], v[50:53]
	v_mfma_f32_16x16x32_bf16 v[42:45], v[242:245], v[150:153], v[42:45]
	v_mfma_f32_16x16x32_bf16 v[34:37], v[234:237], v[158:161], v[34:37]
	v_mfma_f32_16x16x32_bf16 v[26:29], v[242:245], v[158:161], v[26:29]
	v_mfma_f32_16x16x32_bf16 v[18:21], v[234:237], v[198:201], v[18:21]
	v_mfma_f32_16x16x32_bf16 v[10:13], v[242:245], v[198:201], v[10:13]
	v_mfma_f32_16x16x32_bf16 v[6:9], v[234:237], v[206:209], v[6:9]
	v_mfma_f32_16x16x32_bf16 v[2:5], v[242:245], v[206:209], v[2:5]
	s_setprio 0
	s_add_i32 s54, s54, 2
	s_add_u32 s42, s42, 0x100
	s_addc_u32 s43, s43, 0
	s_add_u32 s52, s52, 0x100
	s_addc_u32 s53, s53, 0
	s_cmp_gt_u32 s54, 13
	s_barrier
	s_cbranch_scc0 .LBB0_289
	v_lshl_add_u32 v208, s49, 8, v216
	v_ashrrev_i32_e32 v209, 31, v208
	v_lshlrev_b64 v[130:131], 6, v[208:209]
	v_or_b32_e32 v206, 16, v208
	v_lshl_add_u64 v[130:131], v[186:187], 0, v[130:131]
	v_ashrrev_i32_e32 v207, 31, v206
	global_load_dwordx4 v[154:157], v[130:131], off
	v_lshlrev_b64 v[130:131], 6, v[206:207]
	v_lshl_add_u64 v[130:131], v[186:187], 0, v[130:131]
	global_load_dwordx4 v[158:161], v[130:131], off
	v_or_b32_e32 v204, 32, v208
	v_ashrrev_i32_e32 v205, 31, v204
	v_lshlrev_b64 v[130:131], 6, v[204:205]
	v_or_b32_e32 v202, 48, v208
	v_lshl_add_u64 v[130:131], v[186:187], 0, v[130:131]
	v_ashrrev_i32_e32 v203, 31, v202
	global_load_dwordx4 v[150:153], v[130:131], off
	v_lshlrev_b64 v[130:131], 6, v[202:203]
	v_lshl_add_u64 v[130:131], v[186:187], 0, v[130:131]
	global_load_dwordx4 v[146:149], v[130:131], off
	v_add_u32_e32 v200, 0x80, v208
	v_ashrrev_i32_e32 v201, 31, v200
	v_lshlrev_b64 v[130:131], 6, v[200:201]
	v_add_u32_e32 v198, 0x90, v208
	v_lshl_add_u64 v[130:131], v[186:187], 0, v[130:131]
	v_ashrrev_i32_e32 v199, 31, v198
	global_load_dwordx4 v[142:145], v[130:131], off
	v_lshlrev_b64 v[130:131], 6, v[198:199]
	v_add_u32_e32 v196, 0xa0, v208
	v_lshl_add_u64 v[130:131], v[186:187], 0, v[130:131]
	v_ashrrev_i32_e32 v197, 31, v196
	global_load_dwordx4 v[138:141], v[130:131], off
	v_lshlrev_b64 v[130:131], 6, v[196:197]
	v_add_u32_e32 v194, 0xb0, v208
	v_lshl_add_u64 v[130:131], v[186:187], 0, v[130:131]
	v_ashrrev_i32_e32 v195, 31, v194
	global_load_dwordx4 v[134:137], v[130:131], off
	v_lshlrev_b64 v[130:131], 6, v[194:195]
	v_lshl_add_u64 v[130:131], v[186:187], 0, v[130:131]
	global_load_dwordx4 v[130:133], v[130:131], off
	v_and_b32_e32 v169, 64, v212
	v_xor_b32_e32 v168, 16, v212
	v_add_u32_e32 v169, 64, v169
	v_cmp_lt_i32_e32 vcc, v168, v169
	s_mov_b32 s22, 0x358637bd
	s_cmp_gt_i32 s48, 11
	v_cndmask_b32_e32 v168, v212, v168, vcc
	v_lshlrev_b32_e32 v221, 2, v168
	v_xor_b32_e32 v168, 32, v212
	v_cmp_lt_i32_e32 vcc, v168, v169
	s_cselect_b64 s[30:31], -1, 0
	v_readlane_b32 s50, v254, 42
	v_cndmask_b32_e32 v168, v212, v168, vcc
	v_lshlrev_b32_e32 v220, 2, v168
	s_mov_b64 s[44:45], -1
	s_movk_i32 s1, 0x1800
	s_movk_i32 s33, 0x7fff
	v_readlane_b32 s51, v254, 43
	s_cmpk_gt_u32 s0, 0xff
	s_cbranch_scc1 .Lrs_proj0_post
	s_barrier
.Lrs_proj0_post:
	s_waitcnt vmcnt(0)
	v_mov_b32_e32 v176, v155
	v_mov_b32_e32 v177, v156
	v_mov_b32_e32 v155, v157
	v_mov_b32_e32 v156, v159
	v_mov_b32_e32 v157, v160
	v_mov_b32_e32 v159, v161
	v_pk_add_f32 v[154:155], v[176:177], v[154:155]
	v_pk_add_f32 v[156:157], v[156:157], v[158:159]
	v_mov_b32_e32 v159, v154
	v_mov_b32_e32 v158, v156
	v_mov_b32_e32 v154, v157
	v_pk_add_f32 v[154:155], v[158:159], v[154:155]
	ds_bpermute_b32 v157, v221, v155
	ds_bpermute_b32 v156, v221, v154
	v_mov_b32_e32 v160, v151
	v_mov_b32_e32 v161, v152
	v_mov_b32_e32 v151, v153
	v_mov_b32_e32 v152, v147
	v_mov_b32_e32 v153, v148
	v_mov_b32_e32 v147, v149
	v_pk_add_f32 v[150:151], v[160:161], v[150:151]
	v_pk_add_f32 v[146:147], v[152:153], v[146:147]
	s_waitcnt lgkmcnt(0)
	v_pk_add_f32 v[154:155], v[154:155], v[156:157]
	v_mov_b32_e32 v148, v146
	v_mov_b32_e32 v149, v150
	v_mov_b32_e32 v150, v147
	ds_bpermute_b32 v157, v220, v155
	ds_bpermute_b32 v156, v220, v154
	v_pk_add_f32 v[146:147], v[148:149], v[150:151]
	ds_bpermute_b32 v149, v221, v147
	ds_bpermute_b32 v148, v221, v146
	v_mov_b64_e32 v[158:159], s[22:23]
	s_waitcnt lgkmcnt(2)
	v_pk_add_f32 v[154:155], v[154:155], v[156:157]
	s_mov_b32 s22, 0x3a800000
	v_pk_fma_f32 v[154:155], v[154:155], s[22:23], v[158:159] op_sel_hi:[1,0,0]
	s_waitcnt lgkmcnt(0)
	v_pk_add_f32 v[146:147], v[146:147], v[148:149]
	v_mul_f32_e32 v156, 0x4b800000, v155
	v_cmp_gt_f32_e64 s[42:43], s39, v155
	ds_bpermute_b32 v149, v220, v147
	ds_bpermute_b32 v148, v220, v146
	v_cndmask_b32_e64 v155, v155, v156, s[42:43]
	v_rsq_f32_e32 v155, v155
	v_mov_b32_e32 v150, v143
	v_mov_b32_e32 v151, v144
	v_mov_b32_e32 v143, v145
	v_mov_b32_e32 v144, v139
	v_mov_b32_e32 v145, v140
	v_mov_b32_e32 v139, v141
	s_waitcnt lgkmcnt(0)
	v_pk_add_f32 v[146:147], v[146:147], v[148:149]
	v_pk_add_f32 v[142:143], v[150:151], v[142:143]
	v_pk_add_f32 v[138:139], v[144:145], v[138:139]
	v_mul_f32_e32 v156, 0x45800000, v155
	v_pk_fma_f32 v[148:149], v[146:147], s[22:23], v[158:159] op_sel_hi:[1,0,0]
	v_mov_b32_e32 v140, v138
	v_mov_b32_e32 v141, v142
	v_mov_b32_e32 v142, v139
	v_cmp_gt_f32_e32 vcc, s39, v154
	v_cndmask_b32_e64 v156, v155, v156, s[42:43]
	v_mul_f32_e32 v155, 0x4b800000, v154
	v_mul_f32_e32 v146, 0x4b800000, v149
	v_cmp_gt_f32_e64 s[42:43], s39, v149
	v_pk_add_f32 v[138:139], v[140:141], v[142:143]
	v_mov_b32_e32 v142, v135
	v_mov_b32_e32 v143, v136
	v_mov_b32_e32 v135, v137
	v_mov_b32_e32 v136, v131
	v_mov_b32_e32 v137, v132
	v_mov_b32_e32 v131, v133
	v_cndmask_b32_e32 v154, v154, v155, vcc
	v_cndmask_b32_e64 v146, v149, v146, s[42:43]
	v_pk_add_f32 v[134:135], v[142:143], v[134:135]
	v_pk_add_f32 v[130:131], v[136:137], v[130:131]
	v_rsq_f32_e32 v154, v154
	v_rsq_f32_e32 v146, v146
	v_mov_b32_e32 v132, v130
	v_mov_b32_e32 v133, v134
	v_mov_b32_e32 v134, v131
	v_pk_add_f32 v[130:131], v[132:133], v[134:135]
	ds_bpermute_b32 v141, v221, v139
	ds_bpermute_b32 v140, v221, v138
	ds_bpermute_b32 v133, v221, v131
	ds_bpermute_b32 v132, v221, v130
	v_mul_f32_e32 v155, 0x45800000, v154
	v_mul_f32_e32 v147, 0x45800000, v146
	v_cndmask_b32_e32 v154, v154, v155, vcc
	v_cmp_gt_f32_e32 vcc, s39, v148
	v_cndmask_b32_e64 v146, v146, v147, s[42:43]
	v_mul_f32_e32 v147, 0x4b800000, v148
	v_cndmask_b32_e32 v147, v148, v147, vcc
	v_rsq_f32_e32 v147, v147
	s_waitcnt lgkmcnt(2)
	v_pk_add_f32 v[138:139], v[138:139], v[140:141]
	s_waitcnt lgkmcnt(0)
	v_pk_add_f32 v[132:133], v[130:131], v[132:133]
	ds_bpermute_b32 v141, v220, v139
	ds_bpermute_b32 v140, v220, v138
	ds_bpermute_b32 v135, v220, v133
	ds_bpermute_b32 v134, v220, v132
	v_mul_f32_e32 v148, 0x45800000, v147
	v_cndmask_b32_e64 v130, 0, 1, s[24:25]
	v_cndmask_b32_e32 v148, v147, v148, vcc
	s_and_b64 vcc, exec, s[30:31]
	v_cmp_ne_u32_e64 s[42:43], 1, v130
	s_cbranch_vccz .LBB0_294
	s_and_b64 vcc, exec, s[42:43]
	s_cbranch_vccnz .LBB0_293
	global_load_dwordx4 v[142:145], v[188:189], off
	v_lshlrev_b64 v[130:131], 7, v[208:209]
	v_lshl_add_u64 v[130:131], v[184:185], 0, v[130:131]
	s_waitcnt vmcnt(0)
	v_pk_fma_f32 v[144:145], v[128:129], v[156:157], v[144:145] op_sel_hi:[1,0,1]
	v_pk_fma_f32 v[142:143], v[126:127], v[156:157], v[142:143] op_sel_hi:[1,0,1]
	global_store_dwordx4 v[130:131], v[142:145], off
	global_load_dwordx4 v[142:145], v[188:189], off offset:16
	s_waitcnt vmcnt(0)
	v_pk_fma_f32 v[144:145], v[124:125], v[156:157], v[144:145] op_sel_hi:[1,0,1]
	v_pk_fma_f32 v[142:143], v[122:123], v[156:157], v[142:143] op_sel_hi:[1,0,1]
	global_store_dwordx4 v[130:131], v[142:145], off offset:16
	global_load_dwordx4 v[142:145], v[188:189], off
	v_lshlrev_b64 v[130:131], 7, v[206:207]
	v_lshl_add_u64 v[130:131], v[184:185], 0, v[130:131]
	s_waitcnt vmcnt(0)
	v_pk_fma_f32 v[144:145], v[120:121], v[154:155], v[144:145] op_sel_hi:[1,0,1]
	v_pk_fma_f32 v[142:143], v[118:119], v[154:155], v[142:143] op_sel_hi:[1,0,1]
	global_store_dwordx4 v[130:131], v[142:145], off
	global_load_dwordx4 v[142:145], v[188:189], off offset:16
	s_waitcnt vmcnt(0)
	v_pk_fma_f32 v[144:145], v[112:113], v[154:155], v[144:145] op_sel_hi:[1,0,1]
	v_pk_fma_f32 v[142:143], v[110:111], v[154:155], v[142:143] op_sel_hi:[1,0,1]
	global_store_dwordx4 v[130:131], v[142:145], off offset:16
	global_load_dwordx4 v[142:145], v[188:189], off
	v_lshlrev_b64 v[130:131], 7, v[204:205]
	v_lshl_add_u64 v[130:131], v[184:185], 0, v[130:131]
	s_waitcnt vmcnt(0)
	v_pk_fma_f32 v[144:145], v[104:105], v[146:147], v[144:145] op_sel_hi:[1,0,1]
	v_pk_fma_f32 v[142:143], v[102:103], v[146:147], v[142:143] op_sel_hi:[1,0,1]
	global_store_dwordx4 v[130:131], v[142:145], off
	global_load_dwordx4 v[142:145], v[188:189], off offset:16
	s_waitcnt vmcnt(0)
	v_pk_fma_f32 v[144:145], v[96:97], v[146:147], v[144:145] op_sel_hi:[1,0,1]
	v_pk_fma_f32 v[142:143], v[94:95], v[146:147], v[142:143] op_sel_hi:[1,0,1]
	global_store_dwordx4 v[130:131], v[142:145], off offset:16
	global_load_dwordx4 v[142:145], v[188:189], off
	v_lshlrev_b64 v[130:131], 7, v[202:203]
	v_lshl_add_u64 v[130:131], v[184:185], 0, v[130:131]
	s_waitcnt vmcnt(0)
	v_pk_fma_f32 v[144:145], v[88:89], v[148:149], v[144:145] op_sel_hi:[1,0,1]
	v_pk_fma_f32 v[142:143], v[86:87], v[148:149], v[142:143] op_sel_hi:[1,0,1]
	global_store_dwordx4 v[130:131], v[142:145], off
	global_load_dwordx4 v[142:145], v[188:189], off offset:16
	s_waitcnt vmcnt(0)
	v_pk_fma_f32 v[144:145], v[80:81], v[148:149], v[144:145] op_sel_hi:[1,0,1]
	v_pk_fma_f32 v[142:143], v[78:79], v[148:149], v[142:143] op_sel_hi:[1,0,1]
	global_store_dwordx4 v[130:131], v[142:145], off offset:16

.LBB0_362:
	s_add_u32 s1, s28, 0xfffc0080
	s_addc_u32 s22, s29, -1
	s_add_i32 s23, 0, 0x10000
	v_add_u32_e32 v158, s23, v181
	ds_read_b128 v[130:133], v158
	ds_read_b128 v[134:137], v158 offset:1024
	ds_read_b128 v[154:157], v158 offset:2048
	ds_read_b128 v[186:189], v158 offset:3072
	s_cmp_eq_u32 s44, 12
	s_cselect_b32 s43, s17, s22
	s_cselect_b32 s42, s20, s1
	s_cselect_b32 s31, s9, s34
	s_cselect_b32 s30, s21, s25
	v_lshl_add_u64 v[160:161], s[28:29], 0, v[150:151]
	s_add_i32 m0, s49, 0xc000
	ds_read_b128 v[190:193], v185
	ds_read_b128 v[194:197], v185 offset:1024
	ds_read_b128 v[198:201], v185 offset:2048
	ds_read_b128 v[202:205], v185 offset:3072
	ds_read_b128 v[206:209], v185 offset:4096
	ds_read_b128 v[216:219], v185 offset:5120
	ds_read_b128 v[230:233], v185 offset:6144
	ds_read_b128 v[234:237], v185 offset:7168
	global_load_lds_dwordx4 v[160:161], off
	v_lshl_add_u64 v[160:161], s[28:29], 0, v[152:153]
	s_add_i32 m0, s49, 0xe000
	s_nop 0
	global_load_lds_dwordx4 v[160:161], off
	s_add_i32 s1, 0, 0x14000
	v_add_u32_e32 v158, s1, v181
	ds_read_b128 v[238:241], v158
	ds_read_b128 v[242:245], v158 offset:1024
	ds_read_b128 v[246:249], v158 offset:2048
	ds_read_b128 v[176:179], v158 offset:3072
	s_waitcnt vmcnt(8)
	s_waitcnt lgkmcnt(0)
	s_barrier
	s_setprio 1
	v_mfma_f32_16x16x32_bf16 v[126:129], v[130:133], v[190:193], v[126:129]
	v_mfma_f32_16x16x32_bf16 v[122:125], v[154:157], v[190:193], v[122:125]
	v_mfma_f32_16x16x32_bf16 v[110:113], v[130:133], v[198:201], v[110:113]
	v_mfma_f32_16x16x32_bf16 v[106:109], v[154:157], v[198:201], v[106:109]
	v_mfma_f32_16x16x32_bf16 v[94:97], v[130:133], v[206:209], v[94:97]
	v_mfma_f32_16x16x32_bf16 v[90:93], v[154:157], v[206:209], v[90:93]
	v_mfma_f32_16x16x32_bf16 v[78:81], v[130:133], v[230:233], v[78:81]
	v_mfma_f32_16x16x32_bf16 v[74:77], v[154:157], v[230:233], v[74:77]
	v_mfma_f32_16x16x32_bf16 v[126:129], v[134:137], v[194:197], v[126:129]
	v_mfma_f32_16x16x32_bf16 v[122:125], v[186:189], v[194:197], v[122:125]
	v_mfma_f32_16x16x32_bf16 v[110:113], v[134:137], v[202:205], v[110:113]
	v_mfma_f32_16x16x32_bf16 v[106:109], v[186:189], v[202:205], v[106:109]
	v_mfma_f32_16x16x32_bf16 v[94:97], v[134:137], v[216:219], v[94:97]
	v_mfma_f32_16x16x32_bf16 v[90:93], v[186:189], v[216:219], v[90:93]
	v_mfma_f32_16x16x32_bf16 v[78:81], v[134:137], v[234:237], v[78:81]
	v_mfma_f32_16x16x32_bf16 v[74:77], v[186:189], v[234:237], v[74:77]
	v_mfma_f32_16x16x32_bf16 v[118:121], v[238:241], v[190:193], v[118:121]
	v_mfma_f32_16x16x32_bf16 v[114:117], v[246:249], v[190:193], v[114:117]
	v_mfma_f32_16x16x32_bf16 v[102:105], v[238:241], v[198:201], v[102:105]
	v_mfma_f32_16x16x32_bf16 v[98:101], v[246:249], v[198:201], v[98:101]
	v_mfma_f32_16x16x32_bf16 v[86:89], v[238:241], v[206:209], v[86:89]
	v_mfma_f32_16x16x32_bf16 v[82:85], v[246:249], v[206:209], v[82:85]
	v_mfma_f32_16x16x32_bf16 v[70:73], v[238:241], v[230:233], v[70:73]
	v_mfma_f32_16x16x32_bf16 v[66:69], v[246:249], v[230:233], v[66:69]
	v_mfma_f32_16x16x32_bf16 v[118:121], v[242:245], v[194:197], v[118:121]
	v_mfma_f32_16x16x32_bf16 v[114:117], v[176:179], v[194:197], v[114:117]
	v_mfma_f32_16x16x32_bf16 v[102:105], v[242:245], v[202:205], v[102:105]
	v_mfma_f32_16x16x32_bf16 v[98:101], v[176:179], v[202:205], v[98:101]
	v_mfma_f32_16x16x32_bf16 v[86:89], v[242:245], v[216:219], v[86:89]
	v_mfma_f32_16x16x32_bf16 v[82:85], v[176:179], v[216:219], v[82:85]
	v_mfma_f32_16x16x32_bf16 v[70:73], v[242:245], v[234:237], v[70:73]
	v_mfma_f32_16x16x32_bf16 v[66:69], v[176:179], v[234:237], v[66:69]
	s_setprio 0
	s_barrier
	ds_read_b128 v[190:193], v185 offset:16384
	ds_read_b128 v[194:197], v185 offset:17408
	ds_read_b128 v[198:201], v185 offset:18432
	ds_read_b128 v[202:205], v185 offset:19456
	ds_read_b128 v[206:209], v185 offset:20480
	ds_read_b128 v[216:219], v185 offset:21504
	ds_read_b128 v[230:233], v185 offset:22528
	ds_read_b128 v[234:237], v185 offset:23552
	s_add_i32 s22, s23, s48
	v_lshl_add_u64 v[160:161], s[30:31], 0, v[0:1]
	s_mov_b32 m0, s22
	s_nop 0
	global_load_lds_dwordx4 v[160:161], off
	v_lshl_add_u64 v[220:221], s[30:31], 0, v[138:139]
	s_add_i32 m0, s22, 0x2000
	s_nop 0
	global_load_lds_dwordx4 v[220:221], off
	s_mov_b32 m0, s49
	v_lshl_add_u64 v[250:251], s[42:43], 0, v[142:143]
	global_load_lds_dwordx4 v[250:251], off
	v_lshl_add_u64 v[168:169], s[42:43], 0, v[140:141]
	s_mov_b32 m0, s50
	s_nop 0
	global_load_lds_dwordx4 v[168:169], off
	s_add_u32 s22, s30, 0x40000
	s_addc_u32 s23, s31, 0
	s_add_i32 s1, s1, s48
	s_mov_b32 m0, s1
	s_nop 0
	global_load_lds_dwordx4 v0, s[22:23]
	s_add_i32 m0, s1, 0x2000
	s_nop 0
	global_load_lds_dwordx4 v138, s[22:23]
	s_waitcnt vmcnt(8)
	s_waitcnt lgkmcnt(0)
	s_barrier
	s_setprio 1
	v_mfma_f32_16x16x32_bf16 v[62:65], v[130:133], v[190:193], v[62:65]
	v_mfma_f32_16x16x32_bf16 v[58:61], v[154:157], v[190:193], v[58:61]
	v_mfma_f32_16x16x32_bf16 v[46:49], v[130:133], v[198:201], v[46:49]
	v_mfma_f32_16x16x32_bf16 v[42:45], v[154:157], v[198:201], v[42:45]
	v_mfma_f32_16x16x32_bf16 v[30:33], v[130:133], v[206:209], v[30:33]
	v_mfma_f32_16x16x32_bf16 v[26:29], v[154:157], v[206:209], v[26:29]
	v_mfma_f32_16x16x32_bf16 v[14:17], v[130:133], v[230:233], v[14:17]
	v_mfma_f32_16x16x32_bf16 v[10:13], v[154:157], v[230:233], v[10:13]
	v_mfma_f32_16x16x32_bf16 v[62:65], v[134:137], v[194:197], v[62:65]
	v_mfma_f32_16x16x32_bf16 v[58:61], v[186:189], v[194:197], v[58:61]
	v_mfma_f32_16x16x32_bf16 v[46:49], v[134:137], v[202:205], v[46:49]
	v_mfma_f32_16x16x32_bf16 v[42:45], v[186:189], v[202:205], v[42:45]
	v_mfma_f32_16x16x32_bf16 v[30:33], v[134:137], v[216:219], v[30:33]
	v_mfma_f32_16x16x32_bf16 v[26:29], v[186:189], v[216:219], v[26:29]
	v_mfma_f32_16x16x32_bf16 v[14:17], v[134:137], v[234:237], v[14:17]
	v_mfma_f32_16x16x32_bf16 v[10:13], v[186:189], v[234:237], v[10:13]
	v_mfma_f32_16x16x32_bf16 v[54:57], v[238:241], v[190:193], v[54:57]
	v_mfma_f32_16x16x32_bf16 v[50:53], v[246:249], v[190:193], v[50:53]
	v_mfma_f32_16x16x32_bf16 v[38:41], v[238:241], v[198:201], v[38:41]
	v_mfma_f32_16x16x32_bf16 v[34:37], v[246:249], v[198:201], v[34:37]
	v_mfma_f32_16x16x32_bf16 v[22:25], v[238:241], v[206:209], v[22:25]
	v_mfma_f32_16x16x32_bf16 v[18:21], v[246:249], v[206:209], v[18:21]
	v_mfma_f32_16x16x32_bf16 v[6:9], v[238:241], v[230:233], v[6:9]
	v_mfma_f32_16x16x32_bf16 v[2:5], v[246:249], v[230:233], v[2:5]
	v_mfma_f32_16x16x32_bf16 v[54:57], v[242:245], v[194:197], v[54:57]
	v_mfma_f32_16x16x32_bf16 v[50:53], v[176:179], v[194:197], v[50:53]
	v_mfma_f32_16x16x32_bf16 v[38:41], v[242:245], v[202:205], v[38:41]
	v_mfma_f32_16x16x32_bf16 v[34:37], v[176:179], v[202:205], v[34:37]
	v_mfma_f32_16x16x32_bf16 v[22:25], v[242:245], v[216:219], v[22:25]
	v_mfma_f32_16x16x32_bf16 v[18:21], v[176:179], v[216:219], v[18:21]
	v_mfma_f32_16x16x32_bf16 v[6:9], v[242:245], v[234:237], v[6:9]
	v_mfma_f32_16x16x32_bf16 v[2:5], v[176:179], v[234:237], v[2:5]
	s_setprio 0
	s_barrier
	s_add_i32 s1, 0, 0x18000
	v_add_u32_e32 v158, s1, v181
	ds_read_b128 v[130:133], v158
	ds_read_b128 v[134:137], v158 offset:1024
	ds_read_b128 v[154:157], v158 offset:2048
	ds_read_b128 v[176:179], v158 offset:3072
	s_add_u32 s22, s42, 0x40000
	s_addc_u32 s23, s43, 0
	s_mov_b32 m0, s51
	v_lshl_add_u64 v[234:235], s[22:23], 0, v[142:143]
	ds_read_b128 v[186:189], v185 offset:32768
	ds_read_b128 v[190:193], v185 offset:33792
	ds_read_b128 v[194:197], v185 offset:34816
	ds_read_b128 v[198:201], v185 offset:35840
	ds_read_b128 v[202:205], v185 offset:36864
	ds_read_b128 v[206:209], v185 offset:37888
	ds_read_b128 v[216:219], v185 offset:38912
	ds_read_b128 v[230:233], v185 offset:39936
	global_load_lds_dwordx4 v[234:235], off
	v_lshl_add_u64 v[234:235], s[22:23], 0, v[140:141]
	s_mov_b32 m0, s52
	s_nop 0
	global_load_lds_dwordx4 v[234:235], off
	s_add_i32 s33, 0, 0x1c000
	v_add_u32_e32 v158, s33, v181
	ds_read_b128 v[234:237], v158
	ds_read_b128 v[238:241], v158 offset:1024
	ds_read_b128 v[242:245], v158 offset:2048
	ds_read_b128 v[246:249], v158 offset:3072
	s_waitcnt vmcnt(8)
	s_waitcnt lgkmcnt(0)
	s_barrier
	s_setprio 1
	v_mfma_f32_16x16x32_bf16 v[126:129], v[130:133], v[186:189], v[126:129]
	v_mfma_f32_16x16x32_bf16 v[122:125], v[154:157], v[186:189], v[122:125]
	v_mfma_f32_16x16x32_bf16 v[110:113], v[130:133], v[194:197], v[110:113]
	v_mfma_f32_16x16x32_bf16 v[106:109], v[154:157], v[194:197], v[106:109]
	v_mfma_f32_16x16x32_bf16 v[94:97], v[130:133], v[202:205], v[94:97]
	v_mfma_f32_16x16x32_bf16 v[90:93], v[154:157], v[202:205], v[90:93]
	v_mfma_f32_16x16x32_bf16 v[78:81], v[130:133], v[216:219], v[78:81]
	v_mfma_f32_16x16x32_bf16 v[74:77], v[154:157], v[216:219], v[74:77]
	v_mfma_f32_16x16x32_bf16 v[126:129], v[134:137], v[190:193], v[126:129]
	v_mfma_f32_16x16x32_bf16 v[122:125], v[176:179], v[190:193], v[122:125]
	v_mfma_f32_16x16x32_bf16 v[110:113], v[134:137], v[198:201], v[110:113]
	v_mfma_f32_16x16x32_bf16 v[106:109], v[176:179], v[198:201], v[106:109]
	v_mfma_f32_16x16x32_bf16 v[94:97], v[134:137], v[206:209], v[94:97]
	v_mfma_f32_16x16x32_bf16 v[90:93], v[176:179], v[206:209], v[90:93]
	v_mfma_f32_16x16x32_bf16 v[78:81], v[134:137], v[230:233], v[78:81]
	v_mfma_f32_16x16x32_bf16 v[74:77], v[176:179], v[230:233], v[74:77]
	v_mfma_f32_16x16x32_bf16 v[118:121], v[234:237], v[186:189], v[118:121]
	v_mfma_f32_16x16x32_bf16 v[114:117], v[242:245], v[186:189], v[114:117]
	v_mfma_f32_16x16x32_bf16 v[102:105], v[234:237], v[194:197], v[102:105]
	v_mfma_f32_16x16x32_bf16 v[98:101], v[242:245], v[194:197], v[98:101]
	v_mfma_f32_16x16x32_bf16 v[86:89], v[234:237], v[202:205], v[86:89]
	v_mfma_f32_16x16x32_bf16 v[82:85], v[242:245], v[202:205], v[82:85]
	v_mfma_f32_16x16x32_bf16 v[70:73], v[234:237], v[216:219], v[70:73]
	v_mfma_f32_16x16x32_bf16 v[66:69], v[242:245], v[216:219], v[66:69]
	v_mfma_f32_16x16x32_bf16 v[118:121], v[238:241], v[190:193], v[118:121]
	v_mfma_f32_16x16x32_bf16 v[114:117], v[246:249], v[190:193], v[114:117]
	v_mfma_f32_16x16x32_bf16 v[102:105], v[238:241], v[198:201], v[102:105]
	v_mfma_f32_16x16x32_bf16 v[98:101], v[246:249], v[198:201], v[98:101]
	v_mfma_f32_16x16x32_bf16 v[86:89], v[238:241], v[206:209], v[86:89]
	v_mfma_f32_16x16x32_bf16 v[82:85], v[246:249], v[206:209], v[82:85]
	v_mfma_f32_16x16x32_bf16 v[70:73], v[238:241], v[230:233], v[70:73]
	v_mfma_f32_16x16x32_bf16 v[66:69], v[246:249], v[230:233], v[66:69]
	s_setprio 0
	s_barrier
	ds_read_b128 v[186:189], v185 offset:49152
	ds_read_b128 v[190:193], v185 offset:50176
	ds_read_b128 v[194:197], v185 offset:51200
	ds_read_b128 v[198:201], v185 offset:52224
	ds_read_b128 v[202:205], v185 offset:53248
	ds_read_b128 v[206:209], v185 offset:54272
	ds_read_b128 v[216:219], v185 offset:55296
	ds_read_b128 v[230:233], v185 offset:56320
	s_add_i32 s1, s1, s48
	v_lshl_add_u64 v[160:161], v[160:161], 0, s[12:13]
	s_mov_b32 m0, s1
	s_nop 0
	global_load_lds_dwordx4 v[160:161], off
	v_lshl_add_u64 v[160:161], v[220:221], 0, s[12:13]
	s_add_i32 m0, s1, 0x2000
	s_nop 0
	global_load_lds_dwordx4 v[160:161], off
	s_mov_b32 m0, s55
	v_lshl_add_u64 v[160:161], v[250:251], 0, s[12:13]
	global_load_lds_dwordx4 v[160:161], off
	v_lshl_add_u64 v[160:161], v[168:169], 0, s[12:13]
	s_mov_b32 m0, s56
	s_nop 0
	global_load_lds_dwordx4 v[160:161], off
	s_add_u32 s22, s30, 0x40080
	s_addc_u32 s23, s31, 0
	s_add_i32 s1, s33, s48
	s_mov_b32 m0, s1
	s_nop 0
	global_load_lds_dwordx4 v0, s[22:23]
	s_add_i32 m0, s1, 0x2000
	s_nop 0
	global_load_lds_dwordx4 v138, s[22:23]
	s_waitcnt vmcnt(8)
	s_waitcnt lgkmcnt(0)
	s_barrier
	s_setprio 1
	v_mfma_f32_16x16x32_bf16 v[62:65], v[130:133], v[186:189], v[62:65]
	v_mfma_f32_16x16x32_bf16 v[58:61], v[154:157], v[186:189], v[58:61]
	v_mfma_f32_16x16x32_bf16 v[46:49], v[130:133], v[194:197], v[46:49]
	v_mfma_f32_16x16x32_bf16 v[42:45], v[154:157], v[194:197], v[42:45]
	v_mfma_f32_16x16x32_bf16 v[30:33], v[130:133], v[202:205], v[30:33]
	v_mfma_f32_16x16x32_bf16 v[26:29], v[154:157], v[202:205], v[26:29]
	v_mfma_f32_16x16x32_bf16 v[14:17], v[130:133], v[216:219], v[14:17]
	v_mfma_f32_16x16x32_bf16 v[10:13], v[154:157], v[216:219], v[10:13]
	v_mfma_f32_16x16x32_bf16 v[62:65], v[134:137], v[190:193], v[62:65]
	v_mfma_f32_16x16x32_bf16 v[58:61], v[176:179], v[190:193], v[58:61]
	v_mfma_f32_16x16x32_bf16 v[46:49], v[134:137], v[198:201], v[46:49]
	v_mfma_f32_16x16x32_bf16 v[42:45], v[176:179], v[198:201], v[42:45]
	v_mfma_f32_16x16x32_bf16 v[30:33], v[134:137], v[206:209], v[30:33]
	v_mfma_f32_16x16x32_bf16 v[26:29], v[176:179], v[206:209], v[26:29]
	v_mfma_f32_16x16x32_bf16 v[14:17], v[134:137], v[230:233], v[14:17]
	v_mfma_f32_16x16x32_bf16 v[10:13], v[176:179], v[230:233], v[10:13]
	v_mfma_f32_16x16x32_bf16 v[54:57], v[234:237], v[186:189], v[54:57]
	v_mfma_f32_16x16x32_bf16 v[50:53], v[242:245], v[186:189], v[50:53]
	v_mfma_f32_16x16x32_bf16 v[38:41], v[234:237], v[194:197], v[38:41]
	v_mfma_f32_16x16x32_bf16 v[34:37], v[242:245], v[194:197], v[34:37]
	v_mfma_f32_16x16x32_bf16 v[22:25], v[234:237], v[202:205], v[22:25]
	v_mfma_f32_16x16x32_bf16 v[18:21], v[242:245], v[202:205], v[18:21]
	v_mfma_f32_16x16x32_bf16 v[6:9], v[234:237], v[216:219], v[6:9]
	v_mfma_f32_16x16x32_bf16 v[2:5], v[242:245], v[216:219], v[2:5]
	v_mfma_f32_16x16x32_bf16 v[54:57], v[238:241], v[190:193], v[54:57]
	v_mfma_f32_16x16x32_bf16 v[50:53], v[246:249], v[190:193], v[50:53]
	v_mfma_f32_16x16x32_bf16 v[38:41], v[238:241], v[198:201], v[38:41]
	v_mfma_f32_16x16x32_bf16 v[34:37], v[246:249], v[198:201], v[34:37]
	v_mfma_f32_16x16x32_bf16 v[22:25], v[238:241], v[206:209], v[22:25]
	v_mfma_f32_16x16x32_bf16 v[18:21], v[246:249], v[206:209], v[18:21]
	v_mfma_f32_16x16x32_bf16 v[6:9], v[238:241], v[230:233], v[6:9]
	v_mfma_f32_16x16x32_bf16 v[2:5], v[246:249], v[230:233], v[2:5]
	s_setprio 0
	s_add_i32 s44, s44, 2
	s_add_u32 s28, s28, 0x100
	s_addc_u32 s29, s29, 0
	s_add_u32 s25, s25, 0x100
	s_addc_u32 s34, s34, 0
	s_cmp_gt_u32 s44, 13
	s_barrier
	s_cbranch_scc0 .LBB0_362
	v_and_b32_e32 v131, 64, v212
	v_xor_b32_e32 v130, 16, v212
	v_add_u32_e32 v131, 64, v131
	v_lshl_add_u32 v190, s16, 8, v159
	v_cmp_lt_i32_e32 vcc, v130, v131
	v_add_u32_e32 v156, s54, v190
	v_or_b32_e32 v134, 16, v156
	v_cndmask_b32_e32 v130, v212, v130, vcc
	v_lshlrev_b32_e32 v191, 2, v130
	v_xor_b32_e32 v130, 32, v212
	v_cmp_lt_i32_e32 vcc, v130, v131
	v_ashrrev_i32_e32 v157, 31, v156
	v_ashrrev_i32_e32 v135, 31, v134
	v_cndmask_b32_e32 v130, v212, v130, vcc
	v_lshlrev_b64 v[136:137], 6, v[156:157]
	v_lshlrev_b64 v[134:135], 6, v[134:135]
	v_lshlrev_b32_e32 v192, 2, v130
	v_lshl_add_u64 v[130:131], v[144:145], 0, v[136:137]
	v_lshl_add_u64 v[160:161], v[144:145], 0, v[134:135]
	global_load_dwordx4 v[130:133], v[130:131], off
	v_lshl_or_b32 v154, s0, 8, v183
	global_load_dwordx4 v[186:189], v[160:161], off
	v_or_b32_e32 v160, 32, v156
	v_ashrrev_i32_e32 v161, 31, v160
	v_lshlrev_b64 v[178:179], 6, v[160:161]
	v_or_b32_e32 v156, 48, v156
	v_lshl_add_u64 v[160:161], v[144:145], 0, v[178:179]
	v_ashrrev_i32_e32 v157, 31, v156
	global_load_dwordx4 v[194:197], v[160:161], off
	v_lshlrev_b64 v[160:161], 6, v[156:157]
	v_lshl_add_u64 v[156:157], v[144:145], 0, v[160:161]
	global_load_dwordx4 v[198:201], v[156:157], off
	s_ashr_i32 s0, s0, 2
	s_mul_hi_i32 s1, s0, 0x55555556
	s_lshr_b32 s9, s1, 31
	s_add_i32 s1, s1, s9
	s_mul_i32 s1, s1, 3
	s_sub_i32 s0, s0, s1
	s_cmp_lt_i32 s0, 2
	s_cselect_b64 s[0:1], -1, 0
	s_and_b64 s[28:29], s[6:7], s[0:1]
	v_ashrrev_i32_e32 v155, 31, v154
	s_mov_b64 s[44:45], -1
	v_or_b32_e32 v193, 48, v190
	s_cmpk_gt_u32 s4, 0xff
	s_cbranch_scc1 .Lrs_proj1_post
	s_barrier
.Lrs_proj1_post:
	s_waitcnt vmcnt(0)
	v_mov_b32_e32 v156, v131
	v_mov_b32_e32 v157, v132
	v_mov_b32_e32 v131, v133
	v_mov_b32_e32 v132, v187
	v_mov_b32_e32 v133, v188
	v_mov_b32_e32 v187, v189
	v_pk_add_f32 v[130:131], v[156:157], v[130:131]
	v_pk_add_f32 v[132:133], v[132:133], v[186:187]
	v_mov_b32_e32 v157, v130
	v_mov_b32_e32 v156, v132
	v_mov_b32_e32 v130, v133
	v_pk_add_f32 v[130:131], v[156:157], v[130:131]
	ds_bpermute_b32 v133, v191, v131
	ds_bpermute_b32 v132, v191, v130
	v_mov_b32_e32 v157, v200
	s_waitcnt lgkmcnt(0)
	v_pk_add_f32 v[130:131], v[130:131], v[132:133]
	ds_bpermute_b32 v133, v192, v131
	ds_bpermute_b32 v132, v192, v130
	s_waitcnt lgkmcnt(0)
	v_pk_add_f32 v[130:131], v[130:131], v[132:133]
	v_mov_b64_e32 v[132:133], s[60:61]
	v_pk_fma_f32 v[130:131], v[130:131], s[58:59], v[132:133] op_sel_hi:[1,0,0]
	s_nop 0
	v_mul_f32_e32 v156, 0x4b800000, v131
	v_cmp_gt_f32_e64 s[42:43], s39, v131
	v_cmp_gt_f32_e32 vcc, s39, v130
	s_nop 0
	v_cndmask_b32_e64 v131, v131, v156, s[42:43]
	v_rsq_f32_e32 v131, v131
	s_nop 0
	v_mul_f32_e32 v156, 0x45800000, v131
	v_cndmask_b32_e64 v184, v131, v156, s[42:43]
	v_mul_f32_e32 v131, 0x4b800000, v130
	v_cndmask_b32_e32 v130, v130, v131, vcc
	v_rsq_f32_e32 v130, v130
	v_mov_b32_e32 v156, v199
	v_mov_b32_e32 v199, v201
	v_pk_add_f32 v[156:157], v[156:157], v[198:199]
	v_mul_f32_e32 v131, 0x45800000, v130
	v_cndmask_b32_e32 v182, v130, v131, vcc
	v_mov_b32_e32 v130, v195
	v_mov_b32_e32 v131, v196
	v_mov_b32_e32 v195, v197
	v_pk_add_f32 v[130:131], v[130:131], v[194:195]
	v_mov_b32_e32 v176, v156
	v_mov_b32_e32 v177, v130
	v_mov_b32_e32 v130, v157
	v_pk_add_f32 v[130:131], v[176:177], v[130:131]
	ds_bpermute_b32 v157, v191, v131
	ds_bpermute_b32 v156, v191, v130
	v_or_b32_e32 v195, 16, v190
	v_or_b32_e32 v194, 32, v190
	s_waitcnt lgkmcnt(0)
	v_pk_add_f32 v[130:131], v[130:131], v[156:157]
	ds_bpermute_b32 v157, v192, v131
	ds_bpermute_b32 v156, v192, v130
	s_waitcnt lgkmcnt(0)
	v_pk_add_f32 v[130:131], v[130:131], v[156:157]
	s_nop 0
	v_pk_fma_f32 v[130:131], v[130:131], s[58:59], v[132:133] op_sel_hi:[1,0,0]
	v_lshlrev_b64 v[156:157], 1, v[154:155]
	v_mul_f32_e32 v132, 0x4b800000, v131
	v_cmp_gt_f32_e64 s[42:43], s39, v131
	v_cmp_gt_f32_e32 vcc, s39, v130
	s_nop 0
	v_cndmask_b32_e64 v131, v131, v132, s[42:43]
	v_rsq_f32_e32 v131, v131
	s_nop 0
	v_mul_f32_e32 v132, 0x45800000, v131
	v_cndmask_b32_e64 v180, v131, v132, s[42:43]
	v_mul_f32_e32 v131, 0x4b800000, v130
	v_cndmask_b32_e32 v130, v130, v131, vcc
	v_rsq_f32_e32 v130, v130
	s_nop 0
	v_mul_f32_e32 v131, 0x45800000, v130
	v_cndmask_b32_e32 v158, v130, v131, vcc
	s_and_b64 vcc, exec, s[28:29]
	s_cbranch_vccnz .LBB0_365
	v_mov_b64_e32 v[176:177], s[68:69]
	v_mad_i64_i32 v[130:131], s[0:1], v190, s86, v[176:177]
	v_lshl_add_u64 v[186:187], v[130:131], 0, v[156:157]
	v_pk_mul_f32 v[132:133], v[128:129], v[184:185] op_sel_hi:[1,0]
	v_pk_mul_f32 v[130:131], v[126:127], v[184:185] op_sel_hi:[1,0]
	v_pk_mul_f32 v[188:189], v[124:125], v[184:185] op_sel_hi:[1,0]
	v_pk_mul_f32 v[196:197], v[122:123], v[184:185] op_sel_hi:[1,0]
	v_cvt_pk_bf16_f32 v130, v130, v131
	v_cvt_pk_bf16_f32 v131, v132, v133
	v_cvt_pk_bf16_f32 v132, v196, v197
	v_cvt_pk_bf16_f32 v133, v188, v189
	global_store_dwordx4 v[186:187], v[130:133], off
	v_pk_mul_f32 v[188:189], v[116:117], v[184:185] op_sel_hi:[1,0]
	v_pk_mul_f32 v[196:197], v[114:115], v[184:185] op_sel_hi:[1,0]
	v_pk_mul_f32 v[132:133], v[120:121], v[184:185] op_sel_hi:[1,0]
	v_pk_mul_f32 v[130:131], v[118:119], v[184:185] op_sel_hi:[1,0]
	s_mov_b64 s[44:45], 0
	v_cvt_pk_bf16_f32 v130, v130, v131
	v_cvt_pk_bf16_f32 v131, v132, v133
	v_cvt_pk_bf16_f32 v132, v196, v197
	v_cvt_pk_bf16_f32 v133, v188, v189
	global_store_dwordx4 v[186:187], v[130:133], off offset:256
	v_pk_mul_f32 v[188:189], v[108:109], v[182:183] op_sel_hi:[1,0]
	v_pk_mul_f32 v[196:197], v[106:107], v[182:183] op_sel_hi:[1,0]
	v_mad_i64_i32 v[130:131], s[0:1], v195, s86, v[176:177]
	v_lshl_add_u64 v[186:187], v[130:131], 0, v[156:157]
	v_pk_mul_f32 v[132:133], v[112:113], v[182:183] op_sel_hi:[1,0]
	v_pk_mul_f32 v[130:131], v[110:111], v[182:183] op_sel_hi:[1,0]
	s_nop 0
	v_cvt_pk_bf16_f32 v130, v130, v131
	v_cvt_pk_bf16_f32 v131, v132, v133
	v_cvt_pk_bf16_f32 v132, v196, v197
	v_cvt_pk_bf16_f32 v133, v188, v189
	global_store_dwordx4 v[186:187], v[130:133], off
	v_pk_mul_f32 v[188:189], v[100:101], v[182:183] op_sel_hi:[1,0]
	v_pk_mul_f32 v[196:197], v[98:99], v[182:183] op_sel_hi:[1,0]
	v_pk_mul_f32 v[132:133], v[104:105], v[182:183] op_sel_hi:[1,0]
	v_pk_mul_f32 v[130:131], v[102:103], v[182:183] op_sel_hi:[1,0]
	s_nop 0
	v_cvt_pk_bf16_f32 v130, v130, v131
	v_cvt_pk_bf16_f32 v131, v132, v133
	v_cvt_pk_bf16_f32 v132, v196, v197
	v_cvt_pk_bf16_f32 v133, v188, v189
	global_store_dwordx4 v[186:187], v[130:133], off offset:256
	v_pk_mul_f32 v[188:189], v[92:93], v[180:181] op_sel_hi:[1,0]
	v_pk_mul_f32 v[196:197], v[90:91], v[180:181] op_sel_hi:[1,0]
	v_mad_i64_i32 v[130:131], s[0:1], v194, s86, v[176:177]
	v_lshl_add_u64 v[186:187], v[130:131], 0, v[156:157]
	v_pk_mul_f32 v[132:133], v[96:97], v[180:181] op_sel_hi:[1,0]
	v_pk_mul_f32 v[130:131], v[94:95], v[180:181] op_sel_hi:[1,0]
	s_nop 0
	v_cvt_pk_bf16_f32 v130, v130, v131
	v_cvt_pk_bf16_f32 v131, v132, v133
	v_cvt_pk_bf16_f32 v132, v196, v197
	v_cvt_pk_bf16_f32 v133, v188, v189
	global_store_dwordx4 v[186:187], v[130:133], off
	v_pk_mul_f32 v[188:189], v[84:85], v[180:181] op_sel_hi:[1,0]
	v_pk_mul_f32 v[196:197], v[82:83], v[180:181] op_sel_hi:[1,0]
	v_pk_mul_f32 v[132:133], v[88:89], v[180:181] op_sel_hi:[1,0]
	v_pk_mul_f32 v[130:131], v[86:87], v[180:181] op_sel_hi:[1,0]
	s_nop 0
	v_cvt_pk_bf16_f32 v130, v130, v131
	v_cvt_pk_bf16_f32 v131, v132, v133
	v_cvt_pk_bf16_f32 v132, v196, v197
	v_cvt_pk_bf16_f32 v133, v188, v189
	global_store_dwordx4 v[186:187], v[130:133], off offset:256
	v_pk_mul_f32 v[186:187], v[76:77], v[158:159] op_sel_hi:[1,0]
	v_pk_mul_f32 v[196:197], v[74:75], v[158:159] op_sel_hi:[1,0]
	v_mad_i64_i32 v[130:131], s[0:1], v193, s86, v[176:177]
	v_lshl_add_u64 v[176:177], v[130:131], 0, v[156:157]
	v_pk_mul_f32 v[132:133], v[80:81], v[158:159] op_sel_hi:[1,0]
	v_pk_mul_f32 v[130:131], v[78:79], v[158:159] op_sel_hi:[1,0]
	v_mad_i64_i32 v[188:189], s[0:1], v193, s86, 0
	v_cvt_pk_bf16_f32 v130, v130, v131
	v_cvt_pk_bf16_f32 v131, v132, v133
	v_cvt_pk_bf16_f32 v132, v196, v197
	v_cvt_pk_bf16_f32 v133, v186, v187
	global_store_dwordx4 v[176:177], v[130:133], off
	v_pk_mul_f32 v[176:177], v[66:67], v[158:159] op_sel_hi:[1,0]
	v_pk_mul_f32 v[186:187], v[68:69], v[158:159] op_sel_hi:[1,0]
	v_pk_mul_f32 v[132:133], v[72:73], v[158:159] op_sel_hi:[1,0]
	v_pk_mul_f32 v[130:131], v[70:71], v[158:159] op_sel_hi:[1,0]
	s_nop 0
	v_cvt_pk_bf16_f32 v130, v130, v131
	v_cvt_pk_bf16_f32 v131, v132, v133
	v_cvt_pk_bf16_f32 v132, v176, v177
